# residual (EpiResid) epilogues of P2/P7/P9: all 16 base-row loads prefetched up front, counted vmcnt; diff-attention 6-step specialised block (static K-ring slots, steady-state guards resolved)
# speedup vs baseline: 1.0435x; 1.0073x over previous
.LBB0_626:
	s_lshl_b32 s0, s30, 5
	s_lshl_b32 s1, s10, 8
	s_or_b32 s0, s1, s0
	v_and_or_b32 v130, v150, 24, s0
	s_lshl_b32 s0, s31, 8
	v_add_u32_e32 v132, s0, v1
	v_ashrrev_i32_e32 v133, 31, v132
	v_lshlrev_b64 v[132:133], 11, v[132:133]
	v_ashrrev_i32_e32 v131, 31, v130
	v_lshl_add_u64 v[132:133], s[72:73], 0, v[132:133]
	v_lshl_add_u64 v[136:137], v[130:131], 1, v[132:133]
	s_barrier
	global_load_dwordx4 v[152:155], v[136:137], off
	global_load_dwordx4 v[156:159], v[136:137], off offset:256
	s_mov_b64 s[98:99], 0x8000
	v_lshl_add_u64 v[216:217], v[136:137], 0, s[98:99]
	global_load_dwordx4 v[160:163], v[216:217], off
	global_load_dwordx4 v[164:167], v[216:217], off offset:256
	s_mov_b64 s[98:99], 0x10000
	v_lshl_add_u64 v[218:219], v[136:137], 0, s[98:99]
	global_load_dwordx4 v[168:171], v[218:219], off
	global_load_dwordx4 v[172:175], v[218:219], off offset:256
	s_mov_b64 s[98:99], 0x18000
	v_lshl_add_u64 v[220:221], v[136:137], 0, s[98:99]
	global_load_dwordx4 v[176:179], v[220:221], off
	global_load_dwordx4 v[180:183], v[220:221], off offset:256
	s_mov_b64 s[98:99], 0x40000
	v_lshl_add_u64 v[222:223], v[136:137], 0, s[98:99]
	global_load_dwordx4 v[184:187], v[222:223], off
	global_load_dwordx4 v[188:191], v[222:223], off offset:256
	s_mov_b64 s[98:99], 0x48000
	v_lshl_add_u64 v[224:225], v[136:137], 0, s[98:99]
	global_load_dwordx4 v[192:195], v[224:225], off
	global_load_dwordx4 v[196:199], v[224:225], off offset:256
	s_mov_b64 s[98:99], 0x50000
	v_lshl_add_u64 v[226:227], v[136:137], 0, s[98:99]
	global_load_dwordx4 v[200:203], v[226:227], off
	global_load_dwordx4 v[204:207], v[226:227], off offset:256
	s_mov_b64 s[98:99], 0x58000
	v_lshl_add_u64 v[228:229], v[136:137], 0, s[98:99]
	global_load_dwordx4 v[208:211], v[228:229], off
	global_load_dwordx4 v[212:215], v[228:229], off offset:256
	s_waitcnt vmcnt(15)
	v_mov_b32_e32 v132, v152
	v_mov_b32_e32 v133, v153
	v_mov_b32_e32 v134, v154
	v_mov_b32_e32 v135, v155
	s_lshl_b32 s1, s30, 2
	v_cmp_gt_u32_e32 vcc, 16, v252
	s_add_i32 s1, s1, 0
	v_lshlrev_b32_e32 v138, 16, v132
	v_and_b32_e32 v139, 0xffff0000, v132
	v_lshlrev_b32_e32 v132, 16, v133
	v_and_b32_e32 v133, 0xffff0000, v133
	v_lshlrev_b32_e32 v140, 16, v134
	v_and_b32_e32 v141, 0xffff0000, v134
	v_lshlrev_b32_e32 v134, 16, v135
	v_and_b32_e32 v135, 0xffff0000, v135
	v_pk_fma_f32 v[132:133], v[128:129], 0.5, v[132:133] op_sel_hi:[1,0,1]
	v_pk_fma_f32 v[138:139], v[126:127], 0.5, v[138:139] op_sel_hi:[1,0,1]
	v_pk_fma_f32 v[134:135], v[124:125], 0.5, v[134:135] op_sel_hi:[1,0,1]
	v_pk_fma_f32 v[140:141], v[122:123], 0.5, v[140:141] op_sel_hi:[1,0,1]
	v_cvt_pk_bf16_f32 v122, v138, v139
	v_cvt_pk_bf16_f32 v123, v132, v133
	v_mul_f32_e32 v139, v139, v139
	v_cvt_pk_bf16_f32 v124, v140, v141
	v_cvt_pk_bf16_f32 v125, v134, v135
	s_waitcnt vmcnt(14)
	v_mov_b32_e32 v126, v156
	v_mov_b32_e32 v127, v157
	v_mov_b32_e32 v128, v158
	v_mov_b32_e32 v129, v159
	v_mul_f32_e32 v133, v133, v133
	v_mul_f32_e32 v141, v141, v141
	v_mul_f32_e32 v135, v135, v135
	v_fmac_f32_e32 v139, v138, v138
	v_fmac_f32_e32 v133, v132, v132
	v_fmac_f32_e32 v141, v140, v140
	v_fmac_f32_e32 v135, v134, v134
	global_store_dwordx4 v[136:137], v[122:125], off
	s_nop 1
	v_add_f32_e32 v122, v139, v133
	v_add_f32_e32 v123, v141, v135
	v_add_f32_e32 v132, v122, v123
	v_lshlrev_b32_e32 v122, 16, v126
	v_and_b32_e32 v123, 0xffff0000, v126
	v_lshlrev_b32_e32 v124, 16, v127
	v_and_b32_e32 v125, 0xffff0000, v127
	v_lshlrev_b32_e32 v126, 16, v128
	v_and_b32_e32 v127, 0xffff0000, v128
	v_lshlrev_b32_e32 v128, 16, v129
	v_and_b32_e32 v129, 0xffff0000, v129
	v_pk_fma_f32 v[120:121], v[120:121], 0.5, v[124:125] op_sel_hi:[1,0,1]
	v_pk_fma_f32 v[118:119], v[118:119], 0.5, v[122:123] op_sel_hi:[1,0,1]
	v_pk_fma_f32 v[122:123], v[116:117], 0.5, v[128:129] op_sel_hi:[1,0,1]
	v_pk_fma_f32 v[124:125], v[114:115], 0.5, v[126:127] op_sel_hi:[1,0,1]
	v_cvt_pk_bf16_f32 v114, v118, v119
	v_cvt_pk_bf16_f32 v115, v120, v121
	v_mul_f32_e32 v119, v119, v119
	v_cvt_pk_bf16_f32 v116, v124, v125
	v_cvt_pk_bf16_f32 v117, v122, v123
	v_mul_f32_e32 v121, v121, v121
	v_mul_f32_e32 v125, v125, v125
	v_mul_f32_e32 v123, v123, v123
	v_fmac_f32_e32 v119, v118, v118
	v_fmac_f32_e32 v121, v120, v120
	v_fmac_f32_e32 v125, v124, v124
	v_fmac_f32_e32 v123, v122, v122
	global_store_dwordx4 v[136:137], v[114:117], off offset:256
	s_nop 1
	v_add_f32_e32 v114, v119, v121
	v_add_f32_e32 v115, v125, v123
	v_add_f32_e32 v114, v114, v115
	v_add_f32_e32 v114, v132, v114
	v_mov_b32_e32 v115, v114
	s_nop 1
	v_permlane16_swap_b32_e32 v114, v115
	v_add_f32_e32 v114, v114, v115
	v_mov_b32_e32 v115, v114
	s_nop 1
	v_permlane32_swap_b32_e32 v114, v115
	s_and_saveexec_b64 s[4:5], vcc
	v_lshl_add_u32 v116, v1, 4, s1
	v_add_f32_e32 v114, v114, v115
	ds_write_b32 v116, v114
	s_or_b64 exec, exec, s[4:5]
	v_or_b32_e32 v114, 16, v1
	v_add_u32_e32 v116, s0, v114
	v_ashrrev_i32_e32 v117, 31, v116
	v_lshlrev_b64 v[116:117], 11, v[116:117]
	v_lshl_add_u64 v[116:117], s[72:73], 0, v[116:117]
	v_lshl_add_u64 v[120:121], v[130:131], 1, v[116:117]
	s_waitcnt vmcnt(15)
	v_mov_b32_e32 v116, v160
	v_mov_b32_e32 v117, v161
	v_mov_b32_e32 v118, v162
	v_mov_b32_e32 v119, v163
	v_lshlrev_b32_e32 v122, 16, v116
	v_and_b32_e32 v123, 0xffff0000, v116
	v_lshlrev_b32_e32 v116, 16, v117
	v_and_b32_e32 v117, 0xffff0000, v117
	v_lshlrev_b32_e32 v124, 16, v118
	v_and_b32_e32 v125, 0xffff0000, v118
	v_lshlrev_b32_e32 v118, 16, v119
	v_and_b32_e32 v119, 0xffff0000, v119
	v_pk_fma_f32 v[116:117], v[112:113], 0.5, v[116:117] op_sel_hi:[1,0,1]
	v_pk_fma_f32 v[122:123], v[110:111], 0.5, v[122:123] op_sel_hi:[1,0,1]
	v_pk_fma_f32 v[118:119], v[108:109], 0.5, v[118:119] op_sel_hi:[1,0,1]
	v_pk_fma_f32 v[124:125], v[106:107], 0.5, v[124:125] op_sel_hi:[1,0,1]
	v_cvt_pk_bf16_f32 v106, v122, v123
	v_cvt_pk_bf16_f32 v107, v116, v117
	v_mul_f32_e32 v115, v123, v123
	v_cvt_pk_bf16_f32 v108, v124, v125
	v_cvt_pk_bf16_f32 v109, v118, v119
	s_waitcnt vmcnt(14)
	v_mov_b32_e32 v110, v164
	v_mov_b32_e32 v111, v165
	v_mov_b32_e32 v112, v166
	v_mov_b32_e32 v113, v167
	v_mul_f32_e32 v117, v117, v117
	v_mul_f32_e32 v123, v125, v125
	v_mul_f32_e32 v119, v119, v119
	v_fmac_f32_e32 v115, v122, v122
	v_fmac_f32_e32 v117, v116, v116
	v_fmac_f32_e32 v123, v124, v124
	v_fmac_f32_e32 v119, v118, v118
	global_store_dwordx4 v[120:121], v[106:109], off
	s_nop 1
	v_add_f32_e32 v106, v115, v117
	v_add_f32_e32 v107, v123, v119
	v_add_f32_e32 v115, v106, v107
	v_lshlrev_b32_e32 v106, 16, v110
	v_and_b32_e32 v107, 0xffff0000, v110
	v_lshlrev_b32_e32 v108, 16, v111
	v_and_b32_e32 v109, 0xffff0000, v111
	v_lshlrev_b32_e32 v110, 16, v112
	v_and_b32_e32 v111, 0xffff0000, v112
	v_lshlrev_b32_e32 v112, 16, v113
	v_and_b32_e32 v113, 0xffff0000, v113
	v_pk_fma_f32 v[104:105], v[104:105], 0.5, v[108:109] op_sel_hi:[1,0,1]
	v_pk_fma_f32 v[102:103], v[102:103], 0.5, v[106:107] op_sel_hi:[1,0,1]
	v_pk_fma_f32 v[106:107], v[100:101], 0.5, v[112:113] op_sel_hi:[1,0,1]
	v_pk_fma_f32 v[108:109], v[98:99], 0.5, v[110:111] op_sel_hi:[1,0,1]
	v_cvt_pk_bf16_f32 v98, v102, v103
	v_cvt_pk_bf16_f32 v99, v104, v105
	v_mul_f32_e32 v103, v103, v103
	v_cvt_pk_bf16_f32 v100, v108, v109
	v_cvt_pk_bf16_f32 v101, v106, v107
	v_mul_f32_e32 v105, v105, v105
	v_mul_f32_e32 v109, v109, v109
	v_mul_f32_e32 v107, v107, v107
	v_fmac_f32_e32 v103, v102, v102
	v_fmac_f32_e32 v105, v104, v104
	v_fmac_f32_e32 v109, v108, v108
	v_fmac_f32_e32 v107, v106, v106
	global_store_dwordx4 v[120:121], v[98:101], off offset:256
	s_nop 1
	v_add_f32_e32 v98, v103, v105
	v_add_f32_e32 v99, v109, v107
	v_add_f32_e32 v98, v98, v99
	v_add_f32_e32 v98, v115, v98
	v_mov_b32_e32 v99, v98
	s_nop 1
	v_permlane16_swap_b32_e32 v98, v99
	v_add_f32_e32 v98, v98, v99
	v_mov_b32_e32 v99, v98
	s_nop 1
	v_permlane32_swap_b32_e32 v98, v99
	s_and_saveexec_b64 s[4:5], vcc
	v_lshl_add_u32 v100, v114, 4, s1
	v_add_f32_e32 v98, v98, v99
	ds_write_b32 v100, v98
	s_or_b64 exec, exec, s[4:5]
	v_or_b32_e32 v98, 32, v1
	v_add_u32_e32 v100, s0, v98
	v_ashrrev_i32_e32 v101, 31, v100
	v_lshlrev_b64 v[100:101], 11, v[100:101]
	v_lshl_add_u64 v[100:101], s[72:73], 0, v[100:101]
	v_lshl_add_u64 v[104:105], v[130:131], 1, v[100:101]
	s_waitcnt vmcnt(15)
	v_mov_b32_e32 v100, v168
	v_mov_b32_e32 v101, v169
	v_mov_b32_e32 v102, v170
	v_mov_b32_e32 v103, v171
	v_lshlrev_b32_e32 v106, 16, v100
	v_and_b32_e32 v107, 0xffff0000, v100
	v_lshlrev_b32_e32 v100, 16, v101
	v_and_b32_e32 v101, 0xffff0000, v101
	v_lshlrev_b32_e32 v108, 16, v102
	v_and_b32_e32 v109, 0xffff0000, v102
	v_lshlrev_b32_e32 v102, 16, v103
	v_and_b32_e32 v103, 0xffff0000, v103
	v_pk_fma_f32 v[100:101], v[96:97], 0.5, v[100:101] op_sel_hi:[1,0,1]
	v_pk_fma_f32 v[106:107], v[94:95], 0.5, v[106:107] op_sel_hi:[1,0,1]
	v_pk_fma_f32 v[102:103], v[92:93], 0.5, v[102:103] op_sel_hi:[1,0,1]
	v_pk_fma_f32 v[108:109], v[90:91], 0.5, v[108:109] op_sel_hi:[1,0,1]
	v_cvt_pk_bf16_f32 v90, v106, v107
	v_cvt_pk_bf16_f32 v91, v100, v101
	v_mul_f32_e32 v99, v107, v107
	v_cvt_pk_bf16_f32 v92, v108, v109
	v_cvt_pk_bf16_f32 v93, v102, v103
	s_waitcnt vmcnt(14)
	v_mov_b32_e32 v94, v172
	v_mov_b32_e32 v95, v173
	v_mov_b32_e32 v96, v174
	v_mov_b32_e32 v97, v175
	v_mul_f32_e32 v101, v101, v101
	v_mul_f32_e32 v107, v109, v109
	v_mul_f32_e32 v103, v103, v103
	v_fmac_f32_e32 v99, v106, v106
	v_fmac_f32_e32 v101, v100, v100
	v_fmac_f32_e32 v107, v108, v108
	v_fmac_f32_e32 v103, v102, v102
	global_store_dwordx4 v[104:105], v[90:93], off
	s_nop 1
	v_add_f32_e32 v90, v99, v101
	v_add_f32_e32 v91, v107, v103
	v_add_f32_e32 v99, v90, v91
	v_lshlrev_b32_e32 v90, 16, v94
	v_and_b32_e32 v91, 0xffff0000, v94
	v_lshlrev_b32_e32 v92, 16, v95
	v_and_b32_e32 v93, 0xffff0000, v95
	v_lshlrev_b32_e32 v94, 16, v96
	v_and_b32_e32 v95, 0xffff0000, v96
	v_lshlrev_b32_e32 v96, 16, v97
	v_and_b32_e32 v97, 0xffff0000, v97
	v_pk_fma_f32 v[88:89], v[88:89], 0.5, v[92:93] op_sel_hi:[1,0,1]
	v_pk_fma_f32 v[86:87], v[86:87], 0.5, v[90:91] op_sel_hi:[1,0,1]
	v_pk_fma_f32 v[90:91], v[84:85], 0.5, v[96:97] op_sel_hi:[1,0,1]
	v_pk_fma_f32 v[92:93], v[82:83], 0.5, v[94:95] op_sel_hi:[1,0,1]
	v_cvt_pk_bf16_f32 v82, v86, v87
	v_cvt_pk_bf16_f32 v83, v88, v89
	v_mul_f32_e32 v87, v87, v87
	v_cvt_pk_bf16_f32 v84, v92, v93
	v_cvt_pk_bf16_f32 v85, v90, v91
	v_mul_f32_e32 v89, v89, v89
	v_mul_f32_e32 v93, v93, v93
	v_mul_f32_e32 v91, v91, v91
	v_fmac_f32_e32 v87, v86, v86
	v_fmac_f32_e32 v89, v88, v88
	v_fmac_f32_e32 v93, v92, v92
	v_fmac_f32_e32 v91, v90, v90
	global_store_dwordx4 v[104:105], v[82:85], off offset:256
	s_nop 1
	v_add_f32_e32 v82, v87, v89
	v_add_f32_e32 v83, v93, v91
	v_add_f32_e32 v82, v82, v83
	v_add_f32_e32 v82, v99, v82
	v_mov_b32_e32 v83, v82
	s_nop 1
	v_permlane16_swap_b32_e32 v82, v83
	v_add_f32_e32 v82, v82, v83
	v_mov_b32_e32 v83, v82
	s_nop 1
	v_permlane32_swap_b32_e32 v82, v83
	s_and_saveexec_b64 s[4:5], vcc
	v_lshl_add_u32 v84, v98, 4, s1
	v_add_f32_e32 v82, v82, v83
	ds_write_b32 v84, v82
	s_or_b64 exec, exec, s[4:5]
	v_or_b32_e32 v82, 48, v1
	v_add_u32_e32 v84, s0, v82
	v_ashrrev_i32_e32 v85, 31, v84
	v_lshlrev_b64 v[84:85], 11, v[84:85]
	v_lshl_add_u64 v[84:85], s[72:73], 0, v[84:85]
	v_lshl_add_u64 v[88:89], v[130:131], 1, v[84:85]
	s_waitcnt vmcnt(15)
	v_mov_b32_e32 v84, v176
	v_mov_b32_e32 v85, v177
	v_mov_b32_e32 v86, v178
	v_mov_b32_e32 v87, v179
	v_lshlrev_b32_e32 v90, 16, v84
	v_and_b32_e32 v91, 0xffff0000, v84
	v_lshlrev_b32_e32 v84, 16, v85
	v_and_b32_e32 v85, 0xffff0000, v85
	v_lshlrev_b32_e32 v92, 16, v86
	v_and_b32_e32 v93, 0xffff0000, v86
	v_lshlrev_b32_e32 v86, 16, v87
	v_and_b32_e32 v87, 0xffff0000, v87
	v_pk_fma_f32 v[84:85], v[80:81], 0.5, v[84:85] op_sel_hi:[1,0,1]
	v_pk_fma_f32 v[90:91], v[78:79], 0.5, v[90:91] op_sel_hi:[1,0,1]
	v_pk_fma_f32 v[86:87], v[76:77], 0.5, v[86:87] op_sel_hi:[1,0,1]
	v_pk_fma_f32 v[92:93], v[74:75], 0.5, v[92:93] op_sel_hi:[1,0,1]
	v_cvt_pk_bf16_f32 v74, v90, v91
	v_cvt_pk_bf16_f32 v75, v84, v85
	v_mul_f32_e32 v83, v91, v91
	v_cvt_pk_bf16_f32 v76, v92, v93
	v_cvt_pk_bf16_f32 v77, v86, v87
	s_waitcnt vmcnt(14)
	v_mov_b32_e32 v78, v180
	v_mov_b32_e32 v79, v181
	v_mov_b32_e32 v80, v182
	v_mov_b32_e32 v81, v183
	v_mul_f32_e32 v85, v85, v85
	v_mul_f32_e32 v91, v93, v93
	v_mul_f32_e32 v87, v87, v87
	v_fmac_f32_e32 v83, v90, v90
	v_fmac_f32_e32 v85, v84, v84
	v_fmac_f32_e32 v91, v92, v92
	v_fmac_f32_e32 v87, v86, v86
	global_store_dwordx4 v[88:89], v[74:77], off
	s_nop 1
	v_add_f32_e32 v74, v83, v85
	v_add_f32_e32 v75, v91, v87
	v_add_f32_e32 v83, v74, v75
	v_lshlrev_b32_e32 v74, 16, v78
	v_and_b32_e32 v75, 0xffff0000, v78
	v_lshlrev_b32_e32 v76, 16, v79
	v_and_b32_e32 v77, 0xffff0000, v79
	v_lshlrev_b32_e32 v78, 16, v80
	v_and_b32_e32 v79, 0xffff0000, v80
	v_lshlrev_b32_e32 v80, 16, v81
	v_and_b32_e32 v81, 0xffff0000, v81
	v_pk_fma_f32 v[72:73], v[72:73], 0.5, v[76:77] op_sel_hi:[1,0,1]
	v_pk_fma_f32 v[70:71], v[70:71], 0.5, v[74:75] op_sel_hi:[1,0,1]
	v_pk_fma_f32 v[74:75], v[68:69], 0.5, v[80:81] op_sel_hi:[1,0,1]
	v_pk_fma_f32 v[76:77], v[66:67], 0.5, v[78:79] op_sel_hi:[1,0,1]
	v_cvt_pk_bf16_f32 v66, v70, v71
	v_cvt_pk_bf16_f32 v67, v72, v73
	v_mul_f32_e32 v71, v71, v71
	v_cvt_pk_bf16_f32 v68, v76, v77
	v_cvt_pk_bf16_f32 v69, v74, v75
	v_mul_f32_e32 v73, v73, v73
	v_mul_f32_e32 v77, v77, v77
	v_mul_f32_e32 v75, v75, v75
	v_fmac_f32_e32 v71, v70, v70
	v_fmac_f32_e32 v73, v72, v72
	v_fmac_f32_e32 v77, v76, v76
	v_fmac_f32_e32 v75, v74, v74
	global_store_dwordx4 v[88:89], v[66:69], off offset:256
	s_nop 1
	v_add_f32_e32 v66, v71, v73
	v_add_f32_e32 v67, v77, v75
	v_add_f32_e32 v66, v66, v67
	v_add_f32_e32 v66, v83, v66
	v_mov_b32_e32 v67, v66
	s_nop 1
	v_permlane16_swap_b32_e32 v66, v67
	v_add_f32_e32 v66, v66, v67
	v_mov_b32_e32 v67, v66
	s_nop 1
	v_permlane32_swap_b32_e32 v66, v67
	s_and_saveexec_b64 s[4:5], vcc
	v_lshl_add_u32 v68, v82, 4, s1
	v_add_f32_e32 v66, v66, v67
	ds_write_b32 v68, v66
	s_or_b64 exec, exec, s[4:5]
	v_add_u32_e32 v66, 0x80, v1
	v_add_u32_e32 v68, s0, v66
	v_ashrrev_i32_e32 v69, 31, v68
	v_lshlrev_b64 v[68:69], 11, v[68:69]
	v_lshl_add_u64 v[68:69], s[72:73], 0, v[68:69]
	v_lshl_add_u64 v[72:73], v[130:131], 1, v[68:69]
	s_waitcnt vmcnt(15)
	v_mov_b32_e32 v68, v184
	v_mov_b32_e32 v69, v185
	v_mov_b32_e32 v70, v186
	v_mov_b32_e32 v71, v187
	v_lshlrev_b32_e32 v74, 16, v68
	v_and_b32_e32 v75, 0xffff0000, v68
	v_lshlrev_b32_e32 v68, 16, v69
	v_and_b32_e32 v69, 0xffff0000, v69
	v_lshlrev_b32_e32 v76, 16, v70
	v_and_b32_e32 v77, 0xffff0000, v70
	v_lshlrev_b32_e32 v70, 16, v71
	v_and_b32_e32 v71, 0xffff0000, v71
	v_pk_fma_f32 v[68:69], v[64:65], 0.5, v[68:69] op_sel_hi:[1,0,1]
	v_pk_fma_f32 v[74:75], v[62:63], 0.5, v[74:75] op_sel_hi:[1,0,1]
	v_pk_fma_f32 v[70:71], v[60:61], 0.5, v[70:71] op_sel_hi:[1,0,1]
	v_pk_fma_f32 v[76:77], v[58:59], 0.5, v[76:77] op_sel_hi:[1,0,1]
	v_cvt_pk_bf16_f32 v58, v74, v75
	v_cvt_pk_bf16_f32 v59, v68, v69
	v_mul_f32_e32 v67, v75, v75
	v_cvt_pk_bf16_f32 v60, v76, v77
	v_cvt_pk_bf16_f32 v61, v70, v71
	s_waitcnt vmcnt(14)
	v_mov_b32_e32 v62, v188
	v_mov_b32_e32 v63, v189
	v_mov_b32_e32 v64, v190
	v_mov_b32_e32 v65, v191
	v_mul_f32_e32 v69, v69, v69
	v_mul_f32_e32 v75, v77, v77
	v_mul_f32_e32 v71, v71, v71
	v_fmac_f32_e32 v67, v74, v74
	v_fmac_f32_e32 v69, v68, v68
	v_fmac_f32_e32 v75, v76, v76
	v_fmac_f32_e32 v71, v70, v70
	global_store_dwordx4 v[72:73], v[58:61], off
	s_nop 1
	v_add_f32_e32 v58, v67, v69
	v_add_f32_e32 v59, v75, v71
	v_add_f32_e32 v67, v58, v59
	v_lshlrev_b32_e32 v58, 16, v62
	v_and_b32_e32 v59, 0xffff0000, v62
	v_lshlrev_b32_e32 v60, 16, v63
	v_and_b32_e32 v61, 0xffff0000, v63
	v_lshlrev_b32_e32 v62, 16, v64
	v_and_b32_e32 v63, 0xffff0000, v64
	v_lshlrev_b32_e32 v64, 16, v65
	v_and_b32_e32 v65, 0xffff0000, v65
	v_pk_fma_f32 v[56:57], v[56:57], 0.5, v[60:61] op_sel_hi:[1,0,1]
	v_pk_fma_f32 v[54:55], v[54:55], 0.5, v[58:59] op_sel_hi:[1,0,1]
	v_pk_fma_f32 v[58:59], v[52:53], 0.5, v[64:65] op_sel_hi:[1,0,1]
	v_pk_fma_f32 v[60:61], v[50:51], 0.5, v[62:63] op_sel_hi:[1,0,1]
	v_cvt_pk_bf16_f32 v50, v54, v55
	v_cvt_pk_bf16_f32 v51, v56, v57
	v_mul_f32_e32 v55, v55, v55
	v_cvt_pk_bf16_f32 v52, v60, v61
	v_cvt_pk_bf16_f32 v53, v58, v59
	v_mul_f32_e32 v57, v57, v57
	v_mul_f32_e32 v61, v61, v61
	v_mul_f32_e32 v59, v59, v59
	v_fmac_f32_e32 v55, v54, v54
	v_fmac_f32_e32 v57, v56, v56
	v_fmac_f32_e32 v61, v60, v60
	v_fmac_f32_e32 v59, v58, v58
	global_store_dwordx4 v[72:73], v[50:53], off offset:256
	s_nop 1
	v_add_f32_e32 v50, v55, v57
	v_add_f32_e32 v51, v61, v59
	v_add_f32_e32 v50, v50, v51
	v_add_f32_e32 v50, v67, v50
	v_mov_b32_e32 v51, v50
	s_nop 1
	v_permlane16_swap_b32_e32 v50, v51
	v_add_f32_e32 v50, v50, v51
	v_mov_b32_e32 v51, v50
	s_nop 1
	v_permlane32_swap_b32_e32 v50, v51
	s_and_saveexec_b64 s[4:5], vcc
	v_lshl_add_u32 v52, v66, 4, s1
	v_add_f32_e32 v50, v50, v51
	ds_write_b32 v52, v50
	s_or_b64 exec, exec, s[4:5]
	v_add_u32_e32 v50, 0x90, v1
	v_add_u32_e32 v52, s0, v50
	v_ashrrev_i32_e32 v53, 31, v52
	v_lshlrev_b64 v[52:53], 11, v[52:53]
	v_lshl_add_u64 v[52:53], s[72:73], 0, v[52:53]
	v_lshl_add_u64 v[56:57], v[130:131], 1, v[52:53]
	s_waitcnt vmcnt(15)
	v_mov_b32_e32 v52, v192
	v_mov_b32_e32 v53, v193
	v_mov_b32_e32 v54, v194
	v_mov_b32_e32 v55, v195
	v_lshlrev_b32_e32 v58, 16, v52
	v_and_b32_e32 v59, 0xffff0000, v52
	v_lshlrev_b32_e32 v52, 16, v53
	v_and_b32_e32 v53, 0xffff0000, v53
	v_lshlrev_b32_e32 v60, 16, v54
	v_and_b32_e32 v61, 0xffff0000, v54
	v_lshlrev_b32_e32 v54, 16, v55
	v_and_b32_e32 v55, 0xffff0000, v55
	v_pk_fma_f32 v[52:53], v[48:49], 0.5, v[52:53] op_sel_hi:[1,0,1]
	v_pk_fma_f32 v[58:59], v[46:47], 0.5, v[58:59] op_sel_hi:[1,0,1]
	v_pk_fma_f32 v[54:55], v[44:45], 0.5, v[54:55] op_sel_hi:[1,0,1]
	v_pk_fma_f32 v[60:61], v[42:43], 0.5, v[60:61] op_sel_hi:[1,0,1]
	v_cvt_pk_bf16_f32 v42, v58, v59
	v_cvt_pk_bf16_f32 v43, v52, v53
	v_mul_f32_e32 v51, v59, v59
	v_cvt_pk_bf16_f32 v44, v60, v61
	v_cvt_pk_bf16_f32 v45, v54, v55
	s_waitcnt vmcnt(14)
	v_mov_b32_e32 v46, v196
	v_mov_b32_e32 v47, v197
	v_mov_b32_e32 v48, v198
	v_mov_b32_e32 v49, v199
	v_mul_f32_e32 v53, v53, v53
	v_mul_f32_e32 v59, v61, v61
	v_mul_f32_e32 v55, v55, v55
	v_fmac_f32_e32 v51, v58, v58
	v_fmac_f32_e32 v53, v52, v52
	v_fmac_f32_e32 v59, v60, v60
	v_fmac_f32_e32 v55, v54, v54
	global_store_dwordx4 v[56:57], v[42:45], off
	s_nop 1
	v_add_f32_e32 v42, v51, v53
	v_add_f32_e32 v43, v59, v55
	v_add_f32_e32 v51, v42, v43
	v_lshlrev_b32_e32 v42, 16, v46
	v_and_b32_e32 v43, 0xffff0000, v46
	v_lshlrev_b32_e32 v44, 16, v47
	v_and_b32_e32 v45, 0xffff0000, v47
	v_lshlrev_b32_e32 v46, 16, v48
	v_and_b32_e32 v47, 0xffff0000, v48
	v_lshlrev_b32_e32 v48, 16, v49
	v_and_b32_e32 v49, 0xffff0000, v49
	v_pk_fma_f32 v[40:41], v[40:41], 0.5, v[44:45] op_sel_hi:[1,0,1]
	v_pk_fma_f32 v[38:39], v[38:39], 0.5, v[42:43] op_sel_hi:[1,0,1]
	v_pk_fma_f32 v[42:43], v[36:37], 0.5, v[48:49] op_sel_hi:[1,0,1]
	v_pk_fma_f32 v[44:45], v[34:35], 0.5, v[46:47] op_sel_hi:[1,0,1]
	v_cvt_pk_bf16_f32 v34, v38, v39
	v_cvt_pk_bf16_f32 v35, v40, v41
	v_mul_f32_e32 v39, v39, v39
	v_cvt_pk_bf16_f32 v36, v44, v45
	v_cvt_pk_bf16_f32 v37, v42, v43
	v_mul_f32_e32 v41, v41, v41
	v_mul_f32_e32 v45, v45, v45
	v_mul_f32_e32 v43, v43, v43
	v_fmac_f32_e32 v39, v38, v38
	v_fmac_f32_e32 v41, v40, v40
	v_fmac_f32_e32 v45, v44, v44
	v_fmac_f32_e32 v43, v42, v42
	global_store_dwordx4 v[56:57], v[34:37], off offset:256
	s_nop 1
	v_add_f32_e32 v34, v39, v41
	v_add_f32_e32 v35, v45, v43
	v_add_f32_e32 v34, v34, v35
	v_add_f32_e32 v34, v51, v34
	v_mov_b32_e32 v35, v34
	s_nop 1
	v_permlane16_swap_b32_e32 v34, v35
	v_add_f32_e32 v34, v34, v35
	v_mov_b32_e32 v35, v34
	s_nop 1
	v_permlane32_swap_b32_e32 v34, v35
	s_and_saveexec_b64 s[4:5], vcc
	v_lshl_add_u32 v36, v50, 4, s1
	v_add_f32_e32 v34, v34, v35
	ds_write_b32 v36, v34
	s_or_b64 exec, exec, s[4:5]
	v_add_u32_e32 v34, 0xa0, v1
	v_add_u32_e32 v36, s0, v34
	v_ashrrev_i32_e32 v37, 31, v36
	v_lshlrev_b64 v[36:37], 11, v[36:37]
	v_lshl_add_u64 v[36:37], s[72:73], 0, v[36:37]
	v_lshl_add_u64 v[40:41], v[130:131], 1, v[36:37]
	s_waitcnt vmcnt(15)
	v_mov_b32_e32 v36, v200
	v_mov_b32_e32 v37, v201
	v_mov_b32_e32 v38, v202
	v_mov_b32_e32 v39, v203
	v_lshlrev_b32_e32 v42, 16, v36
	v_and_b32_e32 v43, 0xffff0000, v36
	v_lshlrev_b32_e32 v36, 16, v37
	v_and_b32_e32 v37, 0xffff0000, v37
	v_lshlrev_b32_e32 v44, 16, v38
	v_and_b32_e32 v45, 0xffff0000, v38
	v_lshlrev_b32_e32 v38, 16, v39
	v_and_b32_e32 v39, 0xffff0000, v39
	v_pk_fma_f32 v[36:37], v[32:33], 0.5, v[36:37] op_sel_hi:[1,0,1]
	v_pk_fma_f32 v[42:43], v[30:31], 0.5, v[42:43] op_sel_hi:[1,0,1]
	v_pk_fma_f32 v[38:39], v[28:29], 0.5, v[38:39] op_sel_hi:[1,0,1]
	v_pk_fma_f32 v[44:45], v[26:27], 0.5, v[44:45] op_sel_hi:[1,0,1]
	v_cvt_pk_bf16_f32 v26, v42, v43
	v_cvt_pk_bf16_f32 v27, v36, v37
	v_mul_f32_e32 v35, v43, v43
	v_cvt_pk_bf16_f32 v28, v44, v45
	v_cvt_pk_bf16_f32 v29, v38, v39
	s_waitcnt vmcnt(14)
	v_mov_b32_e32 v30, v204
	v_mov_b32_e32 v31, v205
	v_mov_b32_e32 v32, v206
	v_mov_b32_e32 v33, v207
	v_mul_f32_e32 v37, v37, v37
	v_mul_f32_e32 v43, v45, v45
	v_mul_f32_e32 v39, v39, v39
	v_fmac_f32_e32 v35, v42, v42
	v_fmac_f32_e32 v37, v36, v36
	v_fmac_f32_e32 v43, v44, v44
	v_fmac_f32_e32 v39, v38, v38
	global_store_dwordx4 v[40:41], v[26:29], off
	s_nop 1
	v_add_f32_e32 v26, v35, v37
	v_add_f32_e32 v27, v43, v39
	v_add_f32_e32 v35, v26, v27
	v_lshlrev_b32_e32 v26, 16, v30
	v_and_b32_e32 v27, 0xffff0000, v30
	v_lshlrev_b32_e32 v28, 16, v31
	v_and_b32_e32 v29, 0xffff0000, v31
	v_lshlrev_b32_e32 v30, 16, v32
	v_and_b32_e32 v31, 0xffff0000, v32
	v_lshlrev_b32_e32 v32, 16, v33
	v_and_b32_e32 v33, 0xffff0000, v33
	v_pk_fma_f32 v[24:25], v[24:25], 0.5, v[28:29] op_sel_hi:[1,0,1]
	v_pk_fma_f32 v[22:23], v[22:23], 0.5, v[26:27] op_sel_hi:[1,0,1]
	v_pk_fma_f32 v[26:27], v[20:21], 0.5, v[32:33] op_sel_hi:[1,0,1]
	v_pk_fma_f32 v[28:29], v[18:19], 0.5, v[30:31] op_sel_hi:[1,0,1]
	v_cvt_pk_bf16_f32 v18, v22, v23
	v_cvt_pk_bf16_f32 v19, v24, v25
	v_mul_f32_e32 v23, v23, v23
	v_cvt_pk_bf16_f32 v20, v28, v29
	v_cvt_pk_bf16_f32 v21, v26, v27
	v_mul_f32_e32 v25, v25, v25
	v_mul_f32_e32 v29, v29, v29
	v_mul_f32_e32 v27, v27, v27
	v_fmac_f32_e32 v23, v22, v22
	v_fmac_f32_e32 v25, v24, v24
	v_fmac_f32_e32 v29, v28, v28
	v_fmac_f32_e32 v27, v26, v26
	global_store_dwordx4 v[40:41], v[18:21], off offset:256
	s_nop 1
	v_add_f32_e32 v18, v23, v25
	v_add_f32_e32 v19, v29, v27
	v_add_f32_e32 v18, v18, v19
	v_add_f32_e32 v18, v35, v18
	v_mov_b32_e32 v19, v18
	s_nop 1
	v_permlane16_swap_b32_e32 v18, v19
	v_add_f32_e32 v18, v18, v19
	v_mov_b32_e32 v19, v18
	s_nop 1
	v_permlane32_swap_b32_e32 v18, v19
	s_and_saveexec_b64 s[4:5], vcc
	v_lshl_add_u32 v20, v34, 4, s1
	v_add_f32_e32 v18, v18, v19
	ds_write_b32 v20, v18
	s_or_b64 exec, exec, s[4:5]
	v_add_u32_e32 v1, 0xb0, v1
	v_add_u32_e32 v18, s0, v1
	v_ashrrev_i32_e32 v19, 31, v18
	v_lshlrev_b64 v[18:19], 11, v[18:19]
	v_lshl_add_u64 v[18:19], s[72:73], 0, v[18:19]
	v_lshl_add_u64 v[22:23], v[130:131], 1, v[18:19]
	s_waitcnt vmcnt(15)
	v_mov_b32_e32 v18, v208
	v_mov_b32_e32 v19, v209
	v_mov_b32_e32 v20, v210
	v_mov_b32_e32 v21, v211
	v_lshlrev_b32_e32 v24, 16, v18
	v_and_b32_e32 v25, 0xffff0000, v18
	v_lshlrev_b32_e32 v18, 16, v19
	v_and_b32_e32 v19, 0xffff0000, v19
	v_lshlrev_b32_e32 v26, 16, v20
	v_and_b32_e32 v27, 0xffff0000, v20
	v_lshlrev_b32_e32 v20, 16, v21
	v_and_b32_e32 v21, 0xffff0000, v21
	v_pk_fma_f32 v[18:19], v[16:17], 0.5, v[18:19] op_sel_hi:[1,0,1]
	v_pk_fma_f32 v[24:25], v[14:15], 0.5, v[24:25] op_sel_hi:[1,0,1]
	v_pk_fma_f32 v[20:21], v[12:13], 0.5, v[20:21] op_sel_hi:[1,0,1]
	v_pk_fma_f32 v[26:27], v[10:11], 0.5, v[26:27] op_sel_hi:[1,0,1]
	v_cvt_pk_bf16_f32 v10, v24, v25
	v_cvt_pk_bf16_f32 v11, v18, v19
	v_mul_f32_e32 v25, v25, v25
	v_cvt_pk_bf16_f32 v12, v26, v27
	v_cvt_pk_bf16_f32 v13, v20, v21
	s_waitcnt vmcnt(14)
	v_mov_b32_e32 v14, v212
	v_mov_b32_e32 v15, v213
	v_mov_b32_e32 v16, v214
	v_mov_b32_e32 v17, v215
	v_mul_f32_e32 v19, v19, v19
	v_mul_f32_e32 v27, v27, v27
	v_mul_f32_e32 v21, v21, v21
	v_fmac_f32_e32 v25, v24, v24
	v_fmac_f32_e32 v19, v18, v18
	v_fmac_f32_e32 v27, v26, v26
	v_fmac_f32_e32 v21, v20, v20
	global_store_dwordx4 v[22:23], v[10:13], off
	s_nop 1
	v_add_f32_e32 v10, v25, v19
	v_add_f32_e32 v11, v27, v21
	v_add_f32_e32 v18, v10, v11
	v_lshlrev_b32_e32 v10, 16, v14
	v_and_b32_e32 v11, 0xffff0000, v14
	v_lshlrev_b32_e32 v12, 16, v15
	v_and_b32_e32 v13, 0xffff0000, v15
	v_lshlrev_b32_e32 v14, 16, v16
	v_and_b32_e32 v15, 0xffff0000, v16
	v_lshlrev_b32_e32 v16, 16, v17
	v_and_b32_e32 v17, 0xffff0000, v17
	v_pk_fma_f32 v[8:9], v[8:9], 0.5, v[12:13] op_sel_hi:[1,0,1]
	v_pk_fma_f32 v[6:7], v[6:7], 0.5, v[10:11] op_sel_hi:[1,0,1]
	v_pk_fma_f32 v[10:11], v[4:5], 0.5, v[16:17] op_sel_hi:[1,0,1]
	v_pk_fma_f32 v[12:13], v[2:3], 0.5, v[14:15] op_sel_hi:[1,0,1]
	v_cvt_pk_bf16_f32 v2, v6, v7
	v_cvt_pk_bf16_f32 v3, v8, v9
	v_mul_f32_e32 v7, v7, v7
	v_cvt_pk_bf16_f32 v4, v12, v13
	v_cvt_pk_bf16_f32 v5, v10, v11
	v_mul_f32_e32 v9, v9, v9
	v_mul_f32_e32 v13, v13, v13
	v_mul_f32_e32 v11, v11, v11
	v_fmac_f32_e32 v7, v6, v6
	v_fmac_f32_e32 v9, v8, v8
	v_fmac_f32_e32 v13, v12, v12
	v_fmac_f32_e32 v11, v10, v10
	global_store_dwordx4 v[22:23], v[2:5], off offset:256
	s_nop 1
	v_add_f32_e32 v2, v7, v9
	v_add_f32_e32 v3, v13, v11
	v_add_f32_e32 v2, v2, v3
	v_add_f32_e32 v2, v18, v2
	v_mov_b32_e32 v3, v2
	s_nop 1
	v_permlane16_swap_b32_e32 v2, v3
	v_add_f32_e32 v2, v2, v3
	v_mov_b32_e32 v3, v2
	s_nop 1
	v_permlane32_swap_b32_e32 v2, v3
	s_and_saveexec_b64 s[4:5], vcc
	v_lshl_add_u32 v1, v1, 4, s1
	v_add_f32_e32 v2, v2, v3
	ds_write_b32 v1, v2
	s_or_b64 exec, exec, s[4:5]
	s_waitcnt lgkmcnt(0)
	s_barrier
	s_andn2_b32 s11, s11, 63
	v_or_b32_e32 v1, s11, v252
	s_movk_i32 s1, 0x100
	v_cmp_gt_i32_e32 vcc, s1, v1
	s_and_saveexec_b64 s[4:5], vcc
	s_cbranch_execz .LBB0_644
	v_lshl_add_u32 v2, v1, 4, 0
	ds_read_b128 v[2:5], v2
	v_add_u32_e32 v6, s0, v1
	v_ashrrev_i32_e32 v7, 31, v6
	s_ashr_i32 s11, s10, 31
	s_waitcnt lgkmcnt(0)
	v_mov_b32_e32 v8, v3
	v_mov_b32_e32 v9, v4
	v_mov_b32_e32 v3, v5
	v_pk_add_f32 v[2:3], v[8:9], v[2:3]
	s_nop 0
	v_add_f32_e32 v1, v2, v3
	v_lshl_add_u64 v[2:3], v[6:7], 4, s[16:17]
	v_lshl_add_u64 v[2:3], s[10:11], 2, v[2:3]
	global_store_dword v[2:3], v1, off

.LBB0_1377:
	s_add_i32 s98, s43, 8
	s_cmp_gt_i32 s98, s88
	s_cbranch_scc1 .Ldf_slow
	s_sub_u32 s98, s42, s43
	s_cmp_lt_u32 s98, 5
	s_cbranch_scc1 .Ldf_slow
	s_sub_u32 s98, s22, s43
	s_cmp_lt_u32 s98, 5
	s_cbranch_scc1 .Ldf_slow
	s_cmp_lg_u32 s1, 0x4000
	s_cbranch_scc1 .Ldf_slow
	s_cmp_lg_u32 s14, 0
	s_cbranch_scc0 .Ldf_fast

.LBB0_1638:
	s_lshl_b32 s0, s17, 5
	s_lshl_b32 s1, s10, 8
	s_or_b32 s0, s1, s0
	v_and_or_b32 v130, v150, 24, s0
	s_lshl_b32 s0, s16, 8
	v_add_u32_e32 v132, s0, v1
	v_ashrrev_i32_e32 v133, 31, v132
	v_lshlrev_b64 v[132:133], 11, v[132:133]
	v_ashrrev_i32_e32 v131, 31, v130
	v_lshl_add_u64 v[132:133], s[68:69], 0, v[132:133]
	v_lshl_add_u64 v[136:137], v[130:131], 1, v[132:133]
	s_barrier
	global_load_dwordx4 v[152:155], v[136:137], off
	global_load_dwordx4 v[156:159], v[136:137], off offset:256
	s_mov_b64 s[98:99], 0x8000
	v_lshl_add_u64 v[216:217], v[136:137], 0, s[98:99]
	global_load_dwordx4 v[160:163], v[216:217], off
	global_load_dwordx4 v[164:167], v[216:217], off offset:256
	s_mov_b64 s[98:99], 0x10000
	v_lshl_add_u64 v[218:219], v[136:137], 0, s[98:99]
	global_load_dwordx4 v[168:171], v[218:219], off
	global_load_dwordx4 v[172:175], v[218:219], off offset:256
	s_mov_b64 s[98:99], 0x18000
	v_lshl_add_u64 v[220:221], v[136:137], 0, s[98:99]
	global_load_dwordx4 v[176:179], v[220:221], off
	global_load_dwordx4 v[180:183], v[220:221], off offset:256
	s_mov_b64 s[98:99], 0x40000
	v_lshl_add_u64 v[222:223], v[136:137], 0, s[98:99]
	global_load_dwordx4 v[184:187], v[222:223], off
	global_load_dwordx4 v[188:191], v[222:223], off offset:256
	s_mov_b64 s[98:99], 0x48000
	v_lshl_add_u64 v[224:225], v[136:137], 0, s[98:99]
	global_load_dwordx4 v[192:195], v[224:225], off
	global_load_dwordx4 v[196:199], v[224:225], off offset:256
	s_mov_b64 s[98:99], 0x50000
	v_lshl_add_u64 v[226:227], v[136:137], 0, s[98:99]
	global_load_dwordx4 v[200:203], v[226:227], off
	global_load_dwordx4 v[204:207], v[226:227], off offset:256
	s_mov_b64 s[98:99], 0x58000
	v_lshl_add_u64 v[228:229], v[136:137], 0, s[98:99]
	global_load_dwordx4 v[208:211], v[228:229], off
	global_load_dwordx4 v[212:215], v[228:229], off offset:256
	s_waitcnt vmcnt(15)
	v_mov_b32_e32 v132, v152
	v_mov_b32_e32 v133, v153
	v_mov_b32_e32 v134, v154
	v_mov_b32_e32 v135, v155
	s_lshl_b32 s1, s17, 2
	v_cmp_gt_u32_e32 vcc, 16, v252
	s_add_i32 s1, s1, 0
	v_lshlrev_b32_e32 v138, 16, v132
	v_and_b32_e32 v139, 0xffff0000, v132
	v_lshlrev_b32_e32 v132, 16, v133
	v_and_b32_e32 v133, 0xffff0000, v133
	v_lshlrev_b32_e32 v140, 16, v134
	v_and_b32_e32 v141, 0xffff0000, v134
	v_lshlrev_b32_e32 v134, 16, v135
	v_and_b32_e32 v135, 0xffff0000, v135
	v_pk_add_f32 v[132:133], v[128:129], v[132:133]
	v_pk_add_f32 v[138:139], v[126:127], v[138:139]
	v_pk_add_f32 v[134:135], v[124:125], v[134:135]
	v_pk_add_f32 v[140:141], v[122:123], v[140:141]
	v_cvt_pk_bf16_f32 v122, v138, v139
	v_cvt_pk_bf16_f32 v123, v132, v133
	v_mul_f32_e32 v139, v139, v139
	v_cvt_pk_bf16_f32 v124, v140, v141
	v_cvt_pk_bf16_f32 v125, v134, v135
	s_waitcnt vmcnt(14)
	v_mov_b32_e32 v126, v156
	v_mov_b32_e32 v127, v157
	v_mov_b32_e32 v128, v158
	v_mov_b32_e32 v129, v159
	v_mul_f32_e32 v133, v133, v133
	v_mul_f32_e32 v141, v141, v141
	v_mul_f32_e32 v135, v135, v135
	v_fmac_f32_e32 v139, v138, v138
	v_fmac_f32_e32 v133, v132, v132
	v_fmac_f32_e32 v141, v140, v140
	v_fmac_f32_e32 v135, v134, v134
	global_store_dwordx4 v[136:137], v[122:125], off
	s_nop 1
	v_add_f32_e32 v122, v139, v133
	v_add_f32_e32 v123, v141, v135
	v_add_f32_e32 v132, v122, v123
	v_lshlrev_b32_e32 v122, 16, v126
	v_and_b32_e32 v123, 0xffff0000, v126
	v_lshlrev_b32_e32 v124, 16, v127
	v_and_b32_e32 v125, 0xffff0000, v127
	v_lshlrev_b32_e32 v126, 16, v128
	v_and_b32_e32 v127, 0xffff0000, v128
	v_lshlrev_b32_e32 v128, 16, v129
	v_and_b32_e32 v129, 0xffff0000, v129
	v_pk_add_f32 v[120:121], v[120:121], v[124:125]
	v_pk_add_f32 v[118:119], v[118:119], v[122:123]
	v_pk_add_f32 v[122:123], v[116:117], v[128:129]
	v_pk_add_f32 v[124:125], v[114:115], v[126:127]
	v_cvt_pk_bf16_f32 v114, v118, v119
	v_cvt_pk_bf16_f32 v115, v120, v121
	v_mul_f32_e32 v119, v119, v119
	v_cvt_pk_bf16_f32 v116, v124, v125
	v_cvt_pk_bf16_f32 v117, v122, v123
	v_mul_f32_e32 v121, v121, v121
	v_mul_f32_e32 v125, v125, v125
	v_mul_f32_e32 v123, v123, v123
	v_fmac_f32_e32 v119, v118, v118
	v_fmac_f32_e32 v121, v120, v120
	v_fmac_f32_e32 v125, v124, v124
	v_fmac_f32_e32 v123, v122, v122
	global_store_dwordx4 v[136:137], v[114:117], off offset:256
	s_nop 1
	v_add_f32_e32 v114, v119, v121
	v_add_f32_e32 v115, v125, v123
	v_add_f32_e32 v114, v114, v115
	v_add_f32_e32 v114, v132, v114
	v_mov_b32_e32 v115, v114
	s_nop 1
	v_permlane16_swap_b32_e32 v114, v115
	v_add_f32_e32 v114, v114, v115
	v_mov_b32_e32 v115, v114
	s_nop 1
	v_permlane32_swap_b32_e32 v114, v115
	s_and_saveexec_b64 s[4:5], vcc
	v_add_f32_e32 v114, v114, v115
	v_lshl_add_u32 v115, v1, 4, s1
	ds_write_b32 v115, v114
	s_or_b64 exec, exec, s[4:5]
	v_or_b32_e32 v114, 16, v1
	v_add_u32_e32 v116, s0, v114
	v_ashrrev_i32_e32 v117, 31, v116
	v_lshlrev_b64 v[116:117], 11, v[116:117]
	v_lshl_add_u64 v[116:117], s[68:69], 0, v[116:117]
	v_lshl_add_u64 v[120:121], v[130:131], 1, v[116:117]
	s_waitcnt vmcnt(15)
	v_mov_b32_e32 v116, v160
	v_mov_b32_e32 v117, v161
	v_mov_b32_e32 v118, v162
	v_mov_b32_e32 v119, v163
	v_lshlrev_b32_e32 v122, 16, v116
	v_and_b32_e32 v123, 0xffff0000, v116
	v_lshlrev_b32_e32 v116, 16, v117
	v_and_b32_e32 v117, 0xffff0000, v117
	v_lshlrev_b32_e32 v124, 16, v118
	v_and_b32_e32 v125, 0xffff0000, v118
	v_lshlrev_b32_e32 v118, 16, v119
	v_and_b32_e32 v119, 0xffff0000, v119
	v_pk_add_f32 v[116:117], v[112:113], v[116:117]
	v_pk_add_f32 v[122:123], v[110:111], v[122:123]
	v_pk_add_f32 v[118:119], v[108:109], v[118:119]
	v_pk_add_f32 v[124:125], v[106:107], v[124:125]
	v_cvt_pk_bf16_f32 v106, v122, v123
	v_cvt_pk_bf16_f32 v107, v116, v117
	v_mul_f32_e32 v115, v123, v123
	v_cvt_pk_bf16_f32 v108, v124, v125
	v_cvt_pk_bf16_f32 v109, v118, v119
	s_waitcnt vmcnt(14)
	v_mov_b32_e32 v110, v164
	v_mov_b32_e32 v111, v165
	v_mov_b32_e32 v112, v166
	v_mov_b32_e32 v113, v167
	v_mul_f32_e32 v117, v117, v117
	v_mul_f32_e32 v123, v125, v125
	v_mul_f32_e32 v119, v119, v119
	v_fmac_f32_e32 v115, v122, v122
	v_fmac_f32_e32 v117, v116, v116
	v_fmac_f32_e32 v123, v124, v124
	v_fmac_f32_e32 v119, v118, v118
	global_store_dwordx4 v[120:121], v[106:109], off
	s_nop 1
	v_add_f32_e32 v106, v115, v117
	v_add_f32_e32 v107, v123, v119
	v_add_f32_e32 v115, v106, v107
	v_lshlrev_b32_e32 v106, 16, v110
	v_and_b32_e32 v107, 0xffff0000, v110
	v_lshlrev_b32_e32 v108, 16, v111
	v_and_b32_e32 v109, 0xffff0000, v111
	v_lshlrev_b32_e32 v110, 16, v112
	v_and_b32_e32 v111, 0xffff0000, v112
	v_lshlrev_b32_e32 v112, 16, v113
	v_and_b32_e32 v113, 0xffff0000, v113
	v_pk_add_f32 v[104:105], v[104:105], v[108:109]
	v_pk_add_f32 v[102:103], v[102:103], v[106:107]
	v_pk_add_f32 v[106:107], v[100:101], v[112:113]
	v_pk_add_f32 v[108:109], v[98:99], v[110:111]
	v_cvt_pk_bf16_f32 v98, v102, v103
	v_cvt_pk_bf16_f32 v99, v104, v105
	v_mul_f32_e32 v103, v103, v103
	v_cvt_pk_bf16_f32 v100, v108, v109
	v_cvt_pk_bf16_f32 v101, v106, v107
	v_mul_f32_e32 v105, v105, v105
	v_mul_f32_e32 v109, v109, v109
	v_mul_f32_e32 v107, v107, v107
	v_fmac_f32_e32 v103, v102, v102
	v_fmac_f32_e32 v105, v104, v104
	v_fmac_f32_e32 v109, v108, v108
	v_fmac_f32_e32 v107, v106, v106
	global_store_dwordx4 v[120:121], v[98:101], off offset:256
	s_nop 1
	v_add_f32_e32 v98, v103, v105
	v_add_f32_e32 v99, v109, v107
	v_add_f32_e32 v98, v98, v99
	v_add_f32_e32 v98, v115, v98
	v_mov_b32_e32 v99, v98
	s_nop 1
	v_permlane16_swap_b32_e32 v98, v99
	v_add_f32_e32 v98, v98, v99
	v_mov_b32_e32 v99, v98
	s_nop 1
	v_permlane32_swap_b32_e32 v98, v99
	s_and_saveexec_b64 s[4:5], vcc
	v_add_f32_e32 v98, v98, v99
	v_lshl_add_u32 v99, v114, 4, s1
	ds_write_b32 v99, v98
	s_or_b64 exec, exec, s[4:5]
	v_or_b32_e32 v98, 32, v1
	v_add_u32_e32 v100, s0, v98
	v_ashrrev_i32_e32 v101, 31, v100
	v_lshlrev_b64 v[100:101], 11, v[100:101]
	v_lshl_add_u64 v[100:101], s[68:69], 0, v[100:101]
	v_lshl_add_u64 v[104:105], v[130:131], 1, v[100:101]
	s_waitcnt vmcnt(15)
	v_mov_b32_e32 v100, v168
	v_mov_b32_e32 v101, v169
	v_mov_b32_e32 v102, v170
	v_mov_b32_e32 v103, v171
	v_lshlrev_b32_e32 v106, 16, v100
	v_and_b32_e32 v107, 0xffff0000, v100
	v_lshlrev_b32_e32 v100, 16, v101
	v_and_b32_e32 v101, 0xffff0000, v101
	v_lshlrev_b32_e32 v108, 16, v102
	v_and_b32_e32 v109, 0xffff0000, v102
	v_lshlrev_b32_e32 v102, 16, v103
	v_and_b32_e32 v103, 0xffff0000, v103
	v_pk_add_f32 v[100:101], v[96:97], v[100:101]
	v_pk_add_f32 v[106:107], v[94:95], v[106:107]
	v_pk_add_f32 v[102:103], v[92:93], v[102:103]
	v_pk_add_f32 v[108:109], v[90:91], v[108:109]
	v_cvt_pk_bf16_f32 v90, v106, v107
	v_cvt_pk_bf16_f32 v91, v100, v101
	v_mul_f32_e32 v99, v107, v107
	v_cvt_pk_bf16_f32 v92, v108, v109
	v_cvt_pk_bf16_f32 v93, v102, v103
	s_waitcnt vmcnt(14)
	v_mov_b32_e32 v94, v172
	v_mov_b32_e32 v95, v173
	v_mov_b32_e32 v96, v174
	v_mov_b32_e32 v97, v175
	v_mul_f32_e32 v101, v101, v101
	v_mul_f32_e32 v107, v109, v109
	v_mul_f32_e32 v103, v103, v103
	v_fmac_f32_e32 v99, v106, v106
	v_fmac_f32_e32 v101, v100, v100
	v_fmac_f32_e32 v107, v108, v108
	v_fmac_f32_e32 v103, v102, v102
	global_store_dwordx4 v[104:105], v[90:93], off
	s_nop 1
	v_add_f32_e32 v90, v99, v101
	v_add_f32_e32 v91, v107, v103
	v_add_f32_e32 v99, v90, v91
	v_lshlrev_b32_e32 v90, 16, v94
	v_and_b32_e32 v91, 0xffff0000, v94
	v_lshlrev_b32_e32 v92, 16, v95
	v_and_b32_e32 v93, 0xffff0000, v95
	v_lshlrev_b32_e32 v94, 16, v96
	v_and_b32_e32 v95, 0xffff0000, v96
	v_lshlrev_b32_e32 v96, 16, v97
	v_and_b32_e32 v97, 0xffff0000, v97
	v_pk_add_f32 v[88:89], v[88:89], v[92:93]
	v_pk_add_f32 v[86:87], v[86:87], v[90:91]
	v_pk_add_f32 v[90:91], v[84:85], v[96:97]
	v_pk_add_f32 v[92:93], v[82:83], v[94:95]
	v_cvt_pk_bf16_f32 v82, v86, v87
	v_cvt_pk_bf16_f32 v83, v88, v89
	v_mul_f32_e32 v87, v87, v87
	v_cvt_pk_bf16_f32 v84, v92, v93
	v_cvt_pk_bf16_f32 v85, v90, v91
	v_mul_f32_e32 v89, v89, v89
	v_mul_f32_e32 v93, v93, v93
	v_mul_f32_e32 v91, v91, v91
	v_fmac_f32_e32 v87, v86, v86
	v_fmac_f32_e32 v89, v88, v88
	v_fmac_f32_e32 v93, v92, v92
	v_fmac_f32_e32 v91, v90, v90
	global_store_dwordx4 v[104:105], v[82:85], off offset:256
	s_nop 1
	v_add_f32_e32 v82, v87, v89
	v_add_f32_e32 v83, v93, v91
	v_add_f32_e32 v82, v82, v83
	v_add_f32_e32 v82, v99, v82
	v_mov_b32_e32 v83, v82
	s_nop 1
	v_permlane16_swap_b32_e32 v82, v83
	v_add_f32_e32 v82, v82, v83
	v_mov_b32_e32 v83, v82
	s_nop 1
	v_permlane32_swap_b32_e32 v82, v83
	s_and_saveexec_b64 s[4:5], vcc
	v_add_f32_e32 v82, v82, v83
	v_lshl_add_u32 v83, v98, 4, s1
	ds_write_b32 v83, v82
	s_or_b64 exec, exec, s[4:5]
	v_or_b32_e32 v82, 48, v1
	v_add_u32_e32 v84, s0, v82
	v_ashrrev_i32_e32 v85, 31, v84
	v_lshlrev_b64 v[84:85], 11, v[84:85]
	v_lshl_add_u64 v[84:85], s[68:69], 0, v[84:85]
	v_lshl_add_u64 v[88:89], v[130:131], 1, v[84:85]
	s_waitcnt vmcnt(15)
	v_mov_b32_e32 v84, v176
	v_mov_b32_e32 v85, v177
	v_mov_b32_e32 v86, v178
	v_mov_b32_e32 v87, v179
	v_lshlrev_b32_e32 v90, 16, v84
	v_and_b32_e32 v91, 0xffff0000, v84
	v_lshlrev_b32_e32 v84, 16, v85
	v_and_b32_e32 v85, 0xffff0000, v85
	v_lshlrev_b32_e32 v92, 16, v86
	v_and_b32_e32 v93, 0xffff0000, v86
	v_lshlrev_b32_e32 v86, 16, v87
	v_and_b32_e32 v87, 0xffff0000, v87
	v_pk_add_f32 v[84:85], v[80:81], v[84:85]
	v_pk_add_f32 v[90:91], v[78:79], v[90:91]
	v_pk_add_f32 v[86:87], v[76:77], v[86:87]
	v_pk_add_f32 v[92:93], v[74:75], v[92:93]
	v_cvt_pk_bf16_f32 v74, v90, v91
	v_cvt_pk_bf16_f32 v75, v84, v85
	v_mul_f32_e32 v83, v91, v91
	v_cvt_pk_bf16_f32 v76, v92, v93
	v_cvt_pk_bf16_f32 v77, v86, v87
	s_waitcnt vmcnt(14)
	v_mov_b32_e32 v78, v180
	v_mov_b32_e32 v79, v181
	v_mov_b32_e32 v80, v182
	v_mov_b32_e32 v81, v183
	v_mul_f32_e32 v85, v85, v85
	v_mul_f32_e32 v91, v93, v93
	v_mul_f32_e32 v87, v87, v87
	v_fmac_f32_e32 v83, v90, v90
	v_fmac_f32_e32 v85, v84, v84
	v_fmac_f32_e32 v91, v92, v92
	v_fmac_f32_e32 v87, v86, v86
	global_store_dwordx4 v[88:89], v[74:77], off
	s_nop 1
	v_add_f32_e32 v74, v83, v85
	v_add_f32_e32 v75, v91, v87
	v_add_f32_e32 v83, v74, v75
	v_lshlrev_b32_e32 v74, 16, v78
	v_and_b32_e32 v75, 0xffff0000, v78
	v_lshlrev_b32_e32 v76, 16, v79
	v_and_b32_e32 v77, 0xffff0000, v79
	v_lshlrev_b32_e32 v78, 16, v80
	v_and_b32_e32 v79, 0xffff0000, v80
	v_lshlrev_b32_e32 v80, 16, v81
	v_and_b32_e32 v81, 0xffff0000, v81
	v_pk_add_f32 v[72:73], v[72:73], v[76:77]
	v_pk_add_f32 v[70:71], v[70:71], v[74:75]
	v_pk_add_f32 v[74:75], v[68:69], v[80:81]
	v_pk_add_f32 v[76:77], v[66:67], v[78:79]
	v_cvt_pk_bf16_f32 v66, v70, v71
	v_cvt_pk_bf16_f32 v67, v72, v73
	v_mul_f32_e32 v71, v71, v71
	v_cvt_pk_bf16_f32 v68, v76, v77
	v_cvt_pk_bf16_f32 v69, v74, v75
	v_mul_f32_e32 v73, v73, v73
	v_mul_f32_e32 v77, v77, v77
	v_mul_f32_e32 v75, v75, v75
	v_fmac_f32_e32 v71, v70, v70
	v_fmac_f32_e32 v73, v72, v72
	v_fmac_f32_e32 v77, v76, v76
	v_fmac_f32_e32 v75, v74, v74
	global_store_dwordx4 v[88:89], v[66:69], off offset:256
	s_nop 1
	v_add_f32_e32 v66, v71, v73
	v_add_f32_e32 v67, v77, v75
	v_add_f32_e32 v66, v66, v67
	v_add_f32_e32 v66, v83, v66
	v_mov_b32_e32 v67, v66
	s_nop 1
	v_permlane16_swap_b32_e32 v66, v67
	v_add_f32_e32 v66, v66, v67
	v_mov_b32_e32 v67, v66
	s_nop 1
	v_permlane32_swap_b32_e32 v66, v67
	s_and_saveexec_b64 s[4:5], vcc
	v_add_f32_e32 v66, v66, v67
	v_lshl_add_u32 v67, v82, 4, s1
	ds_write_b32 v67, v66
	s_or_b64 exec, exec, s[4:5]
	v_add_u32_e32 v66, 0x80, v1
	v_add_u32_e32 v68, s0, v66
	v_ashrrev_i32_e32 v69, 31, v68
	v_lshlrev_b64 v[68:69], 11, v[68:69]
	v_lshl_add_u64 v[68:69], s[68:69], 0, v[68:69]
	v_lshl_add_u64 v[72:73], v[130:131], 1, v[68:69]
	s_waitcnt vmcnt(15)
	v_mov_b32_e32 v68, v184
	v_mov_b32_e32 v69, v185
	v_mov_b32_e32 v70, v186
	v_mov_b32_e32 v71, v187
	v_lshlrev_b32_e32 v74, 16, v68
	v_and_b32_e32 v75, 0xffff0000, v68
	v_lshlrev_b32_e32 v68, 16, v69
	v_and_b32_e32 v69, 0xffff0000, v69
	v_lshlrev_b32_e32 v76, 16, v70
	v_and_b32_e32 v77, 0xffff0000, v70
	v_lshlrev_b32_e32 v70, 16, v71
	v_and_b32_e32 v71, 0xffff0000, v71
	v_pk_add_f32 v[68:69], v[64:65], v[68:69]
	v_pk_add_f32 v[74:75], v[62:63], v[74:75]
	v_pk_add_f32 v[70:71], v[60:61], v[70:71]
	v_pk_add_f32 v[76:77], v[58:59], v[76:77]
	v_cvt_pk_bf16_f32 v58, v74, v75
	v_cvt_pk_bf16_f32 v59, v68, v69
	v_mul_f32_e32 v67, v75, v75
	v_cvt_pk_bf16_f32 v60, v76, v77
	v_cvt_pk_bf16_f32 v61, v70, v71
	s_waitcnt vmcnt(14)
	v_mov_b32_e32 v62, v188
	v_mov_b32_e32 v63, v189
	v_mov_b32_e32 v64, v190
	v_mov_b32_e32 v65, v191
	v_mul_f32_e32 v69, v69, v69
	v_mul_f32_e32 v75, v77, v77
	v_mul_f32_e32 v71, v71, v71
	v_fmac_f32_e32 v67, v74, v74
	v_fmac_f32_e32 v69, v68, v68
	v_fmac_f32_e32 v75, v76, v76
	v_fmac_f32_e32 v71, v70, v70
	global_store_dwordx4 v[72:73], v[58:61], off
	s_nop 1
	v_add_f32_e32 v58, v67, v69
	v_add_f32_e32 v59, v75, v71
	v_add_f32_e32 v67, v58, v59
	v_lshlrev_b32_e32 v58, 16, v62
	v_and_b32_e32 v59, 0xffff0000, v62
	v_lshlrev_b32_e32 v60, 16, v63
	v_and_b32_e32 v61, 0xffff0000, v63
	v_lshlrev_b32_e32 v62, 16, v64
	v_and_b32_e32 v63, 0xffff0000, v64
	v_lshlrev_b32_e32 v64, 16, v65
	v_and_b32_e32 v65, 0xffff0000, v65
	v_pk_add_f32 v[56:57], v[56:57], v[60:61]
	v_pk_add_f32 v[54:55], v[54:55], v[58:59]
	v_pk_add_f32 v[58:59], v[52:53], v[64:65]
	v_pk_add_f32 v[60:61], v[50:51], v[62:63]
	v_cvt_pk_bf16_f32 v50, v54, v55
	v_cvt_pk_bf16_f32 v51, v56, v57
	v_mul_f32_e32 v55, v55, v55
	v_cvt_pk_bf16_f32 v52, v60, v61
	v_cvt_pk_bf16_f32 v53, v58, v59
	v_mul_f32_e32 v57, v57, v57
	v_mul_f32_e32 v61, v61, v61
	v_mul_f32_e32 v59, v59, v59
	v_fmac_f32_e32 v55, v54, v54
	v_fmac_f32_e32 v57, v56, v56
	v_fmac_f32_e32 v61, v60, v60
	v_fmac_f32_e32 v59, v58, v58
	global_store_dwordx4 v[72:73], v[50:53], off offset:256
	s_nop 1
	v_add_f32_e32 v50, v55, v57
	v_add_f32_e32 v51, v61, v59
	v_add_f32_e32 v50, v50, v51
	v_add_f32_e32 v50, v67, v50
	v_mov_b32_e32 v51, v50
	s_nop 1
	v_permlane16_swap_b32_e32 v50, v51
	v_add_f32_e32 v50, v50, v51
	v_mov_b32_e32 v51, v50
	s_nop 1
	v_permlane32_swap_b32_e32 v50, v51
	s_and_saveexec_b64 s[4:5], vcc
	v_add_f32_e32 v50, v50, v51
	v_lshl_add_u32 v51, v66, 4, s1
	ds_write_b32 v51, v50
	s_or_b64 exec, exec, s[4:5]
	v_add_u32_e32 v50, 0x90, v1
	v_add_u32_e32 v52, s0, v50
	v_ashrrev_i32_e32 v53, 31, v52
	v_lshlrev_b64 v[52:53], 11, v[52:53]
	v_lshl_add_u64 v[52:53], s[68:69], 0, v[52:53]
	v_lshl_add_u64 v[56:57], v[130:131], 1, v[52:53]
	s_waitcnt vmcnt(15)
	v_mov_b32_e32 v52, v192
	v_mov_b32_e32 v53, v193
	v_mov_b32_e32 v54, v194
	v_mov_b32_e32 v55, v195
	v_lshlrev_b32_e32 v58, 16, v52
	v_and_b32_e32 v59, 0xffff0000, v52
	v_lshlrev_b32_e32 v52, 16, v53
	v_and_b32_e32 v53, 0xffff0000, v53
	v_lshlrev_b32_e32 v60, 16, v54
	v_and_b32_e32 v61, 0xffff0000, v54
	v_lshlrev_b32_e32 v54, 16, v55
	v_and_b32_e32 v55, 0xffff0000, v55
	v_pk_add_f32 v[52:53], v[48:49], v[52:53]
	v_pk_add_f32 v[58:59], v[46:47], v[58:59]
	v_pk_add_f32 v[54:55], v[44:45], v[54:55]
	v_pk_add_f32 v[60:61], v[42:43], v[60:61]
	v_cvt_pk_bf16_f32 v42, v58, v59
	v_cvt_pk_bf16_f32 v43, v52, v53
	v_mul_f32_e32 v51, v59, v59
	v_cvt_pk_bf16_f32 v44, v60, v61
	v_cvt_pk_bf16_f32 v45, v54, v55
	s_waitcnt vmcnt(14)
	v_mov_b32_e32 v46, v196
	v_mov_b32_e32 v47, v197
	v_mov_b32_e32 v48, v198
	v_mov_b32_e32 v49, v199
	v_mul_f32_e32 v53, v53, v53
	v_mul_f32_e32 v59, v61, v61
	v_mul_f32_e32 v55, v55, v55
	v_fmac_f32_e32 v51, v58, v58
	v_fmac_f32_e32 v53, v52, v52
	v_fmac_f32_e32 v59, v60, v60
	v_fmac_f32_e32 v55, v54, v54
	global_store_dwordx4 v[56:57], v[42:45], off
	s_nop 1
	v_add_f32_e32 v42, v51, v53
	v_add_f32_e32 v43, v59, v55
	v_add_f32_e32 v51, v42, v43
	v_lshlrev_b32_e32 v42, 16, v46
	v_and_b32_e32 v43, 0xffff0000, v46
	v_lshlrev_b32_e32 v44, 16, v47
	v_and_b32_e32 v45, 0xffff0000, v47
	v_lshlrev_b32_e32 v46, 16, v48
	v_and_b32_e32 v47, 0xffff0000, v48
	v_lshlrev_b32_e32 v48, 16, v49
	v_and_b32_e32 v49, 0xffff0000, v49
	v_pk_add_f32 v[40:41], v[40:41], v[44:45]
	v_pk_add_f32 v[38:39], v[38:39], v[42:43]
	v_pk_add_f32 v[42:43], v[36:37], v[48:49]
	v_pk_add_f32 v[44:45], v[34:35], v[46:47]
	v_cvt_pk_bf16_f32 v34, v38, v39
	v_cvt_pk_bf16_f32 v35, v40, v41
	v_mul_f32_e32 v39, v39, v39
	v_cvt_pk_bf16_f32 v36, v44, v45
	v_cvt_pk_bf16_f32 v37, v42, v43
	v_mul_f32_e32 v41, v41, v41
	v_mul_f32_e32 v45, v45, v45
	v_mul_f32_e32 v43, v43, v43
	v_fmac_f32_e32 v39, v38, v38
	v_fmac_f32_e32 v41, v40, v40
	v_fmac_f32_e32 v45, v44, v44
	v_fmac_f32_e32 v43, v42, v42
	global_store_dwordx4 v[56:57], v[34:37], off offset:256
	s_nop 1
	v_add_f32_e32 v34, v39, v41
	v_add_f32_e32 v35, v45, v43
	v_add_f32_e32 v34, v34, v35
	v_add_f32_e32 v34, v51, v34
	v_mov_b32_e32 v35, v34
	s_nop 1
	v_permlane16_swap_b32_e32 v34, v35
	v_add_f32_e32 v34, v34, v35
	v_mov_b32_e32 v35, v34
	s_nop 1
	v_permlane32_swap_b32_e32 v34, v35
	s_and_saveexec_b64 s[4:5], vcc
	v_add_f32_e32 v34, v34, v35
	v_lshl_add_u32 v35, v50, 4, s1
	ds_write_b32 v35, v34
	s_or_b64 exec, exec, s[4:5]
	v_add_u32_e32 v34, 0xa0, v1
	v_add_u32_e32 v36, s0, v34
	v_ashrrev_i32_e32 v37, 31, v36
	v_lshlrev_b64 v[36:37], 11, v[36:37]
	v_lshl_add_u64 v[36:37], s[68:69], 0, v[36:37]
	v_lshl_add_u64 v[40:41], v[130:131], 1, v[36:37]
	s_waitcnt vmcnt(15)
	v_mov_b32_e32 v36, v200
	v_mov_b32_e32 v37, v201
	v_mov_b32_e32 v38, v202
	v_mov_b32_e32 v39, v203
	v_lshlrev_b32_e32 v42, 16, v36
	v_and_b32_e32 v43, 0xffff0000, v36
	v_lshlrev_b32_e32 v36, 16, v37
	v_and_b32_e32 v37, 0xffff0000, v37
	v_lshlrev_b32_e32 v44, 16, v38
	v_and_b32_e32 v45, 0xffff0000, v38
	v_lshlrev_b32_e32 v38, 16, v39
	v_and_b32_e32 v39, 0xffff0000, v39
	v_pk_add_f32 v[36:37], v[32:33], v[36:37]
	v_pk_add_f32 v[42:43], v[30:31], v[42:43]
	v_pk_add_f32 v[38:39], v[28:29], v[38:39]
	v_pk_add_f32 v[44:45], v[26:27], v[44:45]
	v_cvt_pk_bf16_f32 v26, v42, v43
	v_cvt_pk_bf16_f32 v27, v36, v37
	v_mul_f32_e32 v35, v43, v43
	v_cvt_pk_bf16_f32 v28, v44, v45
	v_cvt_pk_bf16_f32 v29, v38, v39
	s_waitcnt vmcnt(14)
	v_mov_b32_e32 v30, v204
	v_mov_b32_e32 v31, v205
	v_mov_b32_e32 v32, v206
	v_mov_b32_e32 v33, v207
	v_mul_f32_e32 v37, v37, v37
	v_mul_f32_e32 v43, v45, v45
	v_mul_f32_e32 v39, v39, v39
	v_fmac_f32_e32 v35, v42, v42
	v_fmac_f32_e32 v37, v36, v36
	v_fmac_f32_e32 v43, v44, v44
	v_fmac_f32_e32 v39, v38, v38
	global_store_dwordx4 v[40:41], v[26:29], off
	s_nop 1
	v_add_f32_e32 v26, v35, v37
	v_add_f32_e32 v27, v43, v39
	v_add_f32_e32 v35, v26, v27
	v_lshlrev_b32_e32 v26, 16, v30
	v_and_b32_e32 v27, 0xffff0000, v30
	v_lshlrev_b32_e32 v28, 16, v31
	v_and_b32_e32 v29, 0xffff0000, v31
	v_lshlrev_b32_e32 v30, 16, v32
	v_and_b32_e32 v31, 0xffff0000, v32
	v_lshlrev_b32_e32 v32, 16, v33
	v_and_b32_e32 v33, 0xffff0000, v33
	v_pk_add_f32 v[24:25], v[24:25], v[28:29]
	v_pk_add_f32 v[22:23], v[22:23], v[26:27]
	v_pk_add_f32 v[26:27], v[20:21], v[32:33]
	v_pk_add_f32 v[28:29], v[18:19], v[30:31]
	v_cvt_pk_bf16_f32 v18, v22, v23
	v_cvt_pk_bf16_f32 v19, v24, v25
	v_mul_f32_e32 v23, v23, v23
	v_cvt_pk_bf16_f32 v20, v28, v29
	v_cvt_pk_bf16_f32 v21, v26, v27
	v_mul_f32_e32 v25, v25, v25
	v_mul_f32_e32 v29, v29, v29
	v_mul_f32_e32 v27, v27, v27
	v_fmac_f32_e32 v23, v22, v22
	v_fmac_f32_e32 v25, v24, v24
	v_fmac_f32_e32 v29, v28, v28
	v_fmac_f32_e32 v27, v26, v26
	global_store_dwordx4 v[40:41], v[18:21], off offset:256
	s_nop 1
	v_add_f32_e32 v18, v23, v25
	v_add_f32_e32 v19, v29, v27
	v_add_f32_e32 v18, v18, v19
	v_add_f32_e32 v18, v35, v18
	v_mov_b32_e32 v19, v18
	s_nop 1
	v_permlane16_swap_b32_e32 v18, v19
	v_add_f32_e32 v18, v18, v19
	v_mov_b32_e32 v19, v18
	s_nop 1
	v_permlane32_swap_b32_e32 v18, v19
	s_and_saveexec_b64 s[4:5], vcc
	v_add_f32_e32 v18, v18, v19
	v_lshl_add_u32 v19, v34, 4, s1
	ds_write_b32 v19, v18
	s_or_b64 exec, exec, s[4:5]
	v_add_u32_e32 v1, 0xb0, v1
	v_add_u32_e32 v18, s0, v1
	v_ashrrev_i32_e32 v19, 31, v18
	v_lshlrev_b64 v[18:19], 11, v[18:19]
	v_lshl_add_u64 v[18:19], s[68:69], 0, v[18:19]
	v_lshl_add_u64 v[22:23], v[130:131], 1, v[18:19]
	s_waitcnt vmcnt(15)
	v_mov_b32_e32 v18, v208
	v_mov_b32_e32 v19, v209
	v_mov_b32_e32 v20, v210
	v_mov_b32_e32 v21, v211
	v_lshlrev_b32_e32 v24, 16, v18
	v_and_b32_e32 v25, 0xffff0000, v18
	v_lshlrev_b32_e32 v18, 16, v19
	v_and_b32_e32 v19, 0xffff0000, v19
	v_lshlrev_b32_e32 v26, 16, v20
	v_and_b32_e32 v27, 0xffff0000, v20
	v_lshlrev_b32_e32 v20, 16, v21
	v_and_b32_e32 v21, 0xffff0000, v21
	v_pk_add_f32 v[18:19], v[16:17], v[18:19]
	v_pk_add_f32 v[24:25], v[14:15], v[24:25]
	v_pk_add_f32 v[20:21], v[12:13], v[20:21]
	v_pk_add_f32 v[26:27], v[10:11], v[26:27]
	v_cvt_pk_bf16_f32 v10, v24, v25
	v_cvt_pk_bf16_f32 v11, v18, v19
	v_mul_f32_e32 v25, v25, v25
	v_cvt_pk_bf16_f32 v12, v26, v27
	v_cvt_pk_bf16_f32 v13, v20, v21
	s_waitcnt vmcnt(14)
	v_mov_b32_e32 v14, v212
	v_mov_b32_e32 v15, v213
	v_mov_b32_e32 v16, v214
	v_mov_b32_e32 v17, v215
	v_mul_f32_e32 v19, v19, v19
	v_mul_f32_e32 v27, v27, v27
	v_mul_f32_e32 v21, v21, v21
	v_fmac_f32_e32 v25, v24, v24
	v_fmac_f32_e32 v19, v18, v18
	v_fmac_f32_e32 v27, v26, v26
	v_fmac_f32_e32 v21, v20, v20
	global_store_dwordx4 v[22:23], v[10:13], off
	s_nop 1
	v_add_f32_e32 v10, v25, v19
	v_add_f32_e32 v11, v27, v21
	v_add_f32_e32 v18, v10, v11
	v_lshlrev_b32_e32 v10, 16, v14
	v_and_b32_e32 v11, 0xffff0000, v14
	v_lshlrev_b32_e32 v12, 16, v15
	v_and_b32_e32 v13, 0xffff0000, v15
	v_lshlrev_b32_e32 v14, 16, v16
	v_and_b32_e32 v15, 0xffff0000, v16
	v_lshlrev_b32_e32 v16, 16, v17
	v_and_b32_e32 v17, 0xffff0000, v17
	v_pk_add_f32 v[8:9], v[8:9], v[12:13]
	v_pk_add_f32 v[6:7], v[6:7], v[10:11]
	v_pk_add_f32 v[10:11], v[4:5], v[16:17]
	v_pk_add_f32 v[12:13], v[2:3], v[14:15]
	v_cvt_pk_bf16_f32 v2, v6, v7
	v_cvt_pk_bf16_f32 v3, v8, v9
	v_mul_f32_e32 v7, v7, v7
	v_cvt_pk_bf16_f32 v4, v12, v13
	v_cvt_pk_bf16_f32 v5, v10, v11
	v_mul_f32_e32 v9, v9, v9
	v_mul_f32_e32 v13, v13, v13
	v_mul_f32_e32 v11, v11, v11
	v_fmac_f32_e32 v7, v6, v6
	v_fmac_f32_e32 v9, v8, v8
	v_fmac_f32_e32 v13, v12, v12
	v_fmac_f32_e32 v11, v10, v10
	global_store_dwordx4 v[22:23], v[2:5], off offset:256
	s_nop 1
	v_add_f32_e32 v2, v7, v9
	v_add_f32_e32 v3, v13, v11
	v_add_f32_e32 v2, v2, v3
	v_add_f32_e32 v2, v18, v2
	v_mov_b32_e32 v3, v2
	s_nop 1
	v_permlane16_swap_b32_e32 v2, v3
	v_add_f32_e32 v2, v2, v3
	v_mov_b32_e32 v3, v2
	s_nop 1
	v_permlane32_swap_b32_e32 v2, v3
	s_and_saveexec_b64 s[4:5], vcc
	v_add_f32_e32 v2, v2, v3
	v_lshl_add_u32 v1, v1, 4, s1
	ds_write_b32 v1, v2
	s_or_b64 exec, exec, s[4:5]
	s_waitcnt lgkmcnt(0)
	s_barrier
	s_andn2_b32 s11, s11, 63
	v_or_b32_e32 v1, s11, v252
	s_movk_i32 s1, 0x100
	v_cmp_gt_i32_e32 vcc, s1, v1
	s_and_saveexec_b64 s[4:5], vcc
	s_cbranch_execz .LBB0_1656
	v_lshl_add_u32 v2, v1, 4, 0
	ds_read_b128 v[2:5], v2
	v_add_u32_e32 v6, s0, v1
	v_ashrrev_i32_e32 v7, 31, v6
	s_ashr_i32 s11, s10, 31
	s_waitcnt lgkmcnt(0)
	v_mov_b32_e32 v8, v3
	v_mov_b32_e32 v9, v4
	v_mov_b32_e32 v3, v5
	v_pk_add_f32 v[2:3], v[8:9], v[2:3]
	s_nop 0
	v_add_f32_e32 v1, v2, v3
	v_lshl_add_u64 v[2:3], v[6:7], 4, s[8:9]
	v_lshl_add_u64 v[2:3], s[10:11], 2, v[2:3]
	global_store_dword v[2:3], v1, off

.LBB0_1901:
	s_lshl_b32 s0, s30, 5
	s_lshl_b32 s1, s16, 8
	s_or_b32 s0, s1, s0
	v_and_or_b32 v130, v150, 24, s0
	s_lshl_b32 s0, s31, 8
	v_add_u32_e32 v132, s0, v1
	v_ashrrev_i32_e32 v133, 31, v132
	v_lshlrev_b64 v[132:133], 11, v[132:133]
	v_ashrrev_i32_e32 v131, 31, v130
	v_lshl_add_u64 v[132:133], s[68:69], 0, v[132:133]
	v_lshl_add_u64 v[136:137], v[130:131], 1, v[132:133]
	s_barrier
	global_load_dwordx4 v[152:155], v[136:137], off
	global_load_dwordx4 v[156:159], v[136:137], off offset:256
	s_mov_b64 s[98:99], 0x8000
	v_lshl_add_u64 v[216:217], v[136:137], 0, s[98:99]
	global_load_dwordx4 v[160:163], v[216:217], off
	global_load_dwordx4 v[164:167], v[216:217], off offset:256
	s_mov_b64 s[98:99], 0x10000
	v_lshl_add_u64 v[218:219], v[136:137], 0, s[98:99]
	global_load_dwordx4 v[168:171], v[218:219], off
	global_load_dwordx4 v[172:175], v[218:219], off offset:256
	s_mov_b64 s[98:99], 0x18000
	v_lshl_add_u64 v[220:221], v[136:137], 0, s[98:99]
	global_load_dwordx4 v[176:179], v[220:221], off
	global_load_dwordx4 v[180:183], v[220:221], off offset:256
	s_mov_b64 s[98:99], 0x40000
	v_lshl_add_u64 v[222:223], v[136:137], 0, s[98:99]
	global_load_dwordx4 v[184:187], v[222:223], off
	global_load_dwordx4 v[188:191], v[222:223], off offset:256
	s_mov_b64 s[98:99], 0x48000
	v_lshl_add_u64 v[224:225], v[136:137], 0, s[98:99]
	global_load_dwordx4 v[192:195], v[224:225], off
	global_load_dwordx4 v[196:199], v[224:225], off offset:256
	s_mov_b64 s[98:99], 0x50000
	v_lshl_add_u64 v[226:227], v[136:137], 0, s[98:99]
	global_load_dwordx4 v[200:203], v[226:227], off
	global_load_dwordx4 v[204:207], v[226:227], off offset:256
	s_mov_b64 s[98:99], 0x58000
	v_lshl_add_u64 v[228:229], v[136:137], 0, s[98:99]
	global_load_dwordx4 v[208:211], v[228:229], off
	global_load_dwordx4 v[212:215], v[228:229], off offset:256
	s_waitcnt vmcnt(15)
	v_mov_b32_e32 v132, v152
	v_mov_b32_e32 v133, v153
	v_mov_b32_e32 v134, v154
	v_mov_b32_e32 v135, v155
	s_lshl_b32 s1, s30, 2
	v_cmp_gt_u32_e32 vcc, 16, v252
	s_add_i32 s1, s1, 0
	v_lshlrev_b32_e32 v138, 16, v132
	v_and_b32_e32 v139, 0xffff0000, v132
	v_lshlrev_b32_e32 v132, 16, v133
	v_and_b32_e32 v133, 0xffff0000, v133
	v_lshlrev_b32_e32 v140, 16, v134
	v_and_b32_e32 v141, 0xffff0000, v134
	v_lshlrev_b32_e32 v134, 16, v135
	v_and_b32_e32 v135, 0xffff0000, v135
	v_pk_fma_f32 v[132:133], v[128:129], 0.5, v[132:133] op_sel_hi:[1,0,1]
	v_pk_fma_f32 v[138:139], v[126:127], 0.5, v[138:139] op_sel_hi:[1,0,1]
	v_pk_fma_f32 v[134:135], v[124:125], 0.5, v[134:135] op_sel_hi:[1,0,1]
	v_pk_fma_f32 v[140:141], v[122:123], 0.5, v[140:141] op_sel_hi:[1,0,1]
	v_cvt_pk_bf16_f32 v122, v138, v139
	v_cvt_pk_bf16_f32 v123, v132, v133
	v_mul_f32_e32 v139, v139, v139
	v_cvt_pk_bf16_f32 v124, v140, v141
	v_cvt_pk_bf16_f32 v125, v134, v135
	s_waitcnt vmcnt(14)
	v_mov_b32_e32 v126, v156
	v_mov_b32_e32 v127, v157
	v_mov_b32_e32 v128, v158
	v_mov_b32_e32 v129, v159
	v_mul_f32_e32 v133, v133, v133
	v_mul_f32_e32 v141, v141, v141
	v_mul_f32_e32 v135, v135, v135
	v_fmac_f32_e32 v139, v138, v138
	v_fmac_f32_e32 v133, v132, v132
	v_fmac_f32_e32 v141, v140, v140
	v_fmac_f32_e32 v135, v134, v134
	global_store_dwordx4 v[136:137], v[122:125], off
	s_nop 1
	v_add_f32_e32 v122, v139, v133
	v_add_f32_e32 v123, v141, v135
	v_add_f32_e32 v132, v122, v123
	v_lshlrev_b32_e32 v122, 16, v126
	v_and_b32_e32 v123, 0xffff0000, v126
	v_lshlrev_b32_e32 v124, 16, v127
	v_and_b32_e32 v125, 0xffff0000, v127
	v_lshlrev_b32_e32 v126, 16, v128
	v_and_b32_e32 v127, 0xffff0000, v128
	v_lshlrev_b32_e32 v128, 16, v129
	v_and_b32_e32 v129, 0xffff0000, v129
	v_pk_fma_f32 v[120:121], v[120:121], 0.5, v[124:125] op_sel_hi:[1,0,1]
	v_pk_fma_f32 v[118:119], v[118:119], 0.5, v[122:123] op_sel_hi:[1,0,1]
	v_pk_fma_f32 v[122:123], v[116:117], 0.5, v[128:129] op_sel_hi:[1,0,1]
	v_pk_fma_f32 v[124:125], v[114:115], 0.5, v[126:127] op_sel_hi:[1,0,1]
	v_cvt_pk_bf16_f32 v114, v118, v119
	v_cvt_pk_bf16_f32 v115, v120, v121
	v_mul_f32_e32 v119, v119, v119
	v_cvt_pk_bf16_f32 v116, v124, v125
	v_cvt_pk_bf16_f32 v117, v122, v123
	v_mul_f32_e32 v121, v121, v121
	v_mul_f32_e32 v125, v125, v125
	v_mul_f32_e32 v123, v123, v123
	v_fmac_f32_e32 v119, v118, v118
	v_fmac_f32_e32 v121, v120, v120
	v_fmac_f32_e32 v125, v124, v124
	v_fmac_f32_e32 v123, v122, v122
	global_store_dwordx4 v[136:137], v[114:117], off offset:256
	s_nop 1
	v_add_f32_e32 v114, v119, v121
	v_add_f32_e32 v115, v125, v123
	v_add_f32_e32 v114, v114, v115
	v_add_f32_e32 v114, v132, v114
	v_mov_b32_e32 v115, v114
	s_nop 1
	v_permlane16_swap_b32_e32 v114, v115
	v_add_f32_e32 v114, v114, v115
	v_mov_b32_e32 v115, v114
	s_nop 1
	v_permlane32_swap_b32_e32 v114, v115
	s_and_saveexec_b64 s[4:5], vcc
	v_add_f32_e32 v114, v114, v115
	v_lshl_add_u32 v115, v1, 4, s1
	ds_write_b32 v115, v114
	s_or_b64 exec, exec, s[4:5]
	v_or_b32_e32 v114, 16, v1
	v_add_u32_e32 v116, s0, v114
	v_ashrrev_i32_e32 v117, 31, v116
	v_lshlrev_b64 v[116:117], 11, v[116:117]
	v_lshl_add_u64 v[116:117], s[68:69], 0, v[116:117]
	v_lshl_add_u64 v[120:121], v[130:131], 1, v[116:117]
	s_waitcnt vmcnt(15)
	v_mov_b32_e32 v116, v160
	v_mov_b32_e32 v117, v161
	v_mov_b32_e32 v118, v162
	v_mov_b32_e32 v119, v163
	v_lshlrev_b32_e32 v122, 16, v116
	v_and_b32_e32 v123, 0xffff0000, v116
	v_lshlrev_b32_e32 v116, 16, v117
	v_and_b32_e32 v117, 0xffff0000, v117
	v_lshlrev_b32_e32 v124, 16, v118
	v_and_b32_e32 v125, 0xffff0000, v118
	v_lshlrev_b32_e32 v118, 16, v119
	v_and_b32_e32 v119, 0xffff0000, v119
	v_pk_fma_f32 v[116:117], v[112:113], 0.5, v[116:117] op_sel_hi:[1,0,1]
	v_pk_fma_f32 v[122:123], v[110:111], 0.5, v[122:123] op_sel_hi:[1,0,1]
	v_pk_fma_f32 v[118:119], v[108:109], 0.5, v[118:119] op_sel_hi:[1,0,1]
	v_pk_fma_f32 v[124:125], v[106:107], 0.5, v[124:125] op_sel_hi:[1,0,1]
	v_cvt_pk_bf16_f32 v106, v122, v123
	v_cvt_pk_bf16_f32 v107, v116, v117
	v_mul_f32_e32 v115, v123, v123
	v_cvt_pk_bf16_f32 v108, v124, v125
	v_cvt_pk_bf16_f32 v109, v118, v119
	s_waitcnt vmcnt(14)
	v_mov_b32_e32 v110, v164
	v_mov_b32_e32 v111, v165
	v_mov_b32_e32 v112, v166
	v_mov_b32_e32 v113, v167
	v_mul_f32_e32 v117, v117, v117
	v_mul_f32_e32 v123, v125, v125
	v_mul_f32_e32 v119, v119, v119
	v_fmac_f32_e32 v115, v122, v122
	v_fmac_f32_e32 v117, v116, v116
	v_fmac_f32_e32 v123, v124, v124
	v_fmac_f32_e32 v119, v118, v118
	global_store_dwordx4 v[120:121], v[106:109], off
	s_nop 1
	v_add_f32_e32 v106, v115, v117
	v_add_f32_e32 v107, v123, v119
	v_add_f32_e32 v115, v106, v107
	v_lshlrev_b32_e32 v106, 16, v110
	v_and_b32_e32 v107, 0xffff0000, v110
	v_lshlrev_b32_e32 v108, 16, v111
	v_and_b32_e32 v109, 0xffff0000, v111
	v_lshlrev_b32_e32 v110, 16, v112
	v_and_b32_e32 v111, 0xffff0000, v112
	v_lshlrev_b32_e32 v112, 16, v113
	v_and_b32_e32 v113, 0xffff0000, v113
	v_pk_fma_f32 v[104:105], v[104:105], 0.5, v[108:109] op_sel_hi:[1,0,1]
	v_pk_fma_f32 v[102:103], v[102:103], 0.5, v[106:107] op_sel_hi:[1,0,1]
	v_pk_fma_f32 v[106:107], v[100:101], 0.5, v[112:113] op_sel_hi:[1,0,1]
	v_pk_fma_f32 v[108:109], v[98:99], 0.5, v[110:111] op_sel_hi:[1,0,1]
	v_cvt_pk_bf16_f32 v98, v102, v103
	v_cvt_pk_bf16_f32 v99, v104, v105
	v_mul_f32_e32 v103, v103, v103
	v_cvt_pk_bf16_f32 v100, v108, v109
	v_cvt_pk_bf16_f32 v101, v106, v107
	v_mul_f32_e32 v105, v105, v105
	v_mul_f32_e32 v109, v109, v109
	v_mul_f32_e32 v107, v107, v107
	v_fmac_f32_e32 v103, v102, v102
	v_fmac_f32_e32 v105, v104, v104
	v_fmac_f32_e32 v109, v108, v108
	v_fmac_f32_e32 v107, v106, v106
	global_store_dwordx4 v[120:121], v[98:101], off offset:256
	s_nop 1
	v_add_f32_e32 v98, v103, v105
	v_add_f32_e32 v99, v109, v107
	v_add_f32_e32 v98, v98, v99
	v_add_f32_e32 v98, v115, v98
	v_mov_b32_e32 v99, v98
	s_nop 1
	v_permlane16_swap_b32_e32 v98, v99
	v_add_f32_e32 v98, v98, v99
	v_mov_b32_e32 v99, v98
	s_nop 1
	v_permlane32_swap_b32_e32 v98, v99
	s_and_saveexec_b64 s[4:5], vcc
	v_add_f32_e32 v98, v98, v99
	v_lshl_add_u32 v99, v114, 4, s1
	ds_write_b32 v99, v98
	s_or_b64 exec, exec, s[4:5]
	v_or_b32_e32 v98, 32, v1
	v_add_u32_e32 v100, s0, v98
	v_ashrrev_i32_e32 v101, 31, v100
	v_lshlrev_b64 v[100:101], 11, v[100:101]
	v_lshl_add_u64 v[100:101], s[68:69], 0, v[100:101]
	v_lshl_add_u64 v[104:105], v[130:131], 1, v[100:101]
	s_waitcnt vmcnt(15)
	v_mov_b32_e32 v100, v168
	v_mov_b32_e32 v101, v169
	v_mov_b32_e32 v102, v170
	v_mov_b32_e32 v103, v171
	v_lshlrev_b32_e32 v106, 16, v100
	v_and_b32_e32 v107, 0xffff0000, v100
	v_lshlrev_b32_e32 v100, 16, v101
	v_and_b32_e32 v101, 0xffff0000, v101
	v_lshlrev_b32_e32 v108, 16, v102
	v_and_b32_e32 v109, 0xffff0000, v102
	v_lshlrev_b32_e32 v102, 16, v103
	v_and_b32_e32 v103, 0xffff0000, v103
	v_pk_fma_f32 v[100:101], v[96:97], 0.5, v[100:101] op_sel_hi:[1,0,1]
	v_pk_fma_f32 v[106:107], v[94:95], 0.5, v[106:107] op_sel_hi:[1,0,1]
	v_pk_fma_f32 v[102:103], v[92:93], 0.5, v[102:103] op_sel_hi:[1,0,1]
	v_pk_fma_f32 v[108:109], v[90:91], 0.5, v[108:109] op_sel_hi:[1,0,1]
	v_cvt_pk_bf16_f32 v90, v106, v107
	v_cvt_pk_bf16_f32 v91, v100, v101
	v_mul_f32_e32 v99, v107, v107
	v_cvt_pk_bf16_f32 v92, v108, v109
	v_cvt_pk_bf16_f32 v93, v102, v103
	s_waitcnt vmcnt(14)
	v_mov_b32_e32 v94, v172
	v_mov_b32_e32 v95, v173
	v_mov_b32_e32 v96, v174
	v_mov_b32_e32 v97, v175
	v_mul_f32_e32 v101, v101, v101
	v_mul_f32_e32 v107, v109, v109
	v_mul_f32_e32 v103, v103, v103
	v_fmac_f32_e32 v99, v106, v106
	v_fmac_f32_e32 v101, v100, v100
	v_fmac_f32_e32 v107, v108, v108
	v_fmac_f32_e32 v103, v102, v102
	global_store_dwordx4 v[104:105], v[90:93], off
	s_nop 1
	v_add_f32_e32 v90, v99, v101
	v_add_f32_e32 v91, v107, v103
	v_add_f32_e32 v99, v90, v91
	v_lshlrev_b32_e32 v90, 16, v94
	v_and_b32_e32 v91, 0xffff0000, v94
	v_lshlrev_b32_e32 v92, 16, v95
	v_and_b32_e32 v93, 0xffff0000, v95
	v_lshlrev_b32_e32 v94, 16, v96
	v_and_b32_e32 v95, 0xffff0000, v96
	v_lshlrev_b32_e32 v96, 16, v97
	v_and_b32_e32 v97, 0xffff0000, v97
	v_pk_fma_f32 v[88:89], v[88:89], 0.5, v[92:93] op_sel_hi:[1,0,1]
	v_pk_fma_f32 v[86:87], v[86:87], 0.5, v[90:91] op_sel_hi:[1,0,1]
	v_pk_fma_f32 v[90:91], v[84:85], 0.5, v[96:97] op_sel_hi:[1,0,1]
	v_pk_fma_f32 v[92:93], v[82:83], 0.5, v[94:95] op_sel_hi:[1,0,1]
	v_cvt_pk_bf16_f32 v82, v86, v87
	v_cvt_pk_bf16_f32 v83, v88, v89
	v_mul_f32_e32 v87, v87, v87
	v_cvt_pk_bf16_f32 v84, v92, v93
	v_cvt_pk_bf16_f32 v85, v90, v91
	v_mul_f32_e32 v89, v89, v89
	v_mul_f32_e32 v93, v93, v93
	v_mul_f32_e32 v91, v91, v91
	v_fmac_f32_e32 v87, v86, v86
	v_fmac_f32_e32 v89, v88, v88
	v_fmac_f32_e32 v93, v92, v92
	v_fmac_f32_e32 v91, v90, v90
	global_store_dwordx4 v[104:105], v[82:85], off offset:256
	s_nop 1
	v_add_f32_e32 v82, v87, v89
	v_add_f32_e32 v83, v93, v91
	v_add_f32_e32 v82, v82, v83
	v_add_f32_e32 v82, v99, v82
	v_mov_b32_e32 v83, v82
	s_nop 1
	v_permlane16_swap_b32_e32 v82, v83
	v_add_f32_e32 v82, v82, v83
	v_mov_b32_e32 v83, v82
	s_nop 1
	v_permlane32_swap_b32_e32 v82, v83
	s_and_saveexec_b64 s[4:5], vcc
	v_add_f32_e32 v82, v82, v83
	v_lshl_add_u32 v83, v98, 4, s1
	ds_write_b32 v83, v82
	s_or_b64 exec, exec, s[4:5]
	v_or_b32_e32 v82, 48, v1
	v_add_u32_e32 v84, s0, v82
	v_ashrrev_i32_e32 v85, 31, v84
	v_lshlrev_b64 v[84:85], 11, v[84:85]
	v_lshl_add_u64 v[84:85], s[68:69], 0, v[84:85]
	v_lshl_add_u64 v[88:89], v[130:131], 1, v[84:85]
	s_waitcnt vmcnt(15)
	v_mov_b32_e32 v84, v176
	v_mov_b32_e32 v85, v177
	v_mov_b32_e32 v86, v178
	v_mov_b32_e32 v87, v179
	v_lshlrev_b32_e32 v90, 16, v84
	v_and_b32_e32 v91, 0xffff0000, v84
	v_lshlrev_b32_e32 v84, 16, v85
	v_and_b32_e32 v85, 0xffff0000, v85
	v_lshlrev_b32_e32 v92, 16, v86
	v_and_b32_e32 v93, 0xffff0000, v86
	v_lshlrev_b32_e32 v86, 16, v87
	v_and_b32_e32 v87, 0xffff0000, v87
	v_pk_fma_f32 v[84:85], v[80:81], 0.5, v[84:85] op_sel_hi:[1,0,1]
	v_pk_fma_f32 v[90:91], v[78:79], 0.5, v[90:91] op_sel_hi:[1,0,1]
	v_pk_fma_f32 v[86:87], v[76:77], 0.5, v[86:87] op_sel_hi:[1,0,1]
	v_pk_fma_f32 v[92:93], v[74:75], 0.5, v[92:93] op_sel_hi:[1,0,1]
	v_cvt_pk_bf16_f32 v74, v90, v91
	v_cvt_pk_bf16_f32 v75, v84, v85
	v_mul_f32_e32 v83, v91, v91
	v_cvt_pk_bf16_f32 v76, v92, v93
	v_cvt_pk_bf16_f32 v77, v86, v87
	s_waitcnt vmcnt(14)
	v_mov_b32_e32 v78, v180
	v_mov_b32_e32 v79, v181
	v_mov_b32_e32 v80, v182
	v_mov_b32_e32 v81, v183
	v_mul_f32_e32 v85, v85, v85
	v_mul_f32_e32 v91, v93, v93
	v_mul_f32_e32 v87, v87, v87
	v_fmac_f32_e32 v83, v90, v90
	v_fmac_f32_e32 v85, v84, v84
	v_fmac_f32_e32 v91, v92, v92
	v_fmac_f32_e32 v87, v86, v86
	global_store_dwordx4 v[88:89], v[74:77], off
	s_nop 1
	v_add_f32_e32 v74, v83, v85
	v_add_f32_e32 v75, v91, v87
	v_add_f32_e32 v83, v74, v75
	v_lshlrev_b32_e32 v74, 16, v78
	v_and_b32_e32 v75, 0xffff0000, v78
	v_lshlrev_b32_e32 v76, 16, v79
	v_and_b32_e32 v77, 0xffff0000, v79
	v_lshlrev_b32_e32 v78, 16, v80
	v_and_b32_e32 v79, 0xffff0000, v80
	v_lshlrev_b32_e32 v80, 16, v81
	v_and_b32_e32 v81, 0xffff0000, v81
	v_pk_fma_f32 v[72:73], v[72:73], 0.5, v[76:77] op_sel_hi:[1,0,1]
	v_pk_fma_f32 v[70:71], v[70:71], 0.5, v[74:75] op_sel_hi:[1,0,1]
	v_pk_fma_f32 v[74:75], v[68:69], 0.5, v[80:81] op_sel_hi:[1,0,1]
	v_pk_fma_f32 v[76:77], v[66:67], 0.5, v[78:79] op_sel_hi:[1,0,1]
	v_cvt_pk_bf16_f32 v66, v70, v71
	v_cvt_pk_bf16_f32 v67, v72, v73
	v_mul_f32_e32 v71, v71, v71
	v_cvt_pk_bf16_f32 v68, v76, v77
	v_cvt_pk_bf16_f32 v69, v74, v75
	v_mul_f32_e32 v73, v73, v73
	v_mul_f32_e32 v77, v77, v77
	v_mul_f32_e32 v75, v75, v75
	v_fmac_f32_e32 v71, v70, v70
	v_fmac_f32_e32 v73, v72, v72
	v_fmac_f32_e32 v77, v76, v76
	v_fmac_f32_e32 v75, v74, v74
	global_store_dwordx4 v[88:89], v[66:69], off offset:256
	s_nop 1
	v_add_f32_e32 v66, v71, v73
	v_add_f32_e32 v67, v77, v75
	v_add_f32_e32 v66, v66, v67
	v_add_f32_e32 v66, v83, v66
	v_mov_b32_e32 v67, v66
	s_nop 1
	v_permlane16_swap_b32_e32 v66, v67
	v_add_f32_e32 v66, v66, v67
	v_mov_b32_e32 v67, v66
	s_nop 1
	v_permlane32_swap_b32_e32 v66, v67
	s_and_saveexec_b64 s[4:5], vcc
	v_add_f32_e32 v66, v66, v67
	v_lshl_add_u32 v67, v82, 4, s1
	ds_write_b32 v67, v66
	s_or_b64 exec, exec, s[4:5]
	v_add_u32_e32 v66, 0x80, v1
	v_add_u32_e32 v68, s0, v66
	v_ashrrev_i32_e32 v69, 31, v68
	v_lshlrev_b64 v[68:69], 11, v[68:69]
	v_lshl_add_u64 v[68:69], s[68:69], 0, v[68:69]
	v_lshl_add_u64 v[72:73], v[130:131], 1, v[68:69]
	s_waitcnt vmcnt(15)
	v_mov_b32_e32 v68, v184
	v_mov_b32_e32 v69, v185
	v_mov_b32_e32 v70, v186
	v_mov_b32_e32 v71, v187
	v_lshlrev_b32_e32 v74, 16, v68
	v_and_b32_e32 v75, 0xffff0000, v68
	v_lshlrev_b32_e32 v68, 16, v69
	v_and_b32_e32 v69, 0xffff0000, v69
	v_lshlrev_b32_e32 v76, 16, v70
	v_and_b32_e32 v77, 0xffff0000, v70
	v_lshlrev_b32_e32 v70, 16, v71
	v_and_b32_e32 v71, 0xffff0000, v71
	v_pk_fma_f32 v[68:69], v[64:65], 0.5, v[68:69] op_sel_hi:[1,0,1]
	v_pk_fma_f32 v[74:75], v[62:63], 0.5, v[74:75] op_sel_hi:[1,0,1]
	v_pk_fma_f32 v[70:71], v[60:61], 0.5, v[70:71] op_sel_hi:[1,0,1]
	v_pk_fma_f32 v[76:77], v[58:59], 0.5, v[76:77] op_sel_hi:[1,0,1]
	v_cvt_pk_bf16_f32 v58, v74, v75
	v_cvt_pk_bf16_f32 v59, v68, v69
	v_mul_f32_e32 v67, v75, v75
	v_cvt_pk_bf16_f32 v60, v76, v77
	v_cvt_pk_bf16_f32 v61, v70, v71
	s_waitcnt vmcnt(14)
	v_mov_b32_e32 v62, v188
	v_mov_b32_e32 v63, v189
	v_mov_b32_e32 v64, v190
	v_mov_b32_e32 v65, v191
	v_mul_f32_e32 v69, v69, v69
	v_mul_f32_e32 v75, v77, v77
	v_mul_f32_e32 v71, v71, v71
	v_fmac_f32_e32 v67, v74, v74
	v_fmac_f32_e32 v69, v68, v68
	v_fmac_f32_e32 v75, v76, v76
	v_fmac_f32_e32 v71, v70, v70
	global_store_dwordx4 v[72:73], v[58:61], off
	s_nop 1
	v_add_f32_e32 v58, v67, v69
	v_add_f32_e32 v59, v75, v71
	v_add_f32_e32 v67, v58, v59
	v_lshlrev_b32_e32 v58, 16, v62
	v_and_b32_e32 v59, 0xffff0000, v62
	v_lshlrev_b32_e32 v60, 16, v63
	v_and_b32_e32 v61, 0xffff0000, v63
	v_lshlrev_b32_e32 v62, 16, v64
	v_and_b32_e32 v63, 0xffff0000, v64
	v_lshlrev_b32_e32 v64, 16, v65
	v_and_b32_e32 v65, 0xffff0000, v65
	v_pk_fma_f32 v[56:57], v[56:57], 0.5, v[60:61] op_sel_hi:[1,0,1]
	v_pk_fma_f32 v[54:55], v[54:55], 0.5, v[58:59] op_sel_hi:[1,0,1]
	v_pk_fma_f32 v[58:59], v[52:53], 0.5, v[64:65] op_sel_hi:[1,0,1]
	v_pk_fma_f32 v[60:61], v[50:51], 0.5, v[62:63] op_sel_hi:[1,0,1]
	v_cvt_pk_bf16_f32 v50, v54, v55
	v_cvt_pk_bf16_f32 v51, v56, v57
	v_mul_f32_e32 v55, v55, v55
	v_cvt_pk_bf16_f32 v52, v60, v61
	v_cvt_pk_bf16_f32 v53, v58, v59
	v_mul_f32_e32 v57, v57, v57
	v_mul_f32_e32 v61, v61, v61
	v_mul_f32_e32 v59, v59, v59
	v_fmac_f32_e32 v55, v54, v54
	v_fmac_f32_e32 v57, v56, v56
	v_fmac_f32_e32 v61, v60, v60
	v_fmac_f32_e32 v59, v58, v58
	global_store_dwordx4 v[72:73], v[50:53], off offset:256
	s_nop 1
	v_add_f32_e32 v50, v55, v57
	v_add_f32_e32 v51, v61, v59
	v_add_f32_e32 v50, v50, v51
	v_add_f32_e32 v50, v67, v50
	v_mov_b32_e32 v51, v50
	s_nop 1
	v_permlane16_swap_b32_e32 v50, v51
	v_add_f32_e32 v50, v50, v51
	v_mov_b32_e32 v51, v50
	s_nop 1
	v_permlane32_swap_b32_e32 v50, v51
	s_and_saveexec_b64 s[4:5], vcc
	v_add_f32_e32 v50, v50, v51
	v_lshl_add_u32 v51, v66, 4, s1
	ds_write_b32 v51, v50
	s_or_b64 exec, exec, s[4:5]
	v_add_u32_e32 v50, 0x90, v1
	v_add_u32_e32 v52, s0, v50
	v_ashrrev_i32_e32 v53, 31, v52
	v_lshlrev_b64 v[52:53], 11, v[52:53]
	v_lshl_add_u64 v[52:53], s[68:69], 0, v[52:53]
	v_lshl_add_u64 v[56:57], v[130:131], 1, v[52:53]
	s_waitcnt vmcnt(15)
	v_mov_b32_e32 v52, v192
	v_mov_b32_e32 v53, v193
	v_mov_b32_e32 v54, v194
	v_mov_b32_e32 v55, v195
	v_lshlrev_b32_e32 v58, 16, v52
	v_and_b32_e32 v59, 0xffff0000, v52
	v_lshlrev_b32_e32 v52, 16, v53
	v_and_b32_e32 v53, 0xffff0000, v53
	v_lshlrev_b32_e32 v60, 16, v54
	v_and_b32_e32 v61, 0xffff0000, v54
	v_lshlrev_b32_e32 v54, 16, v55
	v_and_b32_e32 v55, 0xffff0000, v55
	v_pk_fma_f32 v[52:53], v[48:49], 0.5, v[52:53] op_sel_hi:[1,0,1]
	v_pk_fma_f32 v[58:59], v[46:47], 0.5, v[58:59] op_sel_hi:[1,0,1]
	v_pk_fma_f32 v[54:55], v[44:45], 0.5, v[54:55] op_sel_hi:[1,0,1]
	v_pk_fma_f32 v[60:61], v[42:43], 0.5, v[60:61] op_sel_hi:[1,0,1]
	v_cvt_pk_bf16_f32 v42, v58, v59
	v_cvt_pk_bf16_f32 v43, v52, v53
	v_mul_f32_e32 v51, v59, v59
	v_cvt_pk_bf16_f32 v44, v60, v61
	v_cvt_pk_bf16_f32 v45, v54, v55
	s_waitcnt vmcnt(14)
	v_mov_b32_e32 v46, v196
	v_mov_b32_e32 v47, v197
	v_mov_b32_e32 v48, v198
	v_mov_b32_e32 v49, v199
	v_mul_f32_e32 v53, v53, v53
	v_mul_f32_e32 v59, v61, v61
	v_mul_f32_e32 v55, v55, v55
	v_fmac_f32_e32 v51, v58, v58
	v_fmac_f32_e32 v53, v52, v52
	v_fmac_f32_e32 v59, v60, v60
	v_fmac_f32_e32 v55, v54, v54
	global_store_dwordx4 v[56:57], v[42:45], off
	s_nop 1
	v_add_f32_e32 v42, v51, v53
	v_add_f32_e32 v43, v59, v55
	v_add_f32_e32 v51, v42, v43
	v_lshlrev_b32_e32 v42, 16, v46
	v_and_b32_e32 v43, 0xffff0000, v46
	v_lshlrev_b32_e32 v44, 16, v47
	v_and_b32_e32 v45, 0xffff0000, v47
	v_lshlrev_b32_e32 v46, 16, v48
	v_and_b32_e32 v47, 0xffff0000, v48
	v_lshlrev_b32_e32 v48, 16, v49
	v_and_b32_e32 v49, 0xffff0000, v49
	v_pk_fma_f32 v[40:41], v[40:41], 0.5, v[44:45] op_sel_hi:[1,0,1]
	v_pk_fma_f32 v[38:39], v[38:39], 0.5, v[42:43] op_sel_hi:[1,0,1]
	v_pk_fma_f32 v[42:43], v[36:37], 0.5, v[48:49] op_sel_hi:[1,0,1]
	v_pk_fma_f32 v[44:45], v[34:35], 0.5, v[46:47] op_sel_hi:[1,0,1]
	v_cvt_pk_bf16_f32 v34, v38, v39
	v_cvt_pk_bf16_f32 v35, v40, v41
	v_mul_f32_e32 v39, v39, v39
	v_cvt_pk_bf16_f32 v36, v44, v45
	v_cvt_pk_bf16_f32 v37, v42, v43
	v_mul_f32_e32 v41, v41, v41
	v_mul_f32_e32 v45, v45, v45
	v_mul_f32_e32 v43, v43, v43
	v_fmac_f32_e32 v39, v38, v38
	v_fmac_f32_e32 v41, v40, v40
	v_fmac_f32_e32 v45, v44, v44
	v_fmac_f32_e32 v43, v42, v42
	global_store_dwordx4 v[56:57], v[34:37], off offset:256
	s_nop 1
	v_add_f32_e32 v34, v39, v41
	v_add_f32_e32 v35, v45, v43
	v_add_f32_e32 v34, v34, v35
	v_add_f32_e32 v34, v51, v34
	v_mov_b32_e32 v35, v34
	s_nop 1
	v_permlane16_swap_b32_e32 v34, v35
	v_add_f32_e32 v34, v34, v35
	v_mov_b32_e32 v35, v34
	s_nop 1
	v_permlane32_swap_b32_e32 v34, v35
	s_and_saveexec_b64 s[4:5], vcc
	v_add_f32_e32 v34, v34, v35
	v_lshl_add_u32 v35, v50, 4, s1
	ds_write_b32 v35, v34
	s_or_b64 exec, exec, s[4:5]
	v_add_u32_e32 v34, 0xa0, v1
	v_add_u32_e32 v36, s0, v34
	v_ashrrev_i32_e32 v37, 31, v36
	v_lshlrev_b64 v[36:37], 11, v[36:37]
	v_lshl_add_u64 v[36:37], s[68:69], 0, v[36:37]
	v_lshl_add_u64 v[40:41], v[130:131], 1, v[36:37]
	s_waitcnt vmcnt(15)
	v_mov_b32_e32 v36, v200
	v_mov_b32_e32 v37, v201
	v_mov_b32_e32 v38, v202
	v_mov_b32_e32 v39, v203
	v_lshlrev_b32_e32 v42, 16, v36
	v_and_b32_e32 v43, 0xffff0000, v36
	v_lshlrev_b32_e32 v36, 16, v37
	v_and_b32_e32 v37, 0xffff0000, v37
	v_lshlrev_b32_e32 v44, 16, v38
	v_and_b32_e32 v45, 0xffff0000, v38
	v_lshlrev_b32_e32 v38, 16, v39
	v_and_b32_e32 v39, 0xffff0000, v39
	v_pk_fma_f32 v[36:37], v[32:33], 0.5, v[36:37] op_sel_hi:[1,0,1]
	v_pk_fma_f32 v[42:43], v[30:31], 0.5, v[42:43] op_sel_hi:[1,0,1]
	v_pk_fma_f32 v[38:39], v[28:29], 0.5, v[38:39] op_sel_hi:[1,0,1]
	v_pk_fma_f32 v[44:45], v[26:27], 0.5, v[44:45] op_sel_hi:[1,0,1]
	v_cvt_pk_bf16_f32 v26, v42, v43
	v_cvt_pk_bf16_f32 v27, v36, v37
	v_mul_f32_e32 v35, v43, v43
	v_cvt_pk_bf16_f32 v28, v44, v45
	v_cvt_pk_bf16_f32 v29, v38, v39
	s_waitcnt vmcnt(14)
	v_mov_b32_e32 v30, v204
	v_mov_b32_e32 v31, v205
	v_mov_b32_e32 v32, v206
	v_mov_b32_e32 v33, v207
	v_mul_f32_e32 v37, v37, v37
	v_mul_f32_e32 v43, v45, v45
	v_mul_f32_e32 v39, v39, v39
	v_fmac_f32_e32 v35, v42, v42
	v_fmac_f32_e32 v37, v36, v36
	v_fmac_f32_e32 v43, v44, v44
	v_fmac_f32_e32 v39, v38, v38
	global_store_dwordx4 v[40:41], v[26:29], off
	s_nop 1
	v_add_f32_e32 v26, v35, v37
	v_add_f32_e32 v27, v43, v39
	v_add_f32_e32 v35, v26, v27
	v_lshlrev_b32_e32 v26, 16, v30
	v_and_b32_e32 v27, 0xffff0000, v30
	v_lshlrev_b32_e32 v28, 16, v31
	v_and_b32_e32 v29, 0xffff0000, v31
	v_lshlrev_b32_e32 v30, 16, v32
	v_and_b32_e32 v31, 0xffff0000, v32
	v_lshlrev_b32_e32 v32, 16, v33
	v_and_b32_e32 v33, 0xffff0000, v33
	v_pk_fma_f32 v[24:25], v[24:25], 0.5, v[28:29] op_sel_hi:[1,0,1]
	v_pk_fma_f32 v[22:23], v[22:23], 0.5, v[26:27] op_sel_hi:[1,0,1]
	v_pk_fma_f32 v[26:27], v[20:21], 0.5, v[32:33] op_sel_hi:[1,0,1]
	v_pk_fma_f32 v[28:29], v[18:19], 0.5, v[30:31] op_sel_hi:[1,0,1]
	v_cvt_pk_bf16_f32 v18, v22, v23
	v_cvt_pk_bf16_f32 v19, v24, v25
	v_mul_f32_e32 v23, v23, v23
	v_cvt_pk_bf16_f32 v20, v28, v29
	v_cvt_pk_bf16_f32 v21, v26, v27
	v_mul_f32_e32 v25, v25, v25
	v_mul_f32_e32 v29, v29, v29
	v_mul_f32_e32 v27, v27, v27
	v_fmac_f32_e32 v23, v22, v22
	v_fmac_f32_e32 v25, v24, v24
	v_fmac_f32_e32 v29, v28, v28
	v_fmac_f32_e32 v27, v26, v26
	global_store_dwordx4 v[40:41], v[18:21], off offset:256
	s_nop 1
	v_add_f32_e32 v18, v23, v25
	v_add_f32_e32 v19, v29, v27
	v_add_f32_e32 v18, v18, v19
	v_add_f32_e32 v18, v35, v18
	v_mov_b32_e32 v19, v18
	s_nop 1
	v_permlane16_swap_b32_e32 v18, v19
	v_add_f32_e32 v18, v18, v19
	v_mov_b32_e32 v19, v18
	s_nop 1
	v_permlane32_swap_b32_e32 v18, v19
	s_and_saveexec_b64 s[4:5], vcc
	v_add_f32_e32 v18, v18, v19
	v_lshl_add_u32 v19, v34, 4, s1
	ds_write_b32 v19, v18
	s_or_b64 exec, exec, s[4:5]
	v_add_u32_e32 v1, 0xb0, v1
	v_add_u32_e32 v18, s0, v1
	v_ashrrev_i32_e32 v19, 31, v18
	v_lshlrev_b64 v[18:19], 11, v[18:19]
	v_lshl_add_u64 v[18:19], s[68:69], 0, v[18:19]
	v_lshl_add_u64 v[22:23], v[130:131], 1, v[18:19]
	s_waitcnt vmcnt(15)
	v_mov_b32_e32 v18, v208
	v_mov_b32_e32 v19, v209
	v_mov_b32_e32 v20, v210
	v_mov_b32_e32 v21, v211
	v_lshlrev_b32_e32 v24, 16, v18
	v_and_b32_e32 v25, 0xffff0000, v18
	v_lshlrev_b32_e32 v18, 16, v19
	v_and_b32_e32 v19, 0xffff0000, v19
	v_lshlrev_b32_e32 v26, 16, v20
	v_and_b32_e32 v27, 0xffff0000, v20
	v_lshlrev_b32_e32 v20, 16, v21
	v_and_b32_e32 v21, 0xffff0000, v21
	v_pk_fma_f32 v[18:19], v[16:17], 0.5, v[18:19] op_sel_hi:[1,0,1]
	v_pk_fma_f32 v[24:25], v[14:15], 0.5, v[24:25] op_sel_hi:[1,0,1]
	v_pk_fma_f32 v[20:21], v[12:13], 0.5, v[20:21] op_sel_hi:[1,0,1]
	v_pk_fma_f32 v[26:27], v[10:11], 0.5, v[26:27] op_sel_hi:[1,0,1]
	v_cvt_pk_bf16_f32 v10, v24, v25
	v_cvt_pk_bf16_f32 v11, v18, v19
	v_mul_f32_e32 v25, v25, v25
	v_cvt_pk_bf16_f32 v12, v26, v27
	v_cvt_pk_bf16_f32 v13, v20, v21
	s_waitcnt vmcnt(14)
	v_mov_b32_e32 v14, v212
	v_mov_b32_e32 v15, v213
	v_mov_b32_e32 v16, v214
	v_mov_b32_e32 v17, v215
	v_mul_f32_e32 v19, v19, v19
	v_mul_f32_e32 v27, v27, v27
	v_mul_f32_e32 v21, v21, v21
	v_fmac_f32_e32 v25, v24, v24
	v_fmac_f32_e32 v19, v18, v18
	v_fmac_f32_e32 v27, v26, v26
	v_fmac_f32_e32 v21, v20, v20
	global_store_dwordx4 v[22:23], v[10:13], off
	s_nop 1
	v_add_f32_e32 v10, v25, v19
	v_add_f32_e32 v11, v27, v21
	v_add_f32_e32 v18, v10, v11
	v_lshlrev_b32_e32 v10, 16, v14
	v_and_b32_e32 v11, 0xffff0000, v14
	v_lshlrev_b32_e32 v12, 16, v15
	v_and_b32_e32 v13, 0xffff0000, v15
	v_lshlrev_b32_e32 v14, 16, v16
	v_and_b32_e32 v15, 0xffff0000, v16
	v_lshlrev_b32_e32 v16, 16, v17
	v_and_b32_e32 v17, 0xffff0000, v17
	v_pk_fma_f32 v[8:9], v[8:9], 0.5, v[12:13] op_sel_hi:[1,0,1]
	v_pk_fma_f32 v[6:7], v[6:7], 0.5, v[10:11] op_sel_hi:[1,0,1]
	v_pk_fma_f32 v[10:11], v[4:5], 0.5, v[16:17] op_sel_hi:[1,0,1]
	v_pk_fma_f32 v[12:13], v[2:3], 0.5, v[14:15] op_sel_hi:[1,0,1]
	v_cvt_pk_bf16_f32 v2, v6, v7
	v_cvt_pk_bf16_f32 v3, v8, v9
	v_mul_f32_e32 v7, v7, v7
	v_cvt_pk_bf16_f32 v4, v12, v13
	v_cvt_pk_bf16_f32 v5, v10, v11
	v_mul_f32_e32 v9, v9, v9
	v_mul_f32_e32 v13, v13, v13
	v_mul_f32_e32 v11, v11, v11
	v_fmac_f32_e32 v7, v6, v6
	v_fmac_f32_e32 v9, v8, v8
	v_fmac_f32_e32 v13, v12, v12
	v_fmac_f32_e32 v11, v10, v10
	global_store_dwordx4 v[22:23], v[2:5], off offset:256
	s_nop 1
	v_add_f32_e32 v2, v7, v9
	v_add_f32_e32 v3, v13, v11
	v_add_f32_e32 v2, v2, v3
	v_add_f32_e32 v2, v18, v2
	v_mov_b32_e32 v3, v2
	s_nop 1
	v_permlane16_swap_b32_e32 v2, v3
	v_add_f32_e32 v2, v2, v3
	v_mov_b32_e32 v3, v2
	s_nop 1
	v_permlane32_swap_b32_e32 v2, v3
	s_and_saveexec_b64 s[4:5], vcc
	v_add_f32_e32 v2, v2, v3
	v_lshl_add_u32 v1, v1, 4, s1
	ds_write_b32 v1, v2
	s_or_b64 exec, exec, s[4:5]
	s_waitcnt lgkmcnt(0)
	s_barrier
	s_andn2_b32 s17, s17, 63
	v_or_b32_e32 v1, s17, v252
	s_movk_i32 s1, 0x100
	v_cmp_gt_i32_e32 vcc, s1, v1
	s_and_saveexec_b64 s[4:5], vcc
	s_cbranch_execz .LBB0_1919
	v_lshl_add_u32 v2, v1, 4, 0
	ds_read_b128 v[2:5], v2
	v_add_u32_e32 v6, s0, v1
	v_ashrrev_i32_e32 v7, 31, v6
	s_ashr_i32 s17, s16, 31
	s_waitcnt lgkmcnt(0)
	v_mov_b32_e32 v8, v3
	v_mov_b32_e32 v9, v4
	v_mov_b32_e32 v3, v5
	v_pk_add_f32 v[2:3], v[8:9], v[2:3]
	s_nop 0
	v_add_f32_e32 v1, v2, v3
	v_lshl_add_u64 v[2:3], v[6:7], 4, s[10:11]
	v_lshl_add_u64 v[2:3], s[16:17], 2, v[2:3]
	global_store_dword v[2:3], v1, off

.Ldf_fast:
	s_add_i32 s0, s43, 2
	s_waitcnt vmcnt(4) lgkmcnt(0)
	s_barrier
	s_add_i32 s20, s58, s43
	s_cmp_lt_i32 s20, s89
	s_waitcnt lgkmcnt(2)
	v_mfma_f32_32x32x16_bf16 v[2:17], v[158:161], v[182:185], v[2:17]
	v_subrev_u32_e32 v198, 64, v197
	s_cselect_b64 s[26:27], -1, 0
	v_cvt_f32_i32_e32 v98, v198
	v_cndmask_b32_e64 v188, -v193, v193, s[26:27]
	v_add_u32_e32 v199, s15, v240
	ds_read_b64_tr_b16 v[200:201], v199 offset:51200
	ds_read_b64_tr_b16 v[202:203], v199 offset:51712
	v_fma_f32 v186, v188, v98, -v233
	v_exp_f32_e32 v66, v66
	v_exp_f32_e32 v67, v67
	v_fma_f32 v114, 0, v188, v186
	v_fmamk_f32 v98, v188, 0x42000000, v186
	v_add_f32_e32 v115, v188, v186
	s_waitcnt lgkmcnt(2)
	v_mfma_f32_32x32x16_bf16 v[2:17], v[154:157], v[178:181], v[2:17]
	ds_read_b64_tr_b16 v[182:183], v199 offset:52224
	ds_read_b64_tr_b16 v[184:185], v199 offset:52736
	v_fmamk_f32 v99, v188, 0x42040000, v186
	v_fma_f32 v116, 2.0, v188, v186
	v_exp_f32_e32 v68, v68
	v_exp_f32_e32 v69, v69
	s_waitcnt lgkmcnt(2)
	v_mfma_f32_32x32x16_bf16 v[2:17], v[150:153], v[200:203], v[2:17]
	ds_read_b64_tr_b16 v[178:179], v199 offset:53248
	ds_read_b64_tr_b16 v[180:181], v199 offset:53760
	v_add_f32_e32 v187, v187, v66
	v_fmamk_f32 v100, v188, 0x42080000, v186
	v_fmamk_f32 v117, v188, 0x40400000, v186
	v_cvt_pk_bf16_f32 v174, v66, v67
	v_add_f32_e32 v187, v67, v187
	v_exp_f32_e32 v70, v70
	s_waitcnt lgkmcnt(2)
	v_mfma_f32_32x32x16_bf16 v[2:17], v[146:149], v[182:185], v[2:17]
	ds_read_b64_tr_b16 v[200:201], v199 offset:54272
	ds_read_b64_tr_b16 v[202:203], v199 offset:54784
	v_fma_f32 v182, v188, s16, v186
	v_fma_f32 v183, v188, s17, v186
	v_fmamk_f32 v118, v188, 0x41000000, v186
	v_exp_f32_e32 v71, v71
	v_add_f32_e32 v187, v187, v68
	v_mov_b32_e32 v101, v182
	v_mov_b32_e32 v102, v183
	s_waitcnt lgkmcnt(2)
	v_mfma_f32_32x32x16_bf16 v[18:33], v[158:161], v[178:181], v[18:33]
	ds_read_b64_tr_b16 v[182:183], v199 offset:55296
	ds_read_b64_tr_b16 v[184:185], v199 offset:55808
	v_fmamk_f32 v119, v188, 0x41100000, v186
	v_fmamk_f32 v103, v188, 0x42240000, v186
	v_cvt_pk_bf16_f32 v175, v68, v69
	v_add_f32_e32 v187, v187, v69
	v_exp_f32_e32 v72, v72
	s_waitcnt lgkmcnt(2)
	v_mfma_f32_32x32x16_bf16 v[18:33], v[154:157], v[200:203], v[18:33]
	ds_read_b64_tr_b16 v[178:179], v199 offset:56320
	ds_read_b64_tr_b16 v[180:181], v199 offset:56832
	v_fmamk_f32 v120, v188, 0x41200000, v186
	v_fmamk_f32 v104, v188, 0x42280000, v186
	v_exp_f32_e32 v73, v73
	v_add_f32_e32 v187, v187, v70
	v_cvt_pk_bf16_f32 v176, v70, v71
	s_waitcnt lgkmcnt(2)
	v_mfma_f32_32x32x16_bf16 v[18:33], v[150:153], v[182:185], v[18:33]
	ds_read_b64_tr_b16 v[200:201], v199 offset:57344
	ds_read_b64_tr_b16 v[202:203], v199 offset:57856
	v_fmamk_f32 v121, v188, 0x41300000, v186
	v_fmamk_f32 v105, v188, 0x422c0000, v186
	v_add_f32_e32 v182, v187, v71
	v_exp_f32_e32 v74, v74
	v_exp_f32_e32 v75, v75
	s_waitcnt lgkmcnt(2)
	v_mfma_f32_32x32x16_bf16 v[18:33], v[146:149], v[178:181], v[18:33]
	ds_read_b64_tr_b16 v[204:205], v199 offset:58368
	ds_read_b64_tr_b16 v[206:207], v199 offset:58880
	v_add_f32_e32 v178, v182, v72
	v_fmamk_f32 v106, v188, 0x42400000, v186
	v_fma_f32 v122, v188, s48, v186
	v_fma_f32 v123, v188, s49, v186
	v_cvt_pk_bf16_f32 v177, v72, v73
	v_add_f32_e32 v187, v73, v178
	s_waitcnt lgkmcnt(2)
	v_mfma_f32_32x32x16_bf16 v[34:49], v[158:161], v[200:203], v[34:49]
	ds_read_b64_tr_b16 v[182:183], v199 offset:59392
	ds_read_b64_tr_b16 v[184:185], v199 offset:59904
	v_fmamk_f32 v107, v188, 0x42440000, v186
	v_fmamk_f32 v124, v188, 0x41900000, v186
	v_exp_f32_e32 v76, v76
	v_exp_f32_e32 v77, v77
	s_waitcnt lgkmcnt(2)
	v_mfma_f32_32x32x16_bf16 v[34:49], v[154:157], v[204:207], v[34:49]
	ds_read_b64_tr_b16 v[178:179], v199 offset:60416
	ds_read_b64_tr_b16 v[180:181], v199 offset:60928
	v_add_f32_e32 v187, v187, v74
	v_fmamk_f32 v108, v188, 0x42480000, v186
	v_fmamk_f32 v125, v188, 0x41980000, v186
	v_cvt_pk_bf16_f32 v170, v74, v75
	v_add_f32_e32 v200, v75, v187
	v_exp_f32_e32 v78, v78
	s_add_u32 s6, s76, s62
	s_addc_u32 s7, s77, s63
	s_add_u32 s26, s6, 0x30000
	s_addc_u32 s27, s7, 0
	s_add_u32 s6, s78, s62
	s_addc_u32 s7, s79, s63
	s_add_u32 s70, s6, 0x30000
	s_addc_u32 s71, s7, 0
	s_add_i32 s6, 0, s59
	s_add_i32 s7, s81, s90
	s_add_u32 s84, s26, 0x8000
	s_addc_u32 s85, s27, 0
	s_add_i32 s15, s6, 0x2000
	s_mov_b32 m0, s6
	s_nop 0
	global_load_lds_dwordx4 v191, s[26:27]
	s_mov_b32 m0, s15
	s_nop 0
	global_load_lds_dwordx4 v191, s[84:85]
	s_mov_b32 m0, s21
	s_add_u32 s26, s70, 0x80
	s_addc_u32 s27, s71, 0
	s_add_i32 s6, s7, 0x2000
	s_mov_b32 m0, s7
	s_nop 0
	global_load_lds_dwordx4 v192, s[70:71]
	s_mov_b32 m0, s6
	s_nop 0
	global_load_lds_dwordx4 v192, s[26:27]
	s_mov_b32 m0, s15
	s_waitcnt lgkmcnt(2)
	v_mfma_f32_32x32x16_bf16 v[34:49], v[150:153], v[182:185], v[34:49]
	ds_read_b64_tr_b16 v[202:203], v199 offset:61440
	ds_read_b64_tr_b16 v[204:205], v199 offset:61952
	v_mov_b32_e32 v189, v188
	v_mov_b32_e32 v187, v186
	v_fma_f32 v182, v188, s56, v186
	v_fma_f32 v183, v189, s57, v187
	v_fmamk_f32 v126, v188, 0x41c00000, v186
	v_exp_f32_e32 v79, v79
	v_add_f32_e32 v187, v200, v76
	v_mov_b32_e32 v109, v182
	v_mov_b32_e32 v110, v183
	s_waitcnt lgkmcnt(2)
	v_mfma_f32_32x32x16_bf16 v[34:49], v[146:149], v[178:181], v[34:49]
	ds_read_b64_tr_b16 v[182:183], v199 offset:62464
	ds_read_b64_tr_b16 v[184:185], v199 offset:62976
	v_fmamk_f32 v127, v188, 0x41c80000, v186
	v_fmamk_f32 v111, v188, 0x42640000, v186
	v_cvt_pk_bf16_f32 v171, v76, v77
	v_add_f32_e32 v187, v187, v77
	v_exp_f32_e32 v80, v80
	s_waitcnt lgkmcnt(2)
	v_mfma_f32_32x32x16_bf16 v[50:65], v[158:161], v[202:205], v[50:65]
	ds_read_b64_tr_b16 v[178:179], v199 offset:63488
	ds_read_b64_tr_b16 v[180:181], v199 offset:64000
	v_fmamk_f32 v128, v188, 0x41d00000, v186
	v_fmamk_f32 v112, v188, 0x42680000, v186
	v_exp_f32_e32 v81, v81
	v_add_f32_e32 v187, v187, v78
	v_cvt_pk_bf16_f32 v172, v78, v79
	s_waitcnt lgkmcnt(2)
	v_mfma_f32_32x32x16_bf16 v[50:65], v[154:157], v[182:185], v[50:65]
	ds_read_b64_tr_b16 v[200:201], v199 offset:64512
	ds_read_b64_tr_b16 v[202:203], v199 offset:65024
	v_fmamk_f32 v129, v188, 0x41d80000, v186
	v_fmac_f32_e32 v186, 0x426c0000, v188
	v_exp_f32_e32 v82, v82
	v_exp_f32_e32 v83, v83
	v_mov_b32_e32 v113, v186
	v_add_f32_e32 v186, v187, v79
	s_waitcnt lgkmcnt(2)
	v_mfma_f32_32x32x16_bf16 v[50:65], v[150:153], v[178:181], v[50:65]
	ds_read_b128 v[182:185], v190 offset:16384
	v_add_f32_e32 v178, v186, v80
	v_cvt_pk_bf16_f32 v173, v80, v81
	v_add_f32_e32 v186, v81, v178
	v_exp_f32_e32 v84, v84
	v_exp_f32_e32 v85, v85
	s_waitcnt lgkmcnt(1)
	v_mfma_f32_32x32x16_bf16 v[50:65], v[146:149], v[200:203], v[50:65]
	ds_read_b128 v[178:181], v190 offset:24576
	v_add_f32_e32 v186, v186, v82
	v_cvt_pk_bf16_f32 v166, v82, v83
	v_add_f32_e32 v199, v83, v186
	v_exp_f32_e32 v86, v86
	v_exp_f32_e32 v87, v87
	s_waitcnt lgkmcnt(1)
	v_mfma_f32_32x32x16_bf16 v[114:129], v[182:185], v[130:133], v[114:129]
	ds_read_b128 v[186:189], v194 offset:16384
	v_add_f32_e32 v182, v199, v84
	v_cvt_pk_bf16_f32 v167, v84, v85
	v_add_f32_e32 v199, v85, v182
	v_exp_f32_e32 v88, v88
	v_exp_f32_e32 v89, v89
	s_waitcnt lgkmcnt(1)
	v_mfma_f32_32x32x16_bf16 v[98:113], v[178:181], v[130:133], v[98:113]
	ds_read_b128 v[182:185], v194 offset:24576
	v_add_f32_e32 v178, v199, v86
	v_cvt_pk_bf16_f32 v168, v86, v87
	v_add_f32_e32 v199, v87, v178
	v_exp_f32_e32 v90, v90
	v_exp_f32_e32 v91, v91
	s_waitcnt lgkmcnt(1)
	v_mfma_f32_32x32x16_bf16 v[114:129], v[186:189], v[134:137], v[114:129]
	ds_read_b128 v[178:181], v195 offset:16384
	v_add_f32_e32 v186, v199, v88
	v_cvt_pk_bf16_f32 v169, v88, v89
	v_add_f32_e32 v199, v89, v186
	v_exp_f32_e32 v92, v92
	v_exp_f32_e32 v93, v93
	s_waitcnt lgkmcnt(1)
	v_mfma_f32_32x32x16_bf16 v[98:113], v[182:185], v[134:137], v[98:113]
	ds_read_b128 v[186:189], v195 offset:24576
	v_add_f32_e32 v182, v199, v90
	v_cvt_pk_bf16_f32 v162, v90, v91
	v_add_f32_e32 v182, v91, v182
	v_exp_f32_e32 v94, v94
	v_exp_f32_e32 v95, v95
	s_waitcnt lgkmcnt(1)
	v_mfma_f32_32x32x16_bf16 v[114:129], v[178:181], v[138:141], v[114:129]
	ds_read_b128 v[200:203], v196 offset:16384
	v_add_f32_e32 v178, v182, v92
	v_cvt_pk_bf16_f32 v163, v92, v93
	v_add_f32_e32 v178, v93, v178
	v_exp_f32_e32 v96, v96
	v_exp_f32_e32 v97, v97
	s_waitcnt lgkmcnt(1)
	v_mfma_f32_32x32x16_bf16 v[98:113], v[186:189], v[138:141], v[98:113]
	ds_read_b128 v[204:207], v196 offset:24576
	v_add_f32_e32 v165, v178, v94
	v_add_f32_e32 v165, v95, v165
	v_add_f32_e32 v178, v96, v165
	v_cvt_pk_bf16_f32 v164, v94, v95
	v_cvt_pk_bf16_f32 v165, v96, v97
	v_add_f32_e32 v187, v97, v178
	s_waitcnt lgkmcnt(1)
	v_mfma_f32_32x32x16_bf16 v[114:129], v[200:203], v[142:145], v[114:129]
	v_add_u32_e32 v199, s80, v240
	ds_read_b64_tr_b16 v[182:183], v199 offset:49152
	ds_read_b64_tr_b16 v[184:185], v199 offset:49664
	s_waitcnt lgkmcnt(2)
	v_mfma_f32_32x32x16_bf16 v[98:113], v[204:207], v[142:145], v[98:113]
	ds_read_b64_tr_b16 v[178:179], v199 offset:50176
	ds_read_b64_tr_b16 v[180:181], v199 offset:50688
	s_waitcnt vmcnt(4) lgkmcnt(0)
	s_barrier
	s_add_i32 s6, s81, 0x4000
	s_cmp_lg_u32 s81, 0x10000
	s_cselect_b32 s21, s6, 0
	s_add_i32 s20, s20, 1
	s_cmp_lt_i32 s20, s89
	s_waitcnt lgkmcnt(2)
	v_mfma_f32_32x32x16_bf16 v[2:17], v[174:177], v[182:185], v[2:17]
	s_cselect_b64 s[6:7], -1, 0
	v_cvt_f32_i32_e32 v66, v197
	v_cndmask_b32_e64 v188, -v193, v193, s[6:7]
	ds_read_b64_tr_b16 v[200:201], v199 offset:51200
	ds_read_b64_tr_b16 v[202:203], v199 offset:51712
	v_fma_f32 v186, v188, v66, -v233
	v_exp_f32_e32 v114, v114
	v_exp_f32_e32 v115, v115
	v_fma_f32 v66, 0, v188, v186
	v_fmamk_f32 v82, v188, 0x42000000, v186
	v_add_f32_e32 v67, v188, v186
	s_waitcnt lgkmcnt(2)
	v_mfma_f32_32x32x16_bf16 v[2:17], v[170:173], v[178:181], v[2:17]
	ds_read_b64_tr_b16 v[182:183], v199 offset:52224
	ds_read_b64_tr_b16 v[184:185], v199 offset:52736
	v_fmamk_f32 v83, v188, 0x42040000, v186
	v_fma_f32 v68, 2.0, v188, v186
	v_exp_f32_e32 v116, v116
	v_exp_f32_e32 v117, v117
	s_waitcnt lgkmcnt(2)
	v_mfma_f32_32x32x16_bf16 v[2:17], v[166:169], v[200:203], v[2:17]
	ds_read_b64_tr_b16 v[178:179], v199 offset:53248
	ds_read_b64_tr_b16 v[180:181], v199 offset:53760
	v_add_f32_e32 v187, v187, v114
	v_fmamk_f32 v84, v188, 0x42080000, v186
	v_fmamk_f32 v69, v188, 0x40400000, v186
	v_cvt_pk_bf16_f32 v158, v114, v115
	v_add_f32_e32 v187, v115, v187
	v_exp_f32_e32 v118, v118
	s_waitcnt lgkmcnt(2)
	v_mfma_f32_32x32x16_bf16 v[2:17], v[162:165], v[182:185], v[2:17]
	ds_read_b64_tr_b16 v[200:201], v199 offset:54272
	ds_read_b64_tr_b16 v[202:203], v199 offset:54784
	v_fma_f32 v182, v188, s16, v186
	v_fma_f32 v183, v188, s17, v186
	v_fmamk_f32 v70, v188, 0x41000000, v186
	v_exp_f32_e32 v119, v119
	v_add_f32_e32 v187, v187, v116
	v_mov_b32_e32 v85, v182
	v_mov_b32_e32 v86, v183
	s_waitcnt lgkmcnt(2)
	v_mfma_f32_32x32x16_bf16 v[18:33], v[174:177], v[178:181], v[18:33]
	ds_read_b64_tr_b16 v[182:183], v199 offset:55296
	ds_read_b64_tr_b16 v[184:185], v199 offset:55808
	v_fmamk_f32 v71, v188, 0x41100000, v186
	v_fmamk_f32 v87, v188, 0x42240000, v186
	v_cvt_pk_bf16_f32 v159, v116, v117
	v_add_f32_e32 v187, v187, v117
	v_exp_f32_e32 v120, v120
	s_waitcnt lgkmcnt(2)
	v_mfma_f32_32x32x16_bf16 v[18:33], v[170:173], v[200:203], v[18:33]
	ds_read_b64_tr_b16 v[178:179], v199 offset:56320
	ds_read_b64_tr_b16 v[180:181], v199 offset:56832
	v_fmamk_f32 v72, v188, 0x41200000, v186
	v_fmamk_f32 v88, v188, 0x42280000, v186
	v_exp_f32_e32 v121, v121
	v_add_f32_e32 v187, v187, v118
	v_cvt_pk_bf16_f32 v160, v118, v119
	s_waitcnt lgkmcnt(2)
	v_mfma_f32_32x32x16_bf16 v[18:33], v[166:169], v[182:185], v[18:33]
	ds_read_b64_tr_b16 v[200:201], v199 offset:57344
	ds_read_b64_tr_b16 v[202:203], v199 offset:57856
	v_fmamk_f32 v73, v188, 0x41300000, v186
	v_fmamk_f32 v89, v188, 0x422c0000, v186
	v_add_f32_e32 v182, v187, v119
	v_exp_f32_e32 v122, v122
	v_exp_f32_e32 v123, v123
	s_waitcnt lgkmcnt(2)
	v_mfma_f32_32x32x16_bf16 v[18:33], v[162:165], v[178:181], v[18:33]
	ds_read_b64_tr_b16 v[204:205], v199 offset:58368
	ds_read_b64_tr_b16 v[206:207], v199 offset:58880
	v_add_f32_e32 v178, v182, v120
	v_fmamk_f32 v90, v188, 0x42400000, v186
	v_fma_f32 v74, v188, s48, v186
	v_fma_f32 v75, v188, s49, v186
	v_cvt_pk_bf16_f32 v161, v120, v121
	v_add_f32_e32 v187, v121, v178
	s_waitcnt lgkmcnt(2)
	v_mfma_f32_32x32x16_bf16 v[34:49], v[174:177], v[200:203], v[34:49]
	ds_read_b64_tr_b16 v[182:183], v199 offset:59392
	ds_read_b64_tr_b16 v[184:185], v199 offset:59904
	v_fmamk_f32 v91, v188, 0x42440000, v186
	v_fmamk_f32 v76, v188, 0x41900000, v186
	v_exp_f32_e32 v124, v124
	v_exp_f32_e32 v125, v125
	s_waitcnt lgkmcnt(2)
	v_mfma_f32_32x32x16_bf16 v[34:49], v[170:173], v[204:207], v[34:49]
	ds_read_b64_tr_b16 v[178:179], v199 offset:60416
	ds_read_b64_tr_b16 v[180:181], v199 offset:60928
	v_add_f32_e32 v187, v187, v122
	v_fmamk_f32 v92, v188, 0x42480000, v186
	v_fmamk_f32 v77, v188, 0x41980000, v186
	v_cvt_pk_bf16_f32 v154, v122, v123
	v_add_f32_e32 v198, v123, v187
	v_exp_f32_e32 v126, v126
	s_add_u32 s6, s76, s62
	s_addc_u32 s7, s77, s63
	s_add_u32 s6, s6, 0x40000
	s_addc_u32 s7, s7, 0
	s_add_u32 s15, s78, s62
	s_addc_u32 s20, s79, s63
	s_add_u32 s24, s15, 0x40000
	s_addc_u32 s25, s20, 0
	s_add_i32 s15, 0x4000, s59
	s_add_i32 s20, s21, s90
	s_add_u32 s26, s6, 0x8000
	s_addc_u32 s27, s7, 0
	s_add_i32 s68, s15, 0x2000
	s_mov_b32 m0, s15
	s_nop 0
	global_load_lds_dwordx4 v191, s[6:7]
	s_mov_b32 m0, s68
	s_nop 0
	global_load_lds_dwordx4 v191, s[26:27]
	s_mov_b32 m0, s69
	s_add_u32 s6, s24, 0x80
	s_addc_u32 s7, s25, 0
	s_add_i32 s15, s20, 0x2000
	s_mov_b32 m0, s20
	s_nop 0
	global_load_lds_dwordx4 v192, s[24:25]
	s_mov_b32 m0, s15
	s_nop 0
	global_load_lds_dwordx4 v192, s[6:7]
	s_mov_b32 m0, s26
	s_waitcnt lgkmcnt(2)
	v_mfma_f32_32x32x16_bf16 v[34:49], v[166:169], v[182:185], v[34:49]
	ds_read_b64_tr_b16 v[200:201], v199 offset:61440
	ds_read_b64_tr_b16 v[202:203], v199 offset:61952
	v_mov_b32_e32 v189, v188
	v_mov_b32_e32 v187, v186
	s_add_i32 s6, s80, 0x4000
	s_cmp_lg_u32 s80, 0x10000
	v_pk_fma_f32 v[182:183], v[188:189], s[56:57], v[186:187]
	s_cselect_b32 s15, s6, 0
	v_fmamk_f32 v78, v188, 0x41c00000, v186
	v_exp_f32_e32 v127, v127
	v_add_f32_e32 v187, v198, v124
	v_mov_b32_e32 v93, v182
	v_mov_b32_e32 v94, v183
	s_waitcnt lgkmcnt(2)
	v_mfma_f32_32x32x16_bf16 v[34:49], v[162:165], v[178:181], v[34:49]
	ds_read_b64_tr_b16 v[182:183], v199 offset:62464
	ds_read_b64_tr_b16 v[184:185], v199 offset:62976
	v_fmamk_f32 v79, v188, 0x41c80000, v186
	v_fmamk_f32 v95, v188, 0x42640000, v186
	v_cvt_pk_bf16_f32 v155, v124, v125
	v_add_f32_e32 v187, v187, v125
	v_exp_f32_e32 v128, v128
	s_waitcnt lgkmcnt(2)
	v_mfma_f32_32x32x16_bf16 v[50:65], v[174:177], v[200:203], v[50:65]
	ds_read_b64_tr_b16 v[178:179], v199 offset:63488
	ds_read_b64_tr_b16 v[180:181], v199 offset:64000
	v_fmamk_f32 v80, v188, 0x41d00000, v186
	v_fmamk_f32 v96, v188, 0x42680000, v186
	v_exp_f32_e32 v129, v129
	v_add_f32_e32 v187, v187, v126
	v_cvt_pk_bf16_f32 v156, v126, v127
	s_waitcnt lgkmcnt(2)
	v_mfma_f32_32x32x16_bf16 v[50:65], v[170:173], v[182:185], v[50:65]
	ds_read_b64_tr_b16 v[200:201], v199 offset:64512
	ds_read_b64_tr_b16 v[202:203], v199 offset:65024
	v_fmamk_f32 v81, v188, 0x41d80000, v186
	v_fmac_f32_e32 v186, 0x426c0000, v188
	v_exp_f32_e32 v98, v98
	v_exp_f32_e32 v99, v99
	v_mov_b32_e32 v97, v186
	v_add_f32_e32 v186, v187, v127
	s_waitcnt lgkmcnt(2)
	v_mfma_f32_32x32x16_bf16 v[50:65], v[166:169], v[178:181], v[50:65]
	ds_read_b128 v[182:185], v190 offset:32768
	v_add_f32_e32 v178, v186, v128
	v_cvt_pk_bf16_f32 v157, v128, v129
	v_add_f32_e32 v186, v129, v178
	v_exp_f32_e32 v100, v100
	v_exp_f32_e32 v101, v101
	s_waitcnt lgkmcnt(1)
	v_mfma_f32_32x32x16_bf16 v[50:65], v[162:165], v[200:203], v[50:65]
	ds_read_b128 v[178:181], v190 offset:40960
	v_add_f32_e32 v186, v186, v98
	v_cvt_pk_bf16_f32 v150, v98, v99
	v_add_f32_e32 v198, v99, v186
	v_exp_f32_e32 v102, v102
	v_exp_f32_e32 v103, v103
	s_waitcnt lgkmcnt(1)
	v_mfma_f32_32x32x16_bf16 v[66:81], v[182:185], v[130:133], v[66:81]
	ds_read_b128 v[186:189], v194 offset:32768
	v_add_f32_e32 v182, v198, v100
	v_cvt_pk_bf16_f32 v151, v100, v101
	v_add_f32_e32 v198, v101, v182
	v_exp_f32_e32 v104, v104
	v_exp_f32_e32 v105, v105
	s_waitcnt lgkmcnt(1)
	v_mfma_f32_32x32x16_bf16 v[82:97], v[178:181], v[130:133], v[82:97]
	ds_read_b128 v[182:185], v194 offset:40960
	v_add_f32_e32 v178, v198, v102
	v_cvt_pk_bf16_f32 v152, v102, v103
	v_add_f32_e32 v198, v103, v178
	v_exp_f32_e32 v106, v106
	v_exp_f32_e32 v107, v107
	s_waitcnt lgkmcnt(1)
	v_mfma_f32_32x32x16_bf16 v[66:81], v[186:189], v[134:137], v[66:81]
	ds_read_b128 v[178:181], v195 offset:32768
	v_add_f32_e32 v186, v198, v104
	v_cvt_pk_bf16_f32 v153, v104, v105
	v_add_f32_e32 v198, v105, v186
	v_exp_f32_e32 v108, v108
	v_exp_f32_e32 v109, v109
	s_waitcnt lgkmcnt(1)
	v_mfma_f32_32x32x16_bf16 v[82:97], v[182:185], v[134:137], v[82:97]
	ds_read_b128 v[186:189], v195 offset:40960
	v_add_f32_e32 v182, v198, v106
	v_cvt_pk_bf16_f32 v146, v106, v107
	v_add_f32_e32 v182, v107, v182
	v_exp_f32_e32 v110, v110
	v_exp_f32_e32 v111, v111
	s_waitcnt lgkmcnt(1)
	v_mfma_f32_32x32x16_bf16 v[66:81], v[178:181], v[138:141], v[66:81]
	ds_read_b128 v[198:201], v196 offset:32768
	v_add_f32_e32 v178, v182, v108
	v_cvt_pk_bf16_f32 v147, v108, v109
	v_add_f32_e32 v178, v109, v178
	v_exp_f32_e32 v112, v112
	v_exp_f32_e32 v113, v113
	s_waitcnt lgkmcnt(1)
	v_mfma_f32_32x32x16_bf16 v[82:97], v[186:189], v[138:141], v[82:97]
	ds_read_b128 v[202:205], v196 offset:40960
	v_add_f32_e32 v149, v178, v110
	v_add_f32_e32 v149, v111, v149
	v_add_f32_e32 v178, v112, v149
	v_cvt_pk_bf16_f32 v148, v110, v111
	v_cvt_pk_bf16_f32 v149, v112, v113
	v_add_f32_e32 v187, v113, v178
	s_waitcnt lgkmcnt(1)
	v_mfma_f32_32x32x16_bf16 v[66:81], v[198:201], v[142:145], v[66:81]
	v_add_u32_e32 v180, s15, v240
	ds_read_b64_tr_b16 v[182:183], v180 offset:49152
	ds_read_b64_tr_b16 v[184:185], v180 offset:49664
	s_waitcnt lgkmcnt(2)
	v_mfma_f32_32x32x16_bf16 v[82:97], v[202:205], v[142:145], v[82:97]
	ds_read_b64_tr_b16 v[178:179], v180 offset:50176
	ds_read_b64_tr_b16 v[180:181], v180 offset:50688
	s_add_i32 s6, s15, 0x4000
	s_cmp_lg_u32 s15, 0x10000
	s_cselect_b32 s80, s6, 0
	s_add_i32 s6, s21, 0x4000
	s_cmp_lg_u32 s21, 0x10000
	s_cselect_b32 s81, s6, 0
	s_add_u32 s78, s78, 0x20000
	s_addc_u32 s79, s79, 0
	s_add_u32 s76, s76, 0x20000
	s_addc_u32 s77, s77, 0
	v_add_u32_e32 v197, 0x80, v197
	s_mov_b32 s43, s0
	s_add_i32 s0, s43, 2
	s_waitcnt vmcnt(4) lgkmcnt(0)
	s_barrier
	s_add_i32 s20, s58, s43
	s_cmp_lt_i32 s20, s89
	s_waitcnt lgkmcnt(2)
	v_mfma_f32_32x32x16_bf16 v[2:17], v[158:161], v[182:185], v[2:17]
	v_subrev_u32_e32 v198, 64, v197
	s_cselect_b64 s[26:27], -1, 0
	v_cvt_f32_i32_e32 v98, v198
	v_cndmask_b32_e64 v188, -v193, v193, s[26:27]
	v_add_u32_e32 v199, s15, v240
	ds_read_b64_tr_b16 v[200:201], v199 offset:51200
	ds_read_b64_tr_b16 v[202:203], v199 offset:51712
	v_fma_f32 v186, v188, v98, -v233
	v_exp_f32_e32 v66, v66
	v_exp_f32_e32 v67, v67
	v_fma_f32 v114, 0, v188, v186
	v_fmamk_f32 v98, v188, 0x42000000, v186
	v_add_f32_e32 v115, v188, v186
	s_waitcnt lgkmcnt(2)
	v_mfma_f32_32x32x16_bf16 v[2:17], v[154:157], v[178:181], v[2:17]
	ds_read_b64_tr_b16 v[182:183], v199 offset:52224
	ds_read_b64_tr_b16 v[184:185], v199 offset:52736
	v_fmamk_f32 v99, v188, 0x42040000, v186
	v_fma_f32 v116, 2.0, v188, v186
	v_exp_f32_e32 v68, v68
	v_exp_f32_e32 v69, v69
	s_waitcnt lgkmcnt(2)
	v_mfma_f32_32x32x16_bf16 v[2:17], v[150:153], v[200:203], v[2:17]
	ds_read_b64_tr_b16 v[178:179], v199 offset:53248
	ds_read_b64_tr_b16 v[180:181], v199 offset:53760
	v_add_f32_e32 v187, v187, v66
	v_fmamk_f32 v100, v188, 0x42080000, v186
	v_fmamk_f32 v117, v188, 0x40400000, v186
	v_cvt_pk_bf16_f32 v174, v66, v67
	v_add_f32_e32 v187, v67, v187
	v_exp_f32_e32 v70, v70
	s_waitcnt lgkmcnt(2)
	v_mfma_f32_32x32x16_bf16 v[2:17], v[146:149], v[182:185], v[2:17]
	ds_read_b64_tr_b16 v[200:201], v199 offset:54272
	ds_read_b64_tr_b16 v[202:203], v199 offset:54784
	v_fma_f32 v182, v188, s16, v186
	v_fma_f32 v183, v188, s17, v186
	v_fmamk_f32 v118, v188, 0x41000000, v186
	v_exp_f32_e32 v71, v71
	v_add_f32_e32 v187, v187, v68
	v_mov_b32_e32 v101, v182
	v_mov_b32_e32 v102, v183
	s_waitcnt lgkmcnt(2)
	v_mfma_f32_32x32x16_bf16 v[18:33], v[158:161], v[178:181], v[18:33]
	ds_read_b64_tr_b16 v[182:183], v199 offset:55296
	ds_read_b64_tr_b16 v[184:185], v199 offset:55808
	v_fmamk_f32 v119, v188, 0x41100000, v186
	v_fmamk_f32 v103, v188, 0x42240000, v186
	v_cvt_pk_bf16_f32 v175, v68, v69
	v_add_f32_e32 v187, v187, v69
	v_exp_f32_e32 v72, v72
	s_waitcnt lgkmcnt(2)
	v_mfma_f32_32x32x16_bf16 v[18:33], v[154:157], v[200:203], v[18:33]
	ds_read_b64_tr_b16 v[178:179], v199 offset:56320
	ds_read_b64_tr_b16 v[180:181], v199 offset:56832
	v_fmamk_f32 v120, v188, 0x41200000, v186
	v_fmamk_f32 v104, v188, 0x42280000, v186
	v_exp_f32_e32 v73, v73
	v_add_f32_e32 v187, v187, v70
	v_cvt_pk_bf16_f32 v176, v70, v71
	s_waitcnt lgkmcnt(2)
	v_mfma_f32_32x32x16_bf16 v[18:33], v[150:153], v[182:185], v[18:33]
	ds_read_b64_tr_b16 v[200:201], v199 offset:57344
	ds_read_b64_tr_b16 v[202:203], v199 offset:57856
	v_fmamk_f32 v121, v188, 0x41300000, v186
	v_fmamk_f32 v105, v188, 0x422c0000, v186
	v_add_f32_e32 v182, v187, v71
	v_exp_f32_e32 v74, v74
	v_exp_f32_e32 v75, v75
	s_waitcnt lgkmcnt(2)
	v_mfma_f32_32x32x16_bf16 v[18:33], v[146:149], v[178:181], v[18:33]
	ds_read_b64_tr_b16 v[204:205], v199 offset:58368
	ds_read_b64_tr_b16 v[206:207], v199 offset:58880
	v_add_f32_e32 v178, v182, v72
	v_fmamk_f32 v106, v188, 0x42400000, v186
	v_fma_f32 v122, v188, s48, v186
	v_fma_f32 v123, v188, s49, v186
	v_cvt_pk_bf16_f32 v177, v72, v73
	v_add_f32_e32 v187, v73, v178
	s_waitcnt lgkmcnt(2)
	v_mfma_f32_32x32x16_bf16 v[34:49], v[158:161], v[200:203], v[34:49]
	ds_read_b64_tr_b16 v[182:183], v199 offset:59392
	ds_read_b64_tr_b16 v[184:185], v199 offset:59904
	v_fmamk_f32 v107, v188, 0x42440000, v186
	v_fmamk_f32 v124, v188, 0x41900000, v186
	v_exp_f32_e32 v76, v76
	v_exp_f32_e32 v77, v77
	s_waitcnt lgkmcnt(2)
	v_mfma_f32_32x32x16_bf16 v[34:49], v[154:157], v[204:207], v[34:49]
	ds_read_b64_tr_b16 v[178:179], v199 offset:60416
	ds_read_b64_tr_b16 v[180:181], v199 offset:60928
	v_add_f32_e32 v187, v187, v74
	v_fmamk_f32 v108, v188, 0x42480000, v186
	v_fmamk_f32 v125, v188, 0x41980000, v186
	v_cvt_pk_bf16_f32 v170, v74, v75
	v_add_f32_e32 v200, v75, v187
	v_exp_f32_e32 v78, v78
	s_add_u32 s6, s76, s62
	s_addc_u32 s7, s77, s63
	s_add_u32 s26, s6, 0x30000
	s_addc_u32 s27, s7, 0
	s_add_u32 s6, s78, s62
	s_addc_u32 s7, s79, s63
	s_add_u32 s70, s6, 0x30000
	s_addc_u32 s71, s7, 0
	s_add_i32 s6, 0x8000, s59
	s_add_i32 s7, s81, s90
	s_add_u32 s84, s26, 0x8000
	s_addc_u32 s85, s27, 0
	s_add_i32 s15, s6, 0x2000
	s_mov_b32 m0, s6
	s_nop 0
	global_load_lds_dwordx4 v191, s[26:27]
	s_mov_b32 m0, s15
	s_nop 0
	global_load_lds_dwordx4 v191, s[84:85]
	s_mov_b32 m0, s21
	s_add_u32 s26, s70, 0x80
	s_addc_u32 s27, s71, 0
	s_add_i32 s6, s7, 0x2000
	s_mov_b32 m0, s7
	s_nop 0
	global_load_lds_dwordx4 v192, s[70:71]
	s_mov_b32 m0, s6
	s_nop 0
	global_load_lds_dwordx4 v192, s[26:27]
	s_mov_b32 m0, s15
	s_waitcnt lgkmcnt(2)
	v_mfma_f32_32x32x16_bf16 v[34:49], v[150:153], v[182:185], v[34:49]
	ds_read_b64_tr_b16 v[202:203], v199 offset:61440
	ds_read_b64_tr_b16 v[204:205], v199 offset:61952
	v_mov_b32_e32 v189, v188
	v_mov_b32_e32 v187, v186
	v_fma_f32 v182, v188, s56, v186
	v_fma_f32 v183, v189, s57, v187
	v_fmamk_f32 v126, v188, 0x41c00000, v186
	v_exp_f32_e32 v79, v79
	v_add_f32_e32 v187, v200, v76
	v_mov_b32_e32 v109, v182
	v_mov_b32_e32 v110, v183
	s_waitcnt lgkmcnt(2)
	v_mfma_f32_32x32x16_bf16 v[34:49], v[146:149], v[178:181], v[34:49]
	ds_read_b64_tr_b16 v[182:183], v199 offset:62464
	ds_read_b64_tr_b16 v[184:185], v199 offset:62976
	v_fmamk_f32 v127, v188, 0x41c80000, v186
	v_fmamk_f32 v111, v188, 0x42640000, v186
	v_cvt_pk_bf16_f32 v171, v76, v77
	v_add_f32_e32 v187, v187, v77
	v_exp_f32_e32 v80, v80
	s_waitcnt lgkmcnt(2)
	v_mfma_f32_32x32x16_bf16 v[50:65], v[158:161], v[202:205], v[50:65]
	ds_read_b64_tr_b16 v[178:179], v199 offset:63488
	ds_read_b64_tr_b16 v[180:181], v199 offset:64000
	v_fmamk_f32 v128, v188, 0x41d00000, v186
	v_fmamk_f32 v112, v188, 0x42680000, v186
	v_exp_f32_e32 v81, v81
	v_add_f32_e32 v187, v187, v78
	v_cvt_pk_bf16_f32 v172, v78, v79
	s_waitcnt lgkmcnt(2)
	v_mfma_f32_32x32x16_bf16 v[50:65], v[154:157], v[182:185], v[50:65]
	ds_read_b64_tr_b16 v[200:201], v199 offset:64512
	ds_read_b64_tr_b16 v[202:203], v199 offset:65024
	v_fmamk_f32 v129, v188, 0x41d80000, v186
	v_fmac_f32_e32 v186, 0x426c0000, v188
	v_exp_f32_e32 v82, v82
	v_exp_f32_e32 v83, v83
	v_mov_b32_e32 v113, v186
	v_add_f32_e32 v186, v187, v79
	s_waitcnt lgkmcnt(2)
	v_mfma_f32_32x32x16_bf16 v[50:65], v[150:153], v[178:181], v[50:65]
	ds_read_b128 v[182:185], v190
	v_add_f32_e32 v178, v186, v80
	v_cvt_pk_bf16_f32 v173, v80, v81
	v_add_f32_e32 v186, v81, v178
	v_exp_f32_e32 v84, v84
	v_exp_f32_e32 v85, v85
	s_waitcnt lgkmcnt(1)
	v_mfma_f32_32x32x16_bf16 v[50:65], v[146:149], v[200:203], v[50:65]
	ds_read_b128 v[178:181], v190 offset:8192
	v_add_f32_e32 v186, v186, v82
	v_cvt_pk_bf16_f32 v166, v82, v83
	v_add_f32_e32 v199, v83, v186
	v_exp_f32_e32 v86, v86
	v_exp_f32_e32 v87, v87
	s_waitcnt lgkmcnt(1)
	v_mfma_f32_32x32x16_bf16 v[114:129], v[182:185], v[130:133], v[114:129]
	ds_read_b128 v[186:189], v194
	v_add_f32_e32 v182, v199, v84
	v_cvt_pk_bf16_f32 v167, v84, v85
	v_add_f32_e32 v199, v85, v182
	v_exp_f32_e32 v88, v88
	v_exp_f32_e32 v89, v89
	s_waitcnt lgkmcnt(1)
	v_mfma_f32_32x32x16_bf16 v[98:113], v[178:181], v[130:133], v[98:113]
	ds_read_b128 v[182:185], v194 offset:8192
	v_add_f32_e32 v178, v199, v86
	v_cvt_pk_bf16_f32 v168, v86, v87
	v_add_f32_e32 v199, v87, v178
	v_exp_f32_e32 v90, v90
	v_exp_f32_e32 v91, v91
	s_waitcnt lgkmcnt(1)
	v_mfma_f32_32x32x16_bf16 v[114:129], v[186:189], v[134:137], v[114:129]
	ds_read_b128 v[178:181], v195
	v_add_f32_e32 v186, v199, v88
	v_cvt_pk_bf16_f32 v169, v88, v89
	v_add_f32_e32 v199, v89, v186
	v_exp_f32_e32 v92, v92
	v_exp_f32_e32 v93, v93
	s_waitcnt lgkmcnt(1)
	v_mfma_f32_32x32x16_bf16 v[98:113], v[182:185], v[134:137], v[98:113]
	ds_read_b128 v[186:189], v195 offset:8192
	v_add_f32_e32 v182, v199, v90
	v_cvt_pk_bf16_f32 v162, v90, v91
	v_add_f32_e32 v182, v91, v182
	v_exp_f32_e32 v94, v94
	v_exp_f32_e32 v95, v95
	s_waitcnt lgkmcnt(1)
	v_mfma_f32_32x32x16_bf16 v[114:129], v[178:181], v[138:141], v[114:129]
	ds_read_b128 v[200:203], v196
	v_add_f32_e32 v178, v182, v92
	v_cvt_pk_bf16_f32 v163, v92, v93
	v_add_f32_e32 v178, v93, v178
	v_exp_f32_e32 v96, v96
	v_exp_f32_e32 v97, v97
	s_waitcnt lgkmcnt(1)
	v_mfma_f32_32x32x16_bf16 v[98:113], v[186:189], v[138:141], v[98:113]
	ds_read_b128 v[204:207], v196 offset:8192
	v_add_f32_e32 v165, v178, v94
	v_add_f32_e32 v165, v95, v165
	v_add_f32_e32 v178, v96, v165
	v_cvt_pk_bf16_f32 v164, v94, v95
	v_cvt_pk_bf16_f32 v165, v96, v97
	v_add_f32_e32 v187, v97, v178
	s_waitcnt lgkmcnt(1)
	v_mfma_f32_32x32x16_bf16 v[114:129], v[200:203], v[142:145], v[114:129]
	v_add_u32_e32 v199, s80, v240
	ds_read_b64_tr_b16 v[182:183], v199 offset:49152
	ds_read_b64_tr_b16 v[184:185], v199 offset:49664
	s_waitcnt lgkmcnt(2)
	v_mfma_f32_32x32x16_bf16 v[98:113], v[204:207], v[142:145], v[98:113]
	ds_read_b64_tr_b16 v[178:179], v199 offset:50176
	ds_read_b64_tr_b16 v[180:181], v199 offset:50688
	s_waitcnt vmcnt(4) lgkmcnt(0)
	s_barrier
	s_add_i32 s6, s81, 0x4000
	s_cmp_lg_u32 s81, 0x10000
	s_cselect_b32 s21, s6, 0
	s_add_i32 s20, s20, 1
	s_cmp_lt_i32 s20, s89
	s_waitcnt lgkmcnt(2)
	v_mfma_f32_32x32x16_bf16 v[2:17], v[174:177], v[182:185], v[2:17]
	s_cselect_b64 s[6:7], -1, 0
	v_cvt_f32_i32_e32 v66, v197
	v_cndmask_b32_e64 v188, -v193, v193, s[6:7]
	ds_read_b64_tr_b16 v[200:201], v199 offset:51200
	ds_read_b64_tr_b16 v[202:203], v199 offset:51712
	v_fma_f32 v186, v188, v66, -v233
	v_exp_f32_e32 v114, v114
	v_exp_f32_e32 v115, v115
	v_fma_f32 v66, 0, v188, v186
	v_fmamk_f32 v82, v188, 0x42000000, v186
	v_add_f32_e32 v67, v188, v186
	s_waitcnt lgkmcnt(2)
	v_mfma_f32_32x32x16_bf16 v[2:17], v[170:173], v[178:181], v[2:17]
	ds_read_b64_tr_b16 v[182:183], v199 offset:52224
	ds_read_b64_tr_b16 v[184:185], v199 offset:52736
	v_fmamk_f32 v83, v188, 0x42040000, v186
	v_fma_f32 v68, 2.0, v188, v186
	v_exp_f32_e32 v116, v116
	v_exp_f32_e32 v117, v117
	s_waitcnt lgkmcnt(2)
	v_mfma_f32_32x32x16_bf16 v[2:17], v[166:169], v[200:203], v[2:17]
	ds_read_b64_tr_b16 v[178:179], v199 offset:53248
	ds_read_b64_tr_b16 v[180:181], v199 offset:53760
	v_add_f32_e32 v187, v187, v114
	v_fmamk_f32 v84, v188, 0x42080000, v186
	v_fmamk_f32 v69, v188, 0x40400000, v186
	v_cvt_pk_bf16_f32 v158, v114, v115
	v_add_f32_e32 v187, v115, v187
	v_exp_f32_e32 v118, v118
	s_waitcnt lgkmcnt(2)
	v_mfma_f32_32x32x16_bf16 v[2:17], v[162:165], v[182:185], v[2:17]
	ds_read_b64_tr_b16 v[200:201], v199 offset:54272
	ds_read_b64_tr_b16 v[202:203], v199 offset:54784
	v_fma_f32 v182, v188, s16, v186
	v_fma_f32 v183, v188, s17, v186
	v_fmamk_f32 v70, v188, 0x41000000, v186
	v_exp_f32_e32 v119, v119
	v_add_f32_e32 v187, v187, v116
	v_mov_b32_e32 v85, v182
	v_mov_b32_e32 v86, v183
	s_waitcnt lgkmcnt(2)
	v_mfma_f32_32x32x16_bf16 v[18:33], v[174:177], v[178:181], v[18:33]
	ds_read_b64_tr_b16 v[182:183], v199 offset:55296
	ds_read_b64_tr_b16 v[184:185], v199 offset:55808
	v_fmamk_f32 v71, v188, 0x41100000, v186
	v_fmamk_f32 v87, v188, 0x42240000, v186
	v_cvt_pk_bf16_f32 v159, v116, v117
	v_add_f32_e32 v187, v187, v117
	v_exp_f32_e32 v120, v120
	s_waitcnt lgkmcnt(2)
	v_mfma_f32_32x32x16_bf16 v[18:33], v[170:173], v[200:203], v[18:33]
	ds_read_b64_tr_b16 v[178:179], v199 offset:56320
	ds_read_b64_tr_b16 v[180:181], v199 offset:56832
	v_fmamk_f32 v72, v188, 0x41200000, v186
	v_fmamk_f32 v88, v188, 0x42280000, v186
	v_exp_f32_e32 v121, v121
	v_add_f32_e32 v187, v187, v118
	v_cvt_pk_bf16_f32 v160, v118, v119
	s_waitcnt lgkmcnt(2)
	v_mfma_f32_32x32x16_bf16 v[18:33], v[166:169], v[182:185], v[18:33]
	ds_read_b64_tr_b16 v[200:201], v199 offset:57344
	ds_read_b64_tr_b16 v[202:203], v199 offset:57856
	v_fmamk_f32 v73, v188, 0x41300000, v186
	v_fmamk_f32 v89, v188, 0x422c0000, v186
	v_add_f32_e32 v182, v187, v119
	v_exp_f32_e32 v122, v122
	v_exp_f32_e32 v123, v123
	s_waitcnt lgkmcnt(2)
	v_mfma_f32_32x32x16_bf16 v[18:33], v[162:165], v[178:181], v[18:33]
	ds_read_b64_tr_b16 v[204:205], v199 offset:58368
	ds_read_b64_tr_b16 v[206:207], v199 offset:58880
	v_add_f32_e32 v178, v182, v120
	v_fmamk_f32 v90, v188, 0x42400000, v186
	v_fma_f32 v74, v188, s48, v186
	v_fma_f32 v75, v188, s49, v186
	v_cvt_pk_bf16_f32 v161, v120, v121
	v_add_f32_e32 v187, v121, v178
	s_waitcnt lgkmcnt(2)
	v_mfma_f32_32x32x16_bf16 v[34:49], v[174:177], v[200:203], v[34:49]
	ds_read_b64_tr_b16 v[182:183], v199 offset:59392
	ds_read_b64_tr_b16 v[184:185], v199 offset:59904
	v_fmamk_f32 v91, v188, 0x42440000, v186
	v_fmamk_f32 v76, v188, 0x41900000, v186
	v_exp_f32_e32 v124, v124
	v_exp_f32_e32 v125, v125
	s_waitcnt lgkmcnt(2)
	v_mfma_f32_32x32x16_bf16 v[34:49], v[170:173], v[204:207], v[34:49]
	ds_read_b64_tr_b16 v[178:179], v199 offset:60416
	ds_read_b64_tr_b16 v[180:181], v199 offset:60928
	v_add_f32_e32 v187, v187, v122
	v_fmamk_f32 v92, v188, 0x42480000, v186
	v_fmamk_f32 v77, v188, 0x41980000, v186
	v_cvt_pk_bf16_f32 v154, v122, v123
	v_add_f32_e32 v198, v123, v187
	v_exp_f32_e32 v126, v126
	s_add_u32 s6, s76, s62
	s_addc_u32 s7, s77, s63
	s_add_u32 s6, s6, 0x40000
	s_addc_u32 s7, s7, 0
	s_add_u32 s15, s78, s62
	s_addc_u32 s20, s79, s63
	s_add_u32 s24, s15, 0x40000
	s_addc_u32 s25, s20, 0
	s_add_i32 s15, 0, s59
	s_add_i32 s20, s21, s90
	s_add_u32 s26, s6, 0x8000
	s_addc_u32 s27, s7, 0
	s_add_i32 s68, s15, 0x2000
	s_mov_b32 m0, s15
	s_nop 0
	global_load_lds_dwordx4 v191, s[6:7]
	s_mov_b32 m0, s68
	s_nop 0
	global_load_lds_dwordx4 v191, s[26:27]
	s_mov_b32 m0, s69
	s_add_u32 s6, s24, 0x80
	s_addc_u32 s7, s25, 0
	s_add_i32 s15, s20, 0x2000
	s_mov_b32 m0, s20
	s_nop 0
	global_load_lds_dwordx4 v192, s[24:25]
	s_mov_b32 m0, s15
	s_nop 0
	global_load_lds_dwordx4 v192, s[6:7]
	s_mov_b32 m0, s26
	s_waitcnt lgkmcnt(2)
	v_mfma_f32_32x32x16_bf16 v[34:49], v[166:169], v[182:185], v[34:49]
	ds_read_b64_tr_b16 v[200:201], v199 offset:61440
	ds_read_b64_tr_b16 v[202:203], v199 offset:61952
	v_mov_b32_e32 v189, v188
	v_mov_b32_e32 v187, v186
	s_add_i32 s6, s80, 0x4000
	s_cmp_lg_u32 s80, 0x10000
	v_pk_fma_f32 v[182:183], v[188:189], s[56:57], v[186:187]
	s_cselect_b32 s15, s6, 0
	v_fmamk_f32 v78, v188, 0x41c00000, v186
	v_exp_f32_e32 v127, v127
	v_add_f32_e32 v187, v198, v124
	v_mov_b32_e32 v93, v182
	v_mov_b32_e32 v94, v183
	s_waitcnt lgkmcnt(2)
	v_mfma_f32_32x32x16_bf16 v[34:49], v[162:165], v[178:181], v[34:49]
	ds_read_b64_tr_b16 v[182:183], v199 offset:62464
	ds_read_b64_tr_b16 v[184:185], v199 offset:62976
	v_fmamk_f32 v79, v188, 0x41c80000, v186
	v_fmamk_f32 v95, v188, 0x42640000, v186
	v_cvt_pk_bf16_f32 v155, v124, v125
	v_add_f32_e32 v187, v187, v125
	v_exp_f32_e32 v128, v128
	s_waitcnt lgkmcnt(2)
	v_mfma_f32_32x32x16_bf16 v[50:65], v[174:177], v[200:203], v[50:65]
	ds_read_b64_tr_b16 v[178:179], v199 offset:63488
	ds_read_b64_tr_b16 v[180:181], v199 offset:64000
	v_fmamk_f32 v80, v188, 0x41d00000, v186
	v_fmamk_f32 v96, v188, 0x42680000, v186
	v_exp_f32_e32 v129, v129
	v_add_f32_e32 v187, v187, v126
	v_cvt_pk_bf16_f32 v156, v126, v127
	s_waitcnt lgkmcnt(2)
	v_mfma_f32_32x32x16_bf16 v[50:65], v[170:173], v[182:185], v[50:65]
	ds_read_b64_tr_b16 v[200:201], v199 offset:64512
	ds_read_b64_tr_b16 v[202:203], v199 offset:65024
	v_fmamk_f32 v81, v188, 0x41d80000, v186
	v_fmac_f32_e32 v186, 0x426c0000, v188
	v_exp_f32_e32 v98, v98
	v_exp_f32_e32 v99, v99
	v_mov_b32_e32 v97, v186
	v_add_f32_e32 v186, v187, v127
	s_waitcnt lgkmcnt(2)
	v_mfma_f32_32x32x16_bf16 v[50:65], v[166:169], v[178:181], v[50:65]
	ds_read_b128 v[182:185], v190 offset:16384
	v_add_f32_e32 v178, v186, v128
	v_cvt_pk_bf16_f32 v157, v128, v129
	v_add_f32_e32 v186, v129, v178
	v_exp_f32_e32 v100, v100
	v_exp_f32_e32 v101, v101
	s_waitcnt lgkmcnt(1)
	v_mfma_f32_32x32x16_bf16 v[50:65], v[162:165], v[200:203], v[50:65]
	ds_read_b128 v[178:181], v190 offset:24576
	v_add_f32_e32 v186, v186, v98
	v_cvt_pk_bf16_f32 v150, v98, v99
	v_add_f32_e32 v198, v99, v186
	v_exp_f32_e32 v102, v102
	v_exp_f32_e32 v103, v103
	s_waitcnt lgkmcnt(1)
	v_mfma_f32_32x32x16_bf16 v[66:81], v[182:185], v[130:133], v[66:81]
	ds_read_b128 v[186:189], v194 offset:16384
	v_add_f32_e32 v182, v198, v100
	v_cvt_pk_bf16_f32 v151, v100, v101
	v_add_f32_e32 v198, v101, v182
	v_exp_f32_e32 v104, v104
	v_exp_f32_e32 v105, v105
	s_waitcnt lgkmcnt(1)
	v_mfma_f32_32x32x16_bf16 v[82:97], v[178:181], v[130:133], v[82:97]
	ds_read_b128 v[182:185], v194 offset:24576
	v_add_f32_e32 v178, v198, v102
	v_cvt_pk_bf16_f32 v152, v102, v103
	v_add_f32_e32 v198, v103, v178
	v_exp_f32_e32 v106, v106
	v_exp_f32_e32 v107, v107
	s_waitcnt lgkmcnt(1)
	v_mfma_f32_32x32x16_bf16 v[66:81], v[186:189], v[134:137], v[66:81]
	ds_read_b128 v[178:181], v195 offset:16384
	v_add_f32_e32 v186, v198, v104
	v_cvt_pk_bf16_f32 v153, v104, v105
	v_add_f32_e32 v198, v105, v186
	v_exp_f32_e32 v108, v108
	v_exp_f32_e32 v109, v109
	s_waitcnt lgkmcnt(1)
	v_mfma_f32_32x32x16_bf16 v[82:97], v[182:185], v[134:137], v[82:97]
	ds_read_b128 v[186:189], v195 offset:24576
	v_add_f32_e32 v182, v198, v106
	v_cvt_pk_bf16_f32 v146, v106, v107
	v_add_f32_e32 v182, v107, v182
	v_exp_f32_e32 v110, v110
	v_exp_f32_e32 v111, v111
	s_waitcnt lgkmcnt(1)
	v_mfma_f32_32x32x16_bf16 v[66:81], v[178:181], v[138:141], v[66:81]
	ds_read_b128 v[198:201], v196 offset:16384
	v_add_f32_e32 v178, v182, v108
	v_cvt_pk_bf16_f32 v147, v108, v109
	v_add_f32_e32 v178, v109, v178
	v_exp_f32_e32 v112, v112
	v_exp_f32_e32 v113, v113
	s_waitcnt lgkmcnt(1)
	v_mfma_f32_32x32x16_bf16 v[82:97], v[186:189], v[138:141], v[82:97]
	ds_read_b128 v[202:205], v196 offset:24576
	v_add_f32_e32 v149, v178, v110
	v_add_f32_e32 v149, v111, v149
	v_add_f32_e32 v178, v112, v149
	v_cvt_pk_bf16_f32 v148, v110, v111
	v_cvt_pk_bf16_f32 v149, v112, v113
	v_add_f32_e32 v187, v113, v178
	s_waitcnt lgkmcnt(1)
	v_mfma_f32_32x32x16_bf16 v[66:81], v[198:201], v[142:145], v[66:81]
	v_add_u32_e32 v180, s15, v240
	ds_read_b64_tr_b16 v[182:183], v180 offset:49152
	ds_read_b64_tr_b16 v[184:185], v180 offset:49664
	s_waitcnt lgkmcnt(2)
	v_mfma_f32_32x32x16_bf16 v[82:97], v[202:205], v[142:145], v[82:97]
	ds_read_b64_tr_b16 v[178:179], v180 offset:50176
	ds_read_b64_tr_b16 v[180:181], v180 offset:50688
	s_add_i32 s6, s15, 0x4000
	s_cmp_lg_u32 s15, 0x10000
	s_cselect_b32 s80, s6, 0
	s_add_i32 s6, s21, 0x4000
	s_cmp_lg_u32 s21, 0x10000
	s_cselect_b32 s81, s6, 0
	s_add_u32 s78, s78, 0x20000
	s_addc_u32 s79, s79, 0
	s_add_u32 s76, s76, 0x20000
	s_addc_u32 s77, s77, 0
	v_add_u32_e32 v197, 0x80, v197
	s_mov_b32 s43, s0
	s_add_i32 s0, s43, 2
	s_waitcnt vmcnt(4) lgkmcnt(0)
	s_barrier
	s_add_i32 s20, s58, s43
	s_cmp_lt_i32 s20, s89
	s_waitcnt lgkmcnt(2)
	v_mfma_f32_32x32x16_bf16 v[2:17], v[158:161], v[182:185], v[2:17]
	v_subrev_u32_e32 v198, 64, v197
	s_cselect_b64 s[26:27], -1, 0
	v_cvt_f32_i32_e32 v98, v198
	v_cndmask_b32_e64 v188, -v193, v193, s[26:27]
	v_add_u32_e32 v199, s15, v240
	ds_read_b64_tr_b16 v[200:201], v199 offset:51200
	ds_read_b64_tr_b16 v[202:203], v199 offset:51712
	v_fma_f32 v186, v188, v98, -v233
	v_exp_f32_e32 v66, v66
	v_exp_f32_e32 v67, v67
	v_fma_f32 v114, 0, v188, v186
	v_fmamk_f32 v98, v188, 0x42000000, v186
	v_add_f32_e32 v115, v188, v186
	s_waitcnt lgkmcnt(2)
	v_mfma_f32_32x32x16_bf16 v[2:17], v[154:157], v[178:181], v[2:17]
	ds_read_b64_tr_b16 v[182:183], v199 offset:52224
	ds_read_b64_tr_b16 v[184:185], v199 offset:52736
	v_fmamk_f32 v99, v188, 0x42040000, v186
	v_fma_f32 v116, 2.0, v188, v186
	v_exp_f32_e32 v68, v68
	v_exp_f32_e32 v69, v69
	s_waitcnt lgkmcnt(2)
	v_mfma_f32_32x32x16_bf16 v[2:17], v[150:153], v[200:203], v[2:17]
	ds_read_b64_tr_b16 v[178:179], v199 offset:53248
	ds_read_b64_tr_b16 v[180:181], v199 offset:53760
	v_add_f32_e32 v187, v187, v66
	v_fmamk_f32 v100, v188, 0x42080000, v186
	v_fmamk_f32 v117, v188, 0x40400000, v186
	v_cvt_pk_bf16_f32 v174, v66, v67
	v_add_f32_e32 v187, v67, v187
	v_exp_f32_e32 v70, v70
	s_waitcnt lgkmcnt(2)
	v_mfma_f32_32x32x16_bf16 v[2:17], v[146:149], v[182:185], v[2:17]
	ds_read_b64_tr_b16 v[200:201], v199 offset:54272
	ds_read_b64_tr_b16 v[202:203], v199 offset:54784
	v_fma_f32 v182, v188, s16, v186
	v_fma_f32 v183, v188, s17, v186
	v_fmamk_f32 v118, v188, 0x41000000, v186
	v_exp_f32_e32 v71, v71
	v_add_f32_e32 v187, v187, v68
	v_mov_b32_e32 v101, v182
	v_mov_b32_e32 v102, v183
	s_waitcnt lgkmcnt(2)
	v_mfma_f32_32x32x16_bf16 v[18:33], v[158:161], v[178:181], v[18:33]
	ds_read_b64_tr_b16 v[182:183], v199 offset:55296
	ds_read_b64_tr_b16 v[184:185], v199 offset:55808
	v_fmamk_f32 v119, v188, 0x41100000, v186
	v_fmamk_f32 v103, v188, 0x42240000, v186
	v_cvt_pk_bf16_f32 v175, v68, v69
	v_add_f32_e32 v187, v187, v69
	v_exp_f32_e32 v72, v72
	s_waitcnt lgkmcnt(2)
	v_mfma_f32_32x32x16_bf16 v[18:33], v[154:157], v[200:203], v[18:33]
	ds_read_b64_tr_b16 v[178:179], v199 offset:56320
	ds_read_b64_tr_b16 v[180:181], v199 offset:56832
	v_fmamk_f32 v120, v188, 0x41200000, v186
	v_fmamk_f32 v104, v188, 0x42280000, v186
	v_exp_f32_e32 v73, v73
	v_add_f32_e32 v187, v187, v70
	v_cvt_pk_bf16_f32 v176, v70, v71
	s_waitcnt lgkmcnt(2)
	v_mfma_f32_32x32x16_bf16 v[18:33], v[150:153], v[182:185], v[18:33]
	ds_read_b64_tr_b16 v[200:201], v199 offset:57344
	ds_read_b64_tr_b16 v[202:203], v199 offset:57856
	v_fmamk_f32 v121, v188, 0x41300000, v186
	v_fmamk_f32 v105, v188, 0x422c0000, v186
	v_add_f32_e32 v182, v187, v71
	v_exp_f32_e32 v74, v74
	v_exp_f32_e32 v75, v75
	s_waitcnt lgkmcnt(2)
	v_mfma_f32_32x32x16_bf16 v[18:33], v[146:149], v[178:181], v[18:33]
	ds_read_b64_tr_b16 v[204:205], v199 offset:58368
	ds_read_b64_tr_b16 v[206:207], v199 offset:58880
	v_add_f32_e32 v178, v182, v72
	v_fmamk_f32 v106, v188, 0x42400000, v186
	v_fma_f32 v122, v188, s48, v186
	v_fma_f32 v123, v188, s49, v186
	v_cvt_pk_bf16_f32 v177, v72, v73
	v_add_f32_e32 v187, v73, v178
	s_waitcnt lgkmcnt(2)
	v_mfma_f32_32x32x16_bf16 v[34:49], v[158:161], v[200:203], v[34:49]
	ds_read_b64_tr_b16 v[182:183], v199 offset:59392
	ds_read_b64_tr_b16 v[184:185], v199 offset:59904
	v_fmamk_f32 v107, v188, 0x42440000, v186
	v_fmamk_f32 v124, v188, 0x41900000, v186
	v_exp_f32_e32 v76, v76
	v_exp_f32_e32 v77, v77
	s_waitcnt lgkmcnt(2)
	v_mfma_f32_32x32x16_bf16 v[34:49], v[154:157], v[204:207], v[34:49]
	ds_read_b64_tr_b16 v[178:179], v199 offset:60416
	ds_read_b64_tr_b16 v[180:181], v199 offset:60928
	v_add_f32_e32 v187, v187, v74
	v_fmamk_f32 v108, v188, 0x42480000, v186
	v_fmamk_f32 v125, v188, 0x41980000, v186
	v_cvt_pk_bf16_f32 v170, v74, v75
	v_add_f32_e32 v200, v75, v187
	v_exp_f32_e32 v78, v78
	s_add_u32 s6, s76, s62
	s_addc_u32 s7, s77, s63
	s_add_u32 s26, s6, 0x30000
	s_addc_u32 s27, s7, 0
	s_add_u32 s6, s78, s62
	s_addc_u32 s7, s79, s63
	s_add_u32 s70, s6, 0x30000
	s_addc_u32 s71, s7, 0
	s_add_i32 s6, 0x4000, s59
	s_add_i32 s7, s81, s90
	s_add_u32 s84, s26, 0x8000
	s_addc_u32 s85, s27, 0
	s_add_i32 s15, s6, 0x2000
	s_mov_b32 m0, s6
	s_nop 0
	global_load_lds_dwordx4 v191, s[26:27]
	s_mov_b32 m0, s15
	s_nop 0
	global_load_lds_dwordx4 v191, s[84:85]
	s_mov_b32 m0, s21
	s_add_u32 s26, s70, 0x80
	s_addc_u32 s27, s71, 0
	s_add_i32 s6, s7, 0x2000
	s_mov_b32 m0, s7
	s_nop 0
	global_load_lds_dwordx4 v192, s[70:71]
	s_mov_b32 m0, s6
	s_nop 0
	global_load_lds_dwordx4 v192, s[26:27]
	s_mov_b32 m0, s15
	s_waitcnt lgkmcnt(2)
	v_mfma_f32_32x32x16_bf16 v[34:49], v[150:153], v[182:185], v[34:49]
	ds_read_b64_tr_b16 v[202:203], v199 offset:61440
	ds_read_b64_tr_b16 v[204:205], v199 offset:61952
	v_mov_b32_e32 v189, v188
	v_mov_b32_e32 v187, v186
	v_fma_f32 v182, v188, s56, v186
	v_fma_f32 v183, v189, s57, v187
	v_fmamk_f32 v126, v188, 0x41c00000, v186
	v_exp_f32_e32 v79, v79
	v_add_f32_e32 v187, v200, v76
	v_mov_b32_e32 v109, v182
	v_mov_b32_e32 v110, v183
	s_waitcnt lgkmcnt(2)
	v_mfma_f32_32x32x16_bf16 v[34:49], v[146:149], v[178:181], v[34:49]
	ds_read_b64_tr_b16 v[182:183], v199 offset:62464
	ds_read_b64_tr_b16 v[184:185], v199 offset:62976
	v_fmamk_f32 v127, v188, 0x41c80000, v186
	v_fmamk_f32 v111, v188, 0x42640000, v186
	v_cvt_pk_bf16_f32 v171, v76, v77
	v_add_f32_e32 v187, v187, v77
	v_exp_f32_e32 v80, v80
	s_waitcnt lgkmcnt(2)
	v_mfma_f32_32x32x16_bf16 v[50:65], v[158:161], v[202:205], v[50:65]
	ds_read_b64_tr_b16 v[178:179], v199 offset:63488
	ds_read_b64_tr_b16 v[180:181], v199 offset:64000
	v_fmamk_f32 v128, v188, 0x41d00000, v186
	v_fmamk_f32 v112, v188, 0x42680000, v186
	v_exp_f32_e32 v81, v81
	v_add_f32_e32 v187, v187, v78
	v_cvt_pk_bf16_f32 v172, v78, v79
	s_waitcnt lgkmcnt(2)
	v_mfma_f32_32x32x16_bf16 v[50:65], v[154:157], v[182:185], v[50:65]
	ds_read_b64_tr_b16 v[200:201], v199 offset:64512
	ds_read_b64_tr_b16 v[202:203], v199 offset:65024
	v_fmamk_f32 v129, v188, 0x41d80000, v186
	v_fmac_f32_e32 v186, 0x426c0000, v188
	v_exp_f32_e32 v82, v82
	v_exp_f32_e32 v83, v83
	v_mov_b32_e32 v113, v186
	v_add_f32_e32 v186, v187, v79
	s_waitcnt lgkmcnt(2)
	v_mfma_f32_32x32x16_bf16 v[50:65], v[150:153], v[178:181], v[50:65]
	ds_read_b128 v[182:185], v190 offset:32768
	v_add_f32_e32 v178, v186, v80
	v_cvt_pk_bf16_f32 v173, v80, v81
	v_add_f32_e32 v186, v81, v178
	v_exp_f32_e32 v84, v84
	v_exp_f32_e32 v85, v85
	s_waitcnt lgkmcnt(1)
	v_mfma_f32_32x32x16_bf16 v[50:65], v[146:149], v[200:203], v[50:65]
	ds_read_b128 v[178:181], v190 offset:40960
	v_add_f32_e32 v186, v186, v82
	v_cvt_pk_bf16_f32 v166, v82, v83
	v_add_f32_e32 v199, v83, v186
	v_exp_f32_e32 v86, v86
	v_exp_f32_e32 v87, v87
	s_waitcnt lgkmcnt(1)
	v_mfma_f32_32x32x16_bf16 v[114:129], v[182:185], v[130:133], v[114:129]
	ds_read_b128 v[186:189], v194 offset:32768
	v_add_f32_e32 v182, v199, v84
	v_cvt_pk_bf16_f32 v167, v84, v85
	v_add_f32_e32 v199, v85, v182
	v_exp_f32_e32 v88, v88
	v_exp_f32_e32 v89, v89
	s_waitcnt lgkmcnt(1)
	v_mfma_f32_32x32x16_bf16 v[98:113], v[178:181], v[130:133], v[98:113]
	ds_read_b128 v[182:185], v194 offset:40960
	v_add_f32_e32 v178, v199, v86
	v_cvt_pk_bf16_f32 v168, v86, v87
	v_add_f32_e32 v199, v87, v178
	v_exp_f32_e32 v90, v90
	v_exp_f32_e32 v91, v91
	s_waitcnt lgkmcnt(1)
	v_mfma_f32_32x32x16_bf16 v[114:129], v[186:189], v[134:137], v[114:129]
	ds_read_b128 v[178:181], v195 offset:32768
	v_add_f32_e32 v186, v199, v88
	v_cvt_pk_bf16_f32 v169, v88, v89
	v_add_f32_e32 v199, v89, v186
	v_exp_f32_e32 v92, v92
	v_exp_f32_e32 v93, v93
	s_waitcnt lgkmcnt(1)
	v_mfma_f32_32x32x16_bf16 v[98:113], v[182:185], v[134:137], v[98:113]
	ds_read_b128 v[186:189], v195 offset:40960
	v_add_f32_e32 v182, v199, v90
	v_cvt_pk_bf16_f32 v162, v90, v91
	v_add_f32_e32 v182, v91, v182
	v_exp_f32_e32 v94, v94
	v_exp_f32_e32 v95, v95
	s_waitcnt lgkmcnt(1)
	v_mfma_f32_32x32x16_bf16 v[114:129], v[178:181], v[138:141], v[114:129]
	ds_read_b128 v[200:203], v196 offset:32768
	v_add_f32_e32 v178, v182, v92
	v_cvt_pk_bf16_f32 v163, v92, v93
	v_add_f32_e32 v178, v93, v178
	v_exp_f32_e32 v96, v96
	v_exp_f32_e32 v97, v97
	s_waitcnt lgkmcnt(1)
	v_mfma_f32_32x32x16_bf16 v[98:113], v[186:189], v[138:141], v[98:113]
	ds_read_b128 v[204:207], v196 offset:40960
	v_add_f32_e32 v165, v178, v94
	v_add_f32_e32 v165, v95, v165
	v_add_f32_e32 v178, v96, v165
	v_cvt_pk_bf16_f32 v164, v94, v95
	v_cvt_pk_bf16_f32 v165, v96, v97
	v_add_f32_e32 v187, v97, v178
	s_waitcnt lgkmcnt(1)
	v_mfma_f32_32x32x16_bf16 v[114:129], v[200:203], v[142:145], v[114:129]
	v_add_u32_e32 v199, s80, v240
	ds_read_b64_tr_b16 v[182:183], v199 offset:49152
	ds_read_b64_tr_b16 v[184:185], v199 offset:49664
	s_waitcnt lgkmcnt(2)
	v_mfma_f32_32x32x16_bf16 v[98:113], v[204:207], v[142:145], v[98:113]
	ds_read_b64_tr_b16 v[178:179], v199 offset:50176
	ds_read_b64_tr_b16 v[180:181], v199 offset:50688
	s_waitcnt vmcnt(4) lgkmcnt(0)
	s_barrier
	s_add_i32 s6, s81, 0x4000
	s_cmp_lg_u32 s81, 0x10000
	s_cselect_b32 s21, s6, 0
	s_add_i32 s20, s20, 1
	s_cmp_lt_i32 s20, s89
	s_waitcnt lgkmcnt(2)
	v_mfma_f32_32x32x16_bf16 v[2:17], v[174:177], v[182:185], v[2:17]
	s_cselect_b64 s[6:7], -1, 0
	v_cvt_f32_i32_e32 v66, v197
	v_cndmask_b32_e64 v188, -v193, v193, s[6:7]
	ds_read_b64_tr_b16 v[200:201], v199 offset:51200
	ds_read_b64_tr_b16 v[202:203], v199 offset:51712
	v_fma_f32 v186, v188, v66, -v233
	v_exp_f32_e32 v114, v114
	v_exp_f32_e32 v115, v115
	v_fma_f32 v66, 0, v188, v186
	v_fmamk_f32 v82, v188, 0x42000000, v186
	v_add_f32_e32 v67, v188, v186
	s_waitcnt lgkmcnt(2)
	v_mfma_f32_32x32x16_bf16 v[2:17], v[170:173], v[178:181], v[2:17]
	ds_read_b64_tr_b16 v[182:183], v199 offset:52224
	ds_read_b64_tr_b16 v[184:185], v199 offset:52736
	v_fmamk_f32 v83, v188, 0x42040000, v186
	v_fma_f32 v68, 2.0, v188, v186
	v_exp_f32_e32 v116, v116
	v_exp_f32_e32 v117, v117
	s_waitcnt lgkmcnt(2)
	v_mfma_f32_32x32x16_bf16 v[2:17], v[166:169], v[200:203], v[2:17]
	ds_read_b64_tr_b16 v[178:179], v199 offset:53248
	ds_read_b64_tr_b16 v[180:181], v199 offset:53760
	v_add_f32_e32 v187, v187, v114
	v_fmamk_f32 v84, v188, 0x42080000, v186
	v_fmamk_f32 v69, v188, 0x40400000, v186
	v_cvt_pk_bf16_f32 v158, v114, v115
	v_add_f32_e32 v187, v115, v187
	v_exp_f32_e32 v118, v118
	s_waitcnt lgkmcnt(2)
	v_mfma_f32_32x32x16_bf16 v[2:17], v[162:165], v[182:185], v[2:17]
	ds_read_b64_tr_b16 v[200:201], v199 offset:54272
	ds_read_b64_tr_b16 v[202:203], v199 offset:54784
	v_fma_f32 v182, v188, s16, v186
	v_fma_f32 v183, v188, s17, v186
	v_fmamk_f32 v70, v188, 0x41000000, v186
	v_exp_f32_e32 v119, v119
	v_add_f32_e32 v187, v187, v116
	v_mov_b32_e32 v85, v182
	v_mov_b32_e32 v86, v183
	s_waitcnt lgkmcnt(2)
	v_mfma_f32_32x32x16_bf16 v[18:33], v[174:177], v[178:181], v[18:33]
	ds_read_b64_tr_b16 v[182:183], v199 offset:55296
	ds_read_b64_tr_b16 v[184:185], v199 offset:55808
	v_fmamk_f32 v71, v188, 0x41100000, v186
	v_fmamk_f32 v87, v188, 0x42240000, v186
	v_cvt_pk_bf16_f32 v159, v116, v117
	v_add_f32_e32 v187, v187, v117
	v_exp_f32_e32 v120, v120
	s_waitcnt lgkmcnt(2)
	v_mfma_f32_32x32x16_bf16 v[18:33], v[170:173], v[200:203], v[18:33]
	ds_read_b64_tr_b16 v[178:179], v199 offset:56320
	ds_read_b64_tr_b16 v[180:181], v199 offset:56832
	v_fmamk_f32 v72, v188, 0x41200000, v186
	v_fmamk_f32 v88, v188, 0x42280000, v186
	v_exp_f32_e32 v121, v121
	v_add_f32_e32 v187, v187, v118
	v_cvt_pk_bf16_f32 v160, v118, v119
	s_waitcnt lgkmcnt(2)
	v_mfma_f32_32x32x16_bf16 v[18:33], v[166:169], v[182:185], v[18:33]
	ds_read_b64_tr_b16 v[200:201], v199 offset:57344
	ds_read_b64_tr_b16 v[202:203], v199 offset:57856
	v_fmamk_f32 v73, v188, 0x41300000, v186
	v_fmamk_f32 v89, v188, 0x422c0000, v186
	v_add_f32_e32 v182, v187, v119
	v_exp_f32_e32 v122, v122
	v_exp_f32_e32 v123, v123
	s_waitcnt lgkmcnt(2)
	v_mfma_f32_32x32x16_bf16 v[18:33], v[162:165], v[178:181], v[18:33]
	ds_read_b64_tr_b16 v[204:205], v199 offset:58368
	ds_read_b64_tr_b16 v[206:207], v199 offset:58880
	v_add_f32_e32 v178, v182, v120
	v_fmamk_f32 v90, v188, 0x42400000, v186
	v_fma_f32 v74, v188, s48, v186
	v_fma_f32 v75, v188, s49, v186
	v_cvt_pk_bf16_f32 v161, v120, v121
	v_add_f32_e32 v187, v121, v178
	s_waitcnt lgkmcnt(2)
	v_mfma_f32_32x32x16_bf16 v[34:49], v[174:177], v[200:203], v[34:49]
	ds_read_b64_tr_b16 v[182:183], v199 offset:59392
	ds_read_b64_tr_b16 v[184:185], v199 offset:59904
	v_fmamk_f32 v91, v188, 0x42440000, v186
	v_fmamk_f32 v76, v188, 0x41900000, v186
	v_exp_f32_e32 v124, v124
	v_exp_f32_e32 v125, v125
	s_waitcnt lgkmcnt(2)
	v_mfma_f32_32x32x16_bf16 v[34:49], v[170:173], v[204:207], v[34:49]
	ds_read_b64_tr_b16 v[178:179], v199 offset:60416
	ds_read_b64_tr_b16 v[180:181], v199 offset:60928
	v_add_f32_e32 v187, v187, v122
	v_fmamk_f32 v92, v188, 0x42480000, v186
	v_fmamk_f32 v77, v188, 0x41980000, v186
	v_cvt_pk_bf16_f32 v154, v122, v123
	v_add_f32_e32 v198, v123, v187
	v_exp_f32_e32 v126, v126
	s_add_u32 s6, s76, s62
	s_addc_u32 s7, s77, s63
	s_add_u32 s6, s6, 0x40000
	s_addc_u32 s7, s7, 0
	s_add_u32 s15, s78, s62
	s_addc_u32 s20, s79, s63
	s_add_u32 s24, s15, 0x40000
	s_addc_u32 s25, s20, 0
	s_add_i32 s15, 0x8000, s59
	s_add_i32 s20, s21, s90
	s_add_u32 s26, s6, 0x8000
	s_addc_u32 s27, s7, 0
	s_add_i32 s68, s15, 0x2000
	s_mov_b32 m0, s15
	s_nop 0
	global_load_lds_dwordx4 v191, s[6:7]
	s_mov_b32 m0, s68
	s_nop 0
	global_load_lds_dwordx4 v191, s[26:27]
	s_mov_b32 m0, s69
	s_add_u32 s6, s24, 0x80
	s_addc_u32 s7, s25, 0
	s_add_i32 s15, s20, 0x2000
	s_mov_b32 m0, s20
	s_nop 0
	global_load_lds_dwordx4 v192, s[24:25]
	s_mov_b32 m0, s15
	s_nop 0
	global_load_lds_dwordx4 v192, s[6:7]
	s_mov_b32 m0, s26
	s_waitcnt lgkmcnt(2)
	v_mfma_f32_32x32x16_bf16 v[34:49], v[166:169], v[182:185], v[34:49]
	ds_read_b64_tr_b16 v[200:201], v199 offset:61440
	ds_read_b64_tr_b16 v[202:203], v199 offset:61952
	v_mov_b32_e32 v189, v188
	v_mov_b32_e32 v187, v186
	s_add_i32 s6, s80, 0x4000
	s_cmp_lg_u32 s80, 0x10000
	v_pk_fma_f32 v[182:183], v[188:189], s[56:57], v[186:187]
	s_cselect_b32 s15, s6, 0
	v_fmamk_f32 v78, v188, 0x41c00000, v186
	v_exp_f32_e32 v127, v127
	v_add_f32_e32 v187, v198, v124
	v_mov_b32_e32 v93, v182
	v_mov_b32_e32 v94, v183
	s_waitcnt lgkmcnt(2)
	v_mfma_f32_32x32x16_bf16 v[34:49], v[162:165], v[178:181], v[34:49]
	ds_read_b64_tr_b16 v[182:183], v199 offset:62464
	ds_read_b64_tr_b16 v[184:185], v199 offset:62976
	v_fmamk_f32 v79, v188, 0x41c80000, v186
	v_fmamk_f32 v95, v188, 0x42640000, v186
	v_cvt_pk_bf16_f32 v155, v124, v125
	v_add_f32_e32 v187, v187, v125
	v_exp_f32_e32 v128, v128
	s_waitcnt lgkmcnt(2)
	v_mfma_f32_32x32x16_bf16 v[50:65], v[174:177], v[200:203], v[50:65]
	ds_read_b64_tr_b16 v[178:179], v199 offset:63488
	ds_read_b64_tr_b16 v[180:181], v199 offset:64000
	v_fmamk_f32 v80, v188, 0x41d00000, v186
	v_fmamk_f32 v96, v188, 0x42680000, v186
	v_exp_f32_e32 v129, v129
	v_add_f32_e32 v187, v187, v126
	v_cvt_pk_bf16_f32 v156, v126, v127
	s_waitcnt lgkmcnt(2)
	v_mfma_f32_32x32x16_bf16 v[50:65], v[170:173], v[182:185], v[50:65]
	ds_read_b64_tr_b16 v[200:201], v199 offset:64512
	ds_read_b64_tr_b16 v[202:203], v199 offset:65024
	v_fmamk_f32 v81, v188, 0x41d80000, v186
	v_fmac_f32_e32 v186, 0x426c0000, v188
	v_exp_f32_e32 v98, v98
	v_exp_f32_e32 v99, v99
	v_mov_b32_e32 v97, v186
	v_add_f32_e32 v186, v187, v127
	s_waitcnt lgkmcnt(2)
	v_mfma_f32_32x32x16_bf16 v[50:65], v[166:169], v[178:181], v[50:65]
	ds_read_b128 v[182:185], v190
	v_add_f32_e32 v178, v186, v128
	v_cvt_pk_bf16_f32 v157, v128, v129
	v_add_f32_e32 v186, v129, v178
	v_exp_f32_e32 v100, v100
	v_exp_f32_e32 v101, v101
	s_waitcnt lgkmcnt(1)
	v_mfma_f32_32x32x16_bf16 v[50:65], v[162:165], v[200:203], v[50:65]
	ds_read_b128 v[178:181], v190 offset:8192
	v_add_f32_e32 v186, v186, v98
	v_cvt_pk_bf16_f32 v150, v98, v99
	v_add_f32_e32 v198, v99, v186
	v_exp_f32_e32 v102, v102
	v_exp_f32_e32 v103, v103
	s_waitcnt lgkmcnt(1)
	v_mfma_f32_32x32x16_bf16 v[66:81], v[182:185], v[130:133], v[66:81]
	ds_read_b128 v[186:189], v194
	v_add_f32_e32 v182, v198, v100
	v_cvt_pk_bf16_f32 v151, v100, v101
	v_add_f32_e32 v198, v101, v182
	v_exp_f32_e32 v104, v104
	v_exp_f32_e32 v105, v105
	s_waitcnt lgkmcnt(1)
	v_mfma_f32_32x32x16_bf16 v[82:97], v[178:181], v[130:133], v[82:97]
	ds_read_b128 v[182:185], v194 offset:8192
	v_add_f32_e32 v178, v198, v102
	v_cvt_pk_bf16_f32 v152, v102, v103
	v_add_f32_e32 v198, v103, v178
	v_exp_f32_e32 v106, v106
	v_exp_f32_e32 v107, v107
	s_waitcnt lgkmcnt(1)
	v_mfma_f32_32x32x16_bf16 v[66:81], v[186:189], v[134:137], v[66:81]
	ds_read_b128 v[178:181], v195
	v_add_f32_e32 v186, v198, v104
	v_cvt_pk_bf16_f32 v153, v104, v105
	v_add_f32_e32 v198, v105, v186
	v_exp_f32_e32 v108, v108
	v_exp_f32_e32 v109, v109
	s_waitcnt lgkmcnt(1)
	v_mfma_f32_32x32x16_bf16 v[82:97], v[182:185], v[134:137], v[82:97]
	ds_read_b128 v[186:189], v195 offset:8192
	v_add_f32_e32 v182, v198, v106
	v_cvt_pk_bf16_f32 v146, v106, v107
	v_add_f32_e32 v182, v107, v182
	v_exp_f32_e32 v110, v110
	v_exp_f32_e32 v111, v111
	s_waitcnt lgkmcnt(1)
	v_mfma_f32_32x32x16_bf16 v[66:81], v[178:181], v[138:141], v[66:81]
	ds_read_b128 v[198:201], v196
	v_add_f32_e32 v178, v182, v108
	v_cvt_pk_bf16_f32 v147, v108, v109
	v_add_f32_e32 v178, v109, v178
	v_exp_f32_e32 v112, v112
	v_exp_f32_e32 v113, v113
	s_waitcnt lgkmcnt(1)
	v_mfma_f32_32x32x16_bf16 v[82:97], v[186:189], v[138:141], v[82:97]
	ds_read_b128 v[202:205], v196 offset:8192
	v_add_f32_e32 v149, v178, v110
	v_add_f32_e32 v149, v111, v149
	v_add_f32_e32 v178, v112, v149
	v_cvt_pk_bf16_f32 v148, v110, v111
	v_cvt_pk_bf16_f32 v149, v112, v113
	v_add_f32_e32 v187, v113, v178
	s_waitcnt lgkmcnt(1)
	v_mfma_f32_32x32x16_bf16 v[66:81], v[198:201], v[142:145], v[66:81]
	v_add_u32_e32 v180, s15, v240
	ds_read_b64_tr_b16 v[182:183], v180 offset:49152
	ds_read_b64_tr_b16 v[184:185], v180 offset:49664
	s_waitcnt lgkmcnt(2)
	v_mfma_f32_32x32x16_bf16 v[82:97], v[202:205], v[142:145], v[82:97]
	ds_read_b64_tr_b16 v[178:179], v180 offset:50176
	ds_read_b64_tr_b16 v[180:181], v180 offset:50688
	s_add_i32 s6, s15, 0x4000
	s_cmp_lg_u32 s15, 0x10000
	s_cselect_b32 s80, s6, 0
	s_add_i32 s6, s21, 0x4000
	s_cmp_lg_u32 s21, 0x10000
	s_cselect_b32 s81, s6, 0
	s_add_u32 s78, s78, 0x20000
	s_addc_u32 s79, s79, 0
	s_add_u32 s76, s76, 0x20000
	s_addc_u32 s77, s77, 0
	v_add_u32_e32 v197, 0x80, v197
	s_mov_b32 s43, s0
	s_branch .LBB0_1377
